# G2 LoRA a/g epilogue: k row, a0/k_a/k_k weights and rinv of all 8 row blocks loaded once up front into dead registers, per-block vmcnt(0) waits dropped; G7 E loads hoisted; on top of hand-written phas
# speedup vs baseline: 1.1245x; 1.0204x over previous
; #define PG8_STAGE(bufoff, gbase, voff) do { _Pragma("unroll") for (int _i = 0; _i < 2; ++_i) \
;         __builtin_amdgcn_global_load_lds((const unsigned*)((const char*)(gbase) + (voff)[_i]), (PG8_LAS unsigned*)(lds + (bufoff) + ldsw + _i * 8192), 16, 0, 0); } while (0)
; #define PG8_LDA(dst, b, h) do { _Pragma("unroll") for (int m = 0; m < 4; ++m) _Pragma("unroll") for (int k = 0; k < 2; ++k) dst[m][k] = *(const PG8_LAS bf16x8*)(lds + PG8_SA(b, h) + aoff + m * 2048 + k * 1024); } while (0)
; #define PG8_LDB(dst, b, h) do { _Pragma("unroll") for (int n = 0; n < 2; ++n) _Pragma("unroll") for (int k = 0; k < 2; ++k) dst[n][k] = *(const PG8_LAS bf16x8*)(lds + PG8_SB(b, h) + boff + n * 2048 + k * 1024); } while (0)
; #define PG8_MMA(ai, bj, At, Bt) do { __builtin_amdgcn_s_setprio(1); _Pragma("unroll") for (int m = 0; m < 4; ++m) _Pragma("unroll") for (int n = 0; n < 2; ++n) _Pragma("unroll") for (int k = 0; k < 2; ++k) \
;         acc[ai][bj][m][n] = __builtin_amdgcn_mfma_f32_16x16x32_bf16(Bt[n][k], At[m][k], acc[ai][bj][m][n], 0, 0, 0); __builtin_amdgcn_s_setprio(0); } while (0)
; #define PG8_WAIT_V(n) asm volatile("s_waitcnt vmcnt(" #n ")" ::: "memory")
; #define PG8_WAIT_L(n) asm volatile("s_waitcnt lgkmcnt(" #n ")" ::: "memory")
; #define PG8_BAR __builtin_amdgcn_s_barrier()
; #define PG8_SCHED __builtin_amdgcn_sched_barrier(0)
; template <class Epi, class Sched>
; __device__ __forceinline__ void gemm_phase(PG8_LAS unsigned char* lds, const Gemm g, const Sched& S, const Epi& E) {
;     ...
;             PG8_LDB(B0, 0, 0); PG8_SCHED; PG8_LDA(At, 0, 0); PG8_STAGE(PG8_SA(1, 1), a1 + hstep, voffA);
;             PG8_WAIT_L(8); PG8_BAR; PG8_WAIT_L(0); PG8_MMA(0, 0, At, B0); PG8_BAR; PG8_SCHED;
;             PG8_LDB(B1, 0, 1); PG8_STAGE(PG8_SB(0, 0), b2, voffB);
;             PG8_BAR; PG8_WAIT_L(0); PG8_MMA(0, 1, At, B1); PG8_BAR;
;             PG8_LDA(At, 0, 1); PG8_STAGE(PG8_SA(0, 0), a2, voffA);
;             PG8_BAR; PG8_WAIT_L(0); PG8_MMA(1, 0, At, B0); PG8_BAR; PG8_SCHED;
;             PG8_STAGE(PG8_SB(0, 1), b2 + hstep, voffB);
;             PG8_WAIT_V(6); PG8_BAR; PG8_MMA(1, 1, At, B1); PG8_BAR;
;             PG8_LDB(B0, 1, 0); PG8_SCHED; PG8_LDA(At, 1, 0); PG8_STAGE(PG8_SA(0, 1), a2 + hstep, voffA);
;             PG8_WAIT_L(8); PG8_BAR; PG8_WAIT_L(0); PG8_MMA(0, 0, At, B0); PG8_BAR; PG8_SCHED;
;             PG8_LDB(B1, 1, 1); PG8_STAGE(PG8_SB(1, 0), b3, voffB);
.LBB0_461:
	ds_read_b128 v[8:11], v106
	ds_read_b128 v[12:15], v106 offset:1024
	ds_read_b128 v[16:19], v106 offset:2048
	ds_read_b128 v[20:23], v106 offset:3072
	s_add_u32 s72, s24, 0x18080
	s_addc_u32 s73, s25, 0
	s_add_i32 s79, s38, 0xc000
	v_lshl_add_u64 v[0:1], s[72:73], 0, v[64:65]
	s_mov_b32 m0, s79
	ds_read_b128 v[4:7], v105
	ds_read_b128 v[24:27], v105 offset:1024
	ds_read_b128 v[28:31], v105 offset:2048
	ds_read_b128 v[32:35], v105 offset:3072
	ds_read_b128 v[36:39], v105 offset:4096
	ds_read_b128 v[40:43], v105 offset:5120
	ds_read_b128 v[44:47], v105 offset:6144
	ds_read_b128 v[48:51], v105 offset:7168
	global_load_lds_dwordx4 v[0:1], off
	v_lshl_add_u64 v[0:1], s[72:73], 0, v[68:69]
	s_add_i32 s72, s38, 0xe000
	s_mov_b32 m0, s72
	s_nop 0
	global_load_lds_dwordx4 v[0:1], off
	s_waitcnt lgkmcnt(8)
	s_barrier
	s_waitcnt lgkmcnt(0)
	v_mfma_f32_16x16x32_bf16 v[0:3], v[8:11], v[4:7], 0
	v_mfma_f32_16x16x32_bf16 v[52:55], v[12:15], v[24:27], v[0:3]
	v_mfma_f32_16x16x32_bf16 v[0:3], v[16:19], v[4:7], 0
	v_mfma_f32_16x16x32_bf16 v[56:59], v[20:23], v[24:27], v[0:3]
	v_mfma_f32_16x16x32_bf16 v[0:3], v[8:11], v[28:31], 0
	v_mfma_f32_16x16x32_bf16 v[60:63], v[12:15], v[32:35], v[0:3]
	v_mfma_f32_16x16x32_bf16 v[0:3], v[16:19], v[28:31], 0
	v_mfma_f32_16x16x32_bf16 v[78:81], v[20:23], v[32:35], v[0:3]
	v_mfma_f32_16x16x32_bf16 v[0:3], v[8:11], v[36:39], 0
	v_mfma_f32_16x16x32_bf16 v[82:85], v[12:15], v[40:43], v[0:3]
	v_mfma_f32_16x16x32_bf16 v[0:3], v[16:19], v[36:39], 0
	v_mfma_f32_16x16x32_bf16 v[86:89], v[20:23], v[40:43], v[0:3]
	v_mfma_f32_16x16x32_bf16 v[0:3], v[8:11], v[44:47], 0
	v_mfma_f32_16x16x32_bf16 v[90:93], v[12:15], v[48:51], v[0:3]
	v_mfma_f32_16x16x32_bf16 v[0:3], v[16:19], v[44:47], 0
	v_mfma_f32_16x16x32_bf16 v[94:97], v[20:23], v[48:51], v[0:3]
	s_barrier
	s_nop 4
	v_lshl_add_u64 v[0:1], s[26:27], 0, v[66:67]
	s_add_i32 s75, s66, s37
	v_lshl_add_u64 v[2:3], v[0:1], 0, s[14:15]
	s_mov_b32 m0, s75
	ds_read_b128 v[98:101], v107
	ds_read_b128 v[108:111], v107 offset:1024
	ds_read_b128 v[112:115], v107 offset:2048
	ds_read_b128 v[116:119], v107 offset:3072
	global_load_lds_dwordx4 v[2:3], off
	v_lshl_add_u64 v[2:3], s[26:27], 0, v[70:71]
	s_add_i32 s73, s75, 0x2000
	v_lshl_add_u64 v[120:121], v[2:3], 0, s[14:15]
	s_mov_b32 m0, s73
	s_nop 0
	global_load_lds_dwordx4 v[120:121], off
	s_barrier
	s_waitcnt lgkmcnt(0)
	v_mfma_f32_16x16x32_bf16 v[120:123], v[98:101], v[4:7], 0
	v_mfma_f32_16x16x32_bf16 v[4:7], v[112:115], v[4:7], 0
	v_mfma_f32_16x16x32_bf16 v[120:123], v[108:111], v[24:27], v[120:123]
	v_mfma_f32_16x16x32_bf16 v[24:27], v[116:119], v[24:27], v[4:7]
	v_mfma_f32_16x16x32_bf16 v[4:7], v[98:101], v[28:31], 0
	v_mfma_f32_16x16x32_bf16 v[124:127], v[108:111], v[32:35], v[4:7]
	v_mfma_f32_16x16x32_bf16 v[4:7], v[112:115], v[28:31], 0
	v_mfma_f32_16x16x32_bf16 v[28:31], v[116:119], v[32:35], v[4:7]
	v_mfma_f32_16x16x32_bf16 v[4:7], v[98:101], v[36:39], 0
	v_mfma_f32_16x16x32_bf16 v[32:35], v[108:111], v[40:43], v[4:7]
	v_mfma_f32_16x16x32_bf16 v[4:7], v[112:115], v[36:39], 0
	v_mfma_f32_16x16x32_bf16 v[36:39], v[116:119], v[40:43], v[4:7]
	v_mfma_f32_16x16x32_bf16 v[4:7], v[98:101], v[44:47], 0
	v_mfma_f32_16x16x32_bf16 v[40:43], v[108:111], v[48:51], v[4:7]
	v_mfma_f32_16x16x32_bf16 v[4:7], v[112:115], v[44:47], 0
	v_mfma_f32_16x16x32_bf16 v[44:47], v[116:119], v[48:51], v[4:7]
	s_nop 5
	v_lshl_add_u64 v[4:5], s[24:25], 0, v[64:65]
	s_mov_b32 m0, s38
	v_lshl_add_u64 v[6:7], v[4:5], 0, s[14:15]
	s_barrier
	ds_read_b128 v[48:51], v105 offset:16384
	ds_read_b128 v[128:131], v105 offset:17408
	ds_read_b128 v[132:135], v105 offset:18432
	ds_read_b128 v[136:139], v105 offset:19456
	ds_read_b128 v[140:143], v105 offset:20480
	ds_read_b128 v[144:147], v105 offset:21504
	ds_read_b128 v[148:151], v105 offset:22528
	ds_read_b128 v[152:155], v105 offset:23552
	global_load_lds_dwordx4 v[6:7], off
	v_lshl_add_u64 v[6:7], s[24:25], 0, v[68:69]
	v_lshl_add_u64 v[156:157], v[6:7], 0, s[14:15]
	s_mov_b32 m0, s39
	s_nop 0
	global_load_lds_dwordx4 v[156:157], off
	s_barrier
	s_waitcnt lgkmcnt(0)
	v_mfma_f32_16x16x32_bf16 v[156:159], v[8:11], v[48:51], 0
	v_mfma_f32_16x16x32_bf16 v[164:167], v[8:11], v[132:135], 0
	v_mfma_f32_16x16x32_bf16 v[172:175], v[8:11], v[140:143], 0
	v_mfma_f32_16x16x32_bf16 v[8:11], v[8:11], v[148:151], 0
	v_mfma_f32_16x16x32_bf16 v[156:159], v[12:15], v[128:131], v[156:159]
	v_mfma_f32_16x16x32_bf16 v[160:163], v[16:19], v[48:51], 0
	v_mfma_f32_16x16x32_bf16 v[164:167], v[12:15], v[136:139], v[164:167]
	v_mfma_f32_16x16x32_bf16 v[168:171], v[16:19], v[132:135], 0
	v_mfma_f32_16x16x32_bf16 v[172:175], v[12:15], v[144:147], v[172:175]
	v_mfma_f32_16x16x32_bf16 v[176:179], v[16:19], v[140:143], 0
	v_mfma_f32_16x16x32_bf16 v[10:13], v[12:15], v[152:155], v[8:11]
	v_mfma_f32_16x16x32_bf16 v[14:17], v[16:19], v[148:151], 0
	v_mfma_f32_16x16x32_bf16 v[160:163], v[20:23], v[128:131], v[160:163]
	v_mfma_f32_16x16x32_bf16 v[168:171], v[20:23], v[136:139], v[168:171]
	v_mfma_f32_16x16x32_bf16 v[176:179], v[20:23], v[144:147], v[176:179]
	v_mfma_f32_16x16x32_bf16 v[14:17], v[20:23], v[152:155], v[14:17]
	s_barrier
	s_add_u32 s80, s26, 0x18100
	s_addc_u32 s81, s27, 0
	s_add_i32 s76, s67, s37
	v_lshl_add_u64 v[8:9], s[80:81], 0, v[66:67]
	s_mov_b32 m0, s76
	s_add_i32 s74, s76, 0x2000
	global_load_lds_dwordx4 v[8:9], off
	v_lshl_add_u64 v[8:9], s[80:81], 0, v[70:71]
	s_mov_b32 m0, s74
	s_nop 0
	global_load_lds_dwordx4 v[8:9], off
	s_waitcnt vmcnt(6)
	s_barrier
; #define PG8_STAGE(bufoff, gbase, voff) do { _Pragma("unroll") for (int _i = 0; _i < 2; ++_i) \
;         __builtin_amdgcn_global_load_lds((const unsigned*)((const char*)(gbase) + (voff)[_i]), (PG8_LAS unsigned*)(lds + (bufoff) + ldsw + _i * 8192), 16, 0, 0); } while (0)
; #define PG8_LDA(dst, b, h) do { _Pragma("unroll") for (int m = 0; m < 4; ++m) _Pragma("unroll") for (int k = 0; k < 2; ++k) dst[m][k] = *(const PG8_LAS bf16x8*)(lds + PG8_SA(b, h) + aoff + m * 2048 + k * 1024); } while (0)
; #define PG8_LDB(dst, b, h) do { _Pragma("unroll") for (int n = 0; n < 2; ++n) _Pragma("unroll") for (int k = 0; k < 2; ++k) dst[n][k] = *(const PG8_LAS bf16x8*)(lds + PG8_SB(b, h) + boff + n * 2048 + k * 1024); } while (0)
; #define PG8_MMA(ai, bj, At, Bt) do { __builtin_amdgcn_s_setprio(1); _Pragma("unroll") for (int m = 0; m < 4; ++m) _Pragma("unroll") for (int n = 0; n < 2; ++n) _Pragma("unroll") for (int k = 0; k < 2; ++k) \
;         acc[ai][bj][m][n] = __builtin_amdgcn_mfma_f32_16x16x32_bf16(Bt[n][k], At[m][k], acc[ai][bj][m][n], 0, 0, 0); __builtin_amdgcn_s_setprio(0); } while (0)
; #define PG8_WAIT_L(n) asm volatile("s_waitcnt lgkmcnt(" #n ")" ::: "memory")
; #define PG8_BAR __builtin_amdgcn_s_barrier()
; #define PG8_SCHED __builtin_amdgcn_sched_barrier(0)
; template <class Epi, class Sched>
; __device__ __forceinline__ void gemm_phase(PG8_LAS unsigned char* lds, const Gemm g, const Sched& S, const Epi& E) {
;     ...
;             PG8_LDB(B0, 1, 0); PG8_SCHED; PG8_LDA(At, 1, 0); PG8_STAGE(PG8_SA(0, 1), a2 + hstep, voffA);
;             PG8_WAIT_L(8); PG8_BAR; PG8_WAIT_L(0); PG8_MMA(0, 0, At, B0); PG8_BAR; PG8_SCHED;
;             PG8_LDB(B1, 1, 1); PG8_STAGE(PG8_SB(1, 0), b3, voffB);
;             PG8_BAR; PG8_WAIT_L(0); PG8_MMA(0, 1, At, B1); PG8_BAR;
;             PG8_LDA(At, 1, 1); PG8_STAGE(PG8_SA(1, 0), a3, voffA);
;             PG8_BAR; PG8_WAIT_L(0); PG8_MMA(1, 0, At, B0); PG8_BAR; PG8_SCHED;
	v_mfma_f32_16x16x32_bf16 v[18:21], v[98:101], v[48:51], 0
	v_mfma_f32_16x16x32_bf16 v[48:51], v[112:115], v[48:51], 0
	v_mfma_f32_16x16x32_bf16 v[18:21], v[108:111], v[128:131], v[18:21]
	v_mfma_f32_16x16x32_bf16 v[48:51], v[116:119], v[128:131], v[48:51]
	v_mfma_f32_16x16x32_bf16 v[128:131], v[98:101], v[132:135], 0
	v_mfma_f32_16x16x32_bf16 v[132:135], v[112:115], v[132:135], 0
	v_mfma_f32_16x16x32_bf16 v[128:131], v[108:111], v[136:139], v[128:131]
	v_mfma_f32_16x16x32_bf16 v[132:135], v[116:119], v[136:139], v[132:135]
	v_mfma_f32_16x16x32_bf16 v[136:139], v[98:101], v[140:143], 0
	v_mfma_f32_16x16x32_bf16 v[98:101], v[98:101], v[148:151], 0
	v_mfma_f32_16x16x32_bf16 v[136:139], v[108:111], v[144:147], v[136:139]
	v_mfma_f32_16x16x32_bf16 v[140:143], v[112:115], v[140:143], 0
	v_mfma_f32_16x16x32_bf16 v[98:101], v[108:111], v[152:155], v[98:101]
	v_mfma_f32_16x16x32_bf16 v[108:111], v[112:115], v[148:151], 0
	v_mfma_f32_16x16x32_bf16 v[140:143], v[116:119], v[144:147], v[140:143]
	v_mfma_f32_16x16x32_bf16 v[108:111], v[116:119], v[152:155], v[108:111]
	s_add_i32 s77, 0, 0x18000
	v_add_u32_e32 v8, s77, v104
	s_barrier
	ds_read_b128 v[112:115], v8
	ds_read_b128 v[116:119], v8 offset:1024
	ds_read_b128 v[144:147], v8 offset:2048
	ds_read_b128 v[148:151], v8 offset:3072
	s_add_u32 s80, s24, 0x18100
	s_addc_u32 s81, s25, 0
	s_mov_b32 m0, s40
	v_lshl_add_u64 v[22:23], s[80:81], 0, v[64:65]
	ds_read_b128 v[152:155], v105 offset:32768
	ds_read_b128 v[180:183], v105 offset:33792
	ds_read_b128 v[184:187], v105 offset:34816
	ds_read_b128 v[188:191], v105 offset:35840
	ds_read_b128 v[192:195], v105 offset:36864
	ds_read_b128 v[196:199], v105 offset:37888
	ds_read_b128 v[200:203], v105 offset:38912
	ds_read_b128 v[204:207], v105 offset:39936
	global_load_lds_dwordx4 v[22:23], off
	v_lshl_add_u64 v[22:23], s[80:81], 0, v[68:69]
	s_mov_b32 m0, s41
	s_nop 0
	global_load_lds_dwordx4 v[22:23], off
	s_waitcnt lgkmcnt(8)
	s_barrier
	s_waitcnt lgkmcnt(0)
	v_mfma_f32_16x16x32_bf16 v[52:55], v[112:115], v[152:155], v[52:55]
	v_mfma_f32_16x16x32_bf16 v[56:59], v[144:147], v[152:155], v[56:59]
	v_mfma_f32_16x16x32_bf16 v[60:63], v[112:115], v[184:187], v[60:63]
	v_mfma_f32_16x16x32_bf16 v[78:81], v[144:147], v[184:187], v[78:81]
	v_mfma_f32_16x16x32_bf16 v[82:85], v[112:115], v[192:195], v[82:85]
	v_mfma_f32_16x16x32_bf16 v[86:89], v[144:147], v[192:195], v[86:89]
	v_mfma_f32_16x16x32_bf16 v[90:93], v[112:115], v[200:203], v[90:93]
	v_mfma_f32_16x16x32_bf16 v[94:97], v[144:147], v[200:203], v[94:97]
	v_mfma_f32_16x16x32_bf16 v[52:55], v[116:119], v[180:183], v[52:55]
	v_mfma_f32_16x16x32_bf16 v[56:59], v[148:151], v[180:183], v[56:59]
	v_mfma_f32_16x16x32_bf16 v[60:63], v[116:119], v[188:191], v[60:63]
	v_mfma_f32_16x16x32_bf16 v[78:81], v[148:151], v[188:191], v[78:81]
	v_mfma_f32_16x16x32_bf16 v[82:85], v[116:119], v[196:199], v[82:85]
	v_mfma_f32_16x16x32_bf16 v[86:89], v[148:151], v[196:199], v[86:89]
	v_mfma_f32_16x16x32_bf16 v[90:93], v[116:119], v[204:207], v[90:93]
	v_mfma_f32_16x16x32_bf16 v[94:97], v[148:151], v[204:207], v[94:97]
	s_barrier
	s_add_i32 s81, 0, 0x1c000
	s_add_i32 s80, s77, s37
	v_add_u32_e32 v9, s81, v104
	v_lshl_add_u64 v[22:23], v[0:1], 0, s[16:17]
	s_mov_b32 m0, s80
	s_add_i32 s77, s80, 0x2000
	ds_read_b128 v[208:211], v9
	ds_read_b128 v[212:215], v9 offset:1024
	ds_read_b128 v[216:219], v9 offset:2048
	ds_read_b128 v[220:223], v9 offset:3072
	global_load_lds_dwordx4 v[22:23], off
	v_lshl_add_u64 v[22:23], v[2:3], 0, s[16:17]
	s_mov_b32 m0, s77
	s_nop 0
	global_load_lds_dwordx4 v[22:23], off
	s_barrier
	s_waitcnt lgkmcnt(0)
	v_mfma_f32_16x16x32_bf16 v[120:123], v[208:211], v[152:155], v[120:123]
	v_mfma_f32_16x16x32_bf16 v[22:25], v[216:219], v[152:155], v[24:27]
	v_mfma_f32_16x16x32_bf16 v[124:127], v[208:211], v[184:187], v[124:127]
	v_mfma_f32_16x16x32_bf16 v[26:29], v[216:219], v[184:187], v[28:31]
	v_mfma_f32_16x16x32_bf16 v[30:33], v[208:211], v[192:195], v[32:35]
	v_mfma_f32_16x16x32_bf16 v[34:37], v[216:219], v[192:195], v[36:39]
	v_mfma_f32_16x16x32_bf16 v[38:41], v[208:211], v[200:203], v[40:43]
	v_mfma_f32_16x16x32_bf16 v[42:45], v[216:219], v[200:203], v[44:47]
	v_mfma_f32_16x16x32_bf16 v[120:123], v[212:215], v[180:183], v[120:123]
	v_mfma_f32_16x16x32_bf16 v[22:25], v[220:223], v[180:183], v[22:25]
	v_mfma_f32_16x16x32_bf16 v[124:127], v[212:215], v[188:191], v[124:127]
	v_mfma_f32_16x16x32_bf16 v[26:29], v[220:223], v[188:191], v[26:29]
	v_mfma_f32_16x16x32_bf16 v[30:33], v[212:215], v[196:199], v[30:33]
	v_mfma_f32_16x16x32_bf16 v[34:37], v[220:223], v[196:199], v[34:37]
	v_mfma_f32_16x16x32_bf16 v[38:41], v[212:215], v[204:207], v[38:41]
	v_mfma_f32_16x16x32_bf16 v[42:45], v[220:223], v[204:207], v[42:45]
	s_mov_b32 m0, s43
	v_lshl_add_u64 v[46:47], v[4:5], 0, s[16:17]
	s_barrier
	ds_read_b128 v[152:155], v105 offset:49152
	ds_read_b128 v[180:183], v105 offset:50176
	ds_read_b128 v[184:187], v105 offset:51200
	ds_read_b128 v[188:191], v105 offset:52224
	ds_read_b128 v[192:195], v105 offset:53248
	ds_read_b128 v[196:199], v105 offset:54272
	ds_read_b128 v[200:203], v105 offset:55296
	ds_read_b128 v[204:207], v105 offset:56320
	global_load_lds_dwordx4 v[46:47], off
	v_lshl_add_u64 v[46:47], v[6:7], 0, s[16:17]
	s_mov_b32 m0, s60
	s_nop 0
	global_load_lds_dwordx4 v[46:47], off
	s_barrier
; #define PG8_STAGE(bufoff, gbase, voff) do { _Pragma("unroll") for (int _i = 0; _i < 2; ++_i) \
;         __builtin_amdgcn_global_load_lds((const unsigned*)((const char*)(gbase) + (voff)[_i]), (PG8_LAS unsigned*)(lds + (bufoff) + ldsw + _i * 8192), 16, 0, 0); } while (0)
; #define PG8_LDA(dst, b, h) do { _Pragma("unroll") for (int m = 0; m < 4; ++m) _Pragma("unroll") for (int k = 0; k < 2; ++k) dst[m][k] = *(const PG8_LAS bf16x8*)(lds + PG8_SA(b, h) + aoff + m * 2048 + k * 1024); } while (0)
; #define PG8_LDB(dst, b, h) do { _Pragma("unroll") for (int n = 0; n < 2; ++n) _Pragma("unroll") for (int k = 0; k < 2; ++k) dst[n][k] = *(const PG8_LAS bf16x8*)(lds + PG8_SB(b, h) + boff + n * 2048 + k * 1024); } while (0)
; #define PG8_MMA(ai, bj, At, Bt) do { __builtin_amdgcn_s_setprio(1); _Pragma("unroll") for (int m = 0; m < 4; ++m) _Pragma("unroll") for (int n = 0; n < 2; ++n) _Pragma("unroll") for (int k = 0; k < 2; ++k) \
;         acc[ai][bj][m][n] = __builtin_amdgcn_mfma_f32_16x16x32_bf16(Bt[n][k], At[m][k], acc[ai][bj][m][n], 0, 0, 0); __builtin_amdgcn_s_setprio(0); } while (0)
; #define PG8_WAIT_V(n) asm volatile("s_waitcnt vmcnt(" #n ")" ::: "memory")
; #define PG8_WAIT_L(n) asm volatile("s_waitcnt lgkmcnt(" #n ")" ::: "memory")
; #define PG8_BAR __builtin_amdgcn_s_barrier()
; #define PG8_SCHED __builtin_amdgcn_sched_barrier(0)
; template <class Epi, class Sched>
; __device__ __forceinline__ void gemm_phase(PG8_LAS unsigned char* lds, const Gemm g, const Sched& S, const Epi& E) {
;     ...
;             PG8_LDB(B0, 0, 0); PG8_SCHED; PG8_LDA(At, 0, 0); PG8_STAGE(PG8_SA(1, 1), a1 + hstep, voffA);
;             PG8_WAIT_L(8); PG8_BAR; PG8_WAIT_L(0); PG8_MMA(0, 0, At, B0); PG8_BAR; PG8_SCHED;
;             PG8_LDB(B1, 0, 1); PG8_STAGE(PG8_SB(0, 0), b2, voffB);
;             PG8_BAR; PG8_WAIT_L(0); PG8_MMA(0, 1, At, B1); PG8_BAR;
;             PG8_LDA(At, 0, 1); PG8_STAGE(PG8_SA(0, 0), a2, voffA);
;             PG8_BAR; PG8_WAIT_L(0); PG8_MMA(1, 0, At, B0); PG8_BAR; PG8_SCHED;
;     ...
;             PG8_BAR; PG8_WAIT_L(0); PG8_MMA(1, 0, At, B0); PG8_BAR; PG8_SCHED;
;             PG8_STAGE(PG8_SB(1, 1), b3 + hstep, voffB);
;             PG8_WAIT_V(6); PG8_BAR; PG8_MMA(1, 1, At, B1); PG8_BAR;
	s_waitcnt lgkmcnt(0)
	v_mfma_f32_16x16x32_bf16 v[156:159], v[112:115], v[152:155], v[156:159]
	v_mfma_f32_16x16x32_bf16 v[160:163], v[144:147], v[152:155], v[160:163]
	v_mfma_f32_16x16x32_bf16 v[164:167], v[112:115], v[184:187], v[164:167]
	v_mfma_f32_16x16x32_bf16 v[168:171], v[144:147], v[184:187], v[168:171]
	v_mfma_f32_16x16x32_bf16 v[172:175], v[112:115], v[192:195], v[172:175]
	v_mfma_f32_16x16x32_bf16 v[176:179], v[144:147], v[192:195], v[176:179]
	v_mfma_f32_16x16x32_bf16 v[10:13], v[112:115], v[200:203], v[10:13]
	v_mfma_f32_16x16x32_bf16 v[14:17], v[144:147], v[200:203], v[14:17]
	v_mfma_f32_16x16x32_bf16 v[156:159], v[116:119], v[180:183], v[156:159]
	v_mfma_f32_16x16x32_bf16 v[160:163], v[148:151], v[180:183], v[160:163]
	v_mfma_f32_16x16x32_bf16 v[164:167], v[116:119], v[188:191], v[164:167]
	v_mfma_f32_16x16x32_bf16 v[168:171], v[148:151], v[188:191], v[168:171]
	v_mfma_f32_16x16x32_bf16 v[172:175], v[116:119], v[196:199], v[172:175]
	v_mfma_f32_16x16x32_bf16 v[176:179], v[148:151], v[196:199], v[176:179]
	v_mfma_f32_16x16x32_bf16 v[10:13], v[116:119], v[204:207], v[10:13]
	v_mfma_f32_16x16x32_bf16 v[14:17], v[148:151], v[204:207], v[14:17]
	s_barrier
	s_add_u32 s82, s26, 0x18180
	s_addc_u32 s83, s27, 0
	s_add_i32 s81, s81, s37
	v_lshl_add_u64 v[46:47], s[82:83], 0, v[66:67]
	s_mov_b32 m0, s81
	s_add_i32 s78, s81, 0x2000
	global_load_lds_dwordx4 v[46:47], off
	v_lshl_add_u64 v[46:47], s[82:83], 0, v[70:71]
	s_mov_b32 m0, s78
	s_nop 0
	global_load_lds_dwordx4 v[46:47], off
	s_waitcnt vmcnt(6)
	s_barrier
	v_mfma_f32_16x16x32_bf16 v[18:21], v[208:211], v[152:155], v[18:21]
	v_mfma_f32_16x16x32_bf16 v[46:49], v[216:219], v[152:155], v[48:51]
	v_mfma_f32_16x16x32_bf16 v[112:115], v[208:211], v[184:187], v[128:131]
	v_mfma_f32_16x16x32_bf16 v[116:119], v[216:219], v[184:187], v[132:135]
	v_mfma_f32_16x16x32_bf16 v[128:131], v[208:211], v[192:195], v[136:139]
	v_mfma_f32_16x16x32_bf16 v[132:135], v[216:219], v[192:195], v[140:143]
	v_mfma_f32_16x16x32_bf16 v[98:101], v[208:211], v[200:203], v[98:101]
	v_mfma_f32_16x16x32_bf16 v[108:111], v[216:219], v[200:203], v[108:111]
	v_mfma_f32_16x16x32_bf16 v[18:21], v[212:215], v[180:183], v[18:21]
	v_mfma_f32_16x16x32_bf16 v[46:49], v[220:223], v[180:183], v[46:49]
	v_mfma_f32_16x16x32_bf16 v[112:115], v[212:215], v[188:191], v[112:115]
	v_mfma_f32_16x16x32_bf16 v[116:119], v[220:223], v[188:191], v[116:119]
	v_mfma_f32_16x16x32_bf16 v[128:131], v[212:215], v[196:199], v[128:131]
	v_mfma_f32_16x16x32_bf16 v[132:135], v[220:223], v[196:199], v[132:135]
	v_mfma_f32_16x16x32_bf16 v[98:101], v[212:215], v[204:207], v[98:101]
	v_mfma_f32_16x16x32_bf16 v[108:111], v[220:223], v[204:207], v[108:111]
	s_barrier
	ds_read_b128 v[136:139], v106
	ds_read_b128 v[140:143], v106 offset:1024
	ds_read_b128 v[144:147], v106 offset:2048
	ds_read_b128 v[148:151], v106 offset:3072
	s_add_u32 s82, s24, 0x18180
	s_addc_u32 s83, s25, 0
	s_mov_b32 m0, s79
	v_lshl_add_u64 v[50:51], s[82:83], 0, v[64:65]
	ds_read_b128 v[152:155], v105
	ds_read_b128 v[180:183], v105 offset:1024
	ds_read_b128 v[184:187], v105 offset:2048
	ds_read_b128 v[188:191], v105 offset:3072
	ds_read_b128 v[192:195], v105 offset:4096
	ds_read_b128 v[196:199], v105 offset:5120
	ds_read_b128 v[200:203], v105 offset:6144
	ds_read_b128 v[204:207], v105 offset:7168
	global_load_lds_dwordx4 v[50:51], off
	v_lshl_add_u64 v[50:51], s[82:83], 0, v[68:69]
	s_mov_b32 m0, s72
	s_nop 0
	global_load_lds_dwordx4 v[50:51], off
	s_waitcnt lgkmcnt(8)
	s_barrier
	s_waitcnt lgkmcnt(0)
	v_mfma_f32_16x16x32_bf16 v[50:53], v[136:139], v[152:155], v[52:55]
	v_mfma_f32_16x16x32_bf16 v[54:57], v[144:147], v[152:155], v[56:59]
	v_mfma_f32_16x16x32_bf16 v[58:61], v[136:139], v[184:187], v[60:63]
	v_mfma_f32_16x16x32_bf16 v[78:81], v[144:147], v[184:187], v[78:81]
	v_mfma_f32_16x16x32_bf16 v[82:85], v[136:139], v[192:195], v[82:85]
	v_mfma_f32_16x16x32_bf16 v[86:89], v[144:147], v[192:195], v[86:89]
	v_mfma_f32_16x16x32_bf16 v[90:93], v[136:139], v[200:203], v[90:93]
	v_mfma_f32_16x16x32_bf16 v[94:97], v[144:147], v[200:203], v[94:97]
	v_mfma_f32_16x16x32_bf16 v[50:53], v[140:143], v[180:183], v[50:53]
	v_mfma_f32_16x16x32_bf16 v[54:57], v[148:151], v[180:183], v[54:57]
	v_mfma_f32_16x16x32_bf16 v[58:61], v[140:143], v[188:191], v[58:61]
	v_mfma_f32_16x16x32_bf16 v[78:81], v[148:151], v[188:191], v[78:81]
	v_mfma_f32_16x16x32_bf16 v[82:85], v[140:143], v[196:199], v[82:85]
	v_mfma_f32_16x16x32_bf16 v[86:89], v[148:151], v[196:199], v[86:89]
	v_mfma_f32_16x16x32_bf16 v[90:93], v[140:143], v[204:207], v[90:93]
	v_mfma_f32_16x16x32_bf16 v[94:97], v[148:151], v[204:207], v[94:97]
	s_barrier
	s_mov_b32 m0, s75
	v_lshl_add_u64 v[62:63], v[0:1], 0, s[12:13]
	ds_read_b128 v[208:211], v107
	ds_read_b128 v[212:215], v107 offset:1024
	ds_read_b128 v[216:219], v107 offset:2048
	ds_read_b128 v[220:223], v107 offset:3072
	global_load_lds_dwordx4 v[62:63], off
	v_lshl_add_u64 v[62:63], v[2:3], 0, s[12:13]
	s_mov_b32 m0, s73
	s_nop 0
	global_load_lds_dwordx4 v[62:63], off
	s_barrier
	s_waitcnt lgkmcnt(0)
	v_mfma_f32_16x16x32_bf16 v[120:123], v[208:211], v[152:155], v[120:123]
	v_mfma_f32_16x16x32_bf16 v[22:25], v[216:219], v[152:155], v[22:25]
	v_mfma_f32_16x16x32_bf16 v[124:127], v[208:211], v[184:187], v[124:127]
	v_mfma_f32_16x16x32_bf16 v[26:29], v[216:219], v[184:187], v[26:29]
	v_mfma_f32_16x16x32_bf16 v[30:33], v[208:211], v[192:195], v[30:33]
	v_mfma_f32_16x16x32_bf16 v[34:37], v[216:219], v[192:195], v[34:37]
	v_mfma_f32_16x16x32_bf16 v[38:41], v[208:211], v[200:203], v[38:41]
	v_mfma_f32_16x16x32_bf16 v[42:45], v[216:219], v[200:203], v[42:45]
	v_mfma_f32_16x16x32_bf16 v[120:123], v[212:215], v[180:183], v[120:123]
	v_mfma_f32_16x16x32_bf16 v[22:25], v[220:223], v[180:183], v[22:25]
	v_mfma_f32_16x16x32_bf16 v[124:127], v[212:215], v[188:191], v[124:127]
	v_mfma_f32_16x16x32_bf16 v[26:29], v[220:223], v[188:191], v[26:29]
	v_mfma_f32_16x16x32_bf16 v[30:33], v[212:215], v[196:199], v[30:33]
	v_mfma_f32_16x16x32_bf16 v[34:37], v[220:223], v[196:199], v[34:37]
	v_mfma_f32_16x16x32_bf16 v[38:41], v[212:215], v[204:207], v[38:41]
	v_mfma_f32_16x16x32_bf16 v[42:45], v[220:223], v[204:207], v[42:45]
	s_mov_b32 m0, s38
	v_lshl_add_u64 v[62:63], v[4:5], 0, s[12:13]
	s_barrier
; #define PG8_STAGE(bufoff, gbase, voff) do { _Pragma("unroll") for (int _i = 0; _i < 2; ++_i) \
;         __builtin_amdgcn_global_load_lds((const unsigned*)((const char*)(gbase) + (voff)[_i]), (PG8_LAS unsigned*)(lds + (bufoff) + ldsw + _i * 8192), 16, 0, 0); } while (0)
; #define PG8_LDA(dst, b, h) do { _Pragma("unroll") for (int m = 0; m < 4; ++m) _Pragma("unroll") for (int k = 0; k < 2; ++k) dst[m][k] = *(const PG8_LAS bf16x8*)(lds + PG8_SA(b, h) + aoff + m * 2048 + k * 1024); } while (0)
; #define PG8_LDB(dst, b, h) do { _Pragma("unroll") for (int n = 0; n < 2; ++n) _Pragma("unroll") for (int k = 0; k < 2; ++k) dst[n][k] = *(const PG8_LAS bf16x8*)(lds + PG8_SB(b, h) + boff + n * 2048 + k * 1024); } while (0)
; #define PG8_MMA(ai, bj, At, Bt) do { __builtin_amdgcn_s_setprio(1); _Pragma("unroll") for (int m = 0; m < 4; ++m) _Pragma("unroll") for (int n = 0; n < 2; ++n) _Pragma("unroll") for (int k = 0; k < 2; ++k) \
;         acc[ai][bj][m][n] = __builtin_amdgcn_mfma_f32_16x16x32_bf16(Bt[n][k], At[m][k], acc[ai][bj][m][n], 0, 0, 0); __builtin_amdgcn_s_setprio(0); } while (0)
; #define PG8_WAIT_V(n) asm volatile("s_waitcnt vmcnt(" #n ")" ::: "memory")
; #define PG8_WAIT_L(n) asm volatile("s_waitcnt lgkmcnt(" #n ")" ::: "memory")
; #define PG8_BAR __builtin_amdgcn_s_barrier()
; #define PG8_SCHED __builtin_amdgcn_sched_barrier(0)
; template <class Epi, class Sched>
; __device__ __forceinline__ void gemm_phase(PG8_LAS unsigned char* lds, const Gemm g, const Sched& S, const Epi& E) {
;     ...
;             PG8_LDA(At, 0, 1); PG8_STAGE(PG8_SA(0, 0), a2, voffA);
;             PG8_BAR; PG8_WAIT_L(0); PG8_MMA(1, 0, At, B0); PG8_BAR; PG8_SCHED;
;             PG8_STAGE(PG8_SB(0, 1), b2 + hstep, voffB);
;             PG8_WAIT_V(6); PG8_BAR; PG8_MMA(1, 1, At, B1); PG8_BAR;
;             PG8_LDB(B0, 1, 0); PG8_SCHED; PG8_LDA(At, 1, 0); PG8_STAGE(PG8_SA(0, 1), a2 + hstep, voffA);
;             PG8_WAIT_L(8); PG8_BAR; PG8_WAIT_L(0); PG8_MMA(0, 0, At, B0); PG8_BAR; PG8_SCHED;
;             PG8_LDB(B1, 1, 1); PG8_STAGE(PG8_SB(1, 0), b3, voffB);
;             PG8_BAR; PG8_WAIT_L(0); PG8_MMA(0, 1, At, B1); PG8_BAR;
;             PG8_LDA(At, 1, 1); PG8_STAGE(PG8_SA(1, 0), a3, voffA);
;             PG8_BAR; PG8_WAIT_L(0); PG8_MMA(1, 0, At, B0); PG8_BAR; PG8_SCHED;
	ds_read_b128 v[152:155], v105 offset:16384
	ds_read_b128 v[180:183], v105 offset:17408
	ds_read_b128 v[184:187], v105 offset:18432
	ds_read_b128 v[188:191], v105 offset:19456
	ds_read_b128 v[192:195], v105 offset:20480
	ds_read_b128 v[196:199], v105 offset:21504
	ds_read_b128 v[200:203], v105 offset:22528
	ds_read_b128 v[204:207], v105 offset:23552
	global_load_lds_dwordx4 v[62:63], off
	v_lshl_add_u64 v[62:63], v[6:7], 0, s[12:13]
	s_mov_b32 m0, s39
	s_nop 0
	global_load_lds_dwordx4 v[62:63], off
	s_barrier
	s_waitcnt lgkmcnt(0)
	v_mfma_f32_16x16x32_bf16 v[156:159], v[136:139], v[152:155], v[156:159]
	v_mfma_f32_16x16x32_bf16 v[160:163], v[144:147], v[152:155], v[160:163]
	v_mfma_f32_16x16x32_bf16 v[164:167], v[136:139], v[184:187], v[164:167]
	v_mfma_f32_16x16x32_bf16 v[168:171], v[144:147], v[184:187], v[168:171]
	v_mfma_f32_16x16x32_bf16 v[172:175], v[136:139], v[192:195], v[172:175]
	v_mfma_f32_16x16x32_bf16 v[176:179], v[144:147], v[192:195], v[176:179]
	v_mfma_f32_16x16x32_bf16 v[10:13], v[136:139], v[200:203], v[10:13]
	v_mfma_f32_16x16x32_bf16 v[14:17], v[144:147], v[200:203], v[14:17]
	v_mfma_f32_16x16x32_bf16 v[156:159], v[140:143], v[180:183], v[156:159]
	v_mfma_f32_16x16x32_bf16 v[160:163], v[148:151], v[180:183], v[160:163]
	v_mfma_f32_16x16x32_bf16 v[164:167], v[140:143], v[188:191], v[164:167]
	v_mfma_f32_16x16x32_bf16 v[168:171], v[148:151], v[188:191], v[168:171]
	v_mfma_f32_16x16x32_bf16 v[172:175], v[140:143], v[196:199], v[172:175]
	v_mfma_f32_16x16x32_bf16 v[176:179], v[148:151], v[196:199], v[176:179]
	v_mfma_f32_16x16x32_bf16 v[10:13], v[140:143], v[204:207], v[10:13]
	v_mfma_f32_16x16x32_bf16 v[14:17], v[148:151], v[204:207], v[14:17]
	s_barrier
	s_add_u32 s82, s26, 0x18200
	s_addc_u32 s83, s27, 0
	s_mov_b32 m0, s76
	v_lshl_add_u64 v[62:63], s[82:83], 0, v[66:67]
	global_load_lds_dwordx4 v[62:63], off
	v_lshl_add_u64 v[62:63], s[82:83], 0, v[70:71]
	s_mov_b32 m0, s74
	s_nop 0
	global_load_lds_dwordx4 v[62:63], off
	s_waitcnt vmcnt(6)
	s_barrier
	v_mfma_f32_16x16x32_bf16 v[18:21], v[208:211], v[152:155], v[18:21]
	v_mfma_f32_16x16x32_bf16 v[46:49], v[216:219], v[152:155], v[46:49]
	v_mfma_f32_16x16x32_bf16 v[112:115], v[208:211], v[184:187], v[112:115]
	v_mfma_f32_16x16x32_bf16 v[116:119], v[216:219], v[184:187], v[116:119]
	v_mfma_f32_16x16x32_bf16 v[128:131], v[208:211], v[192:195], v[128:131]
	v_mfma_f32_16x16x32_bf16 v[132:135], v[216:219], v[192:195], v[132:135]
	v_mfma_f32_16x16x32_bf16 v[98:101], v[208:211], v[200:203], v[98:101]
	v_mfma_f32_16x16x32_bf16 v[108:111], v[216:219], v[200:203], v[108:111]
	v_mfma_f32_16x16x32_bf16 v[18:21], v[212:215], v[180:183], v[18:21]
	v_mfma_f32_16x16x32_bf16 v[46:49], v[220:223], v[180:183], v[46:49]
	v_mfma_f32_16x16x32_bf16 v[112:115], v[212:215], v[188:191], v[112:115]
	v_mfma_f32_16x16x32_bf16 v[116:119], v[220:223], v[188:191], v[116:119]
	v_mfma_f32_16x16x32_bf16 v[128:131], v[212:215], v[196:199], v[128:131]
	v_mfma_f32_16x16x32_bf16 v[132:135], v[220:223], v[196:199], v[132:135]
	v_mfma_f32_16x16x32_bf16 v[98:101], v[212:215], v[204:207], v[98:101]
	v_mfma_f32_16x16x32_bf16 v[108:111], v[220:223], v[204:207], v[108:111]
	s_barrier
	ds_read_b128 v[136:139], v8
	ds_read_b128 v[140:143], v8 offset:1024
	ds_read_b128 v[144:147], v8 offset:2048
	ds_read_b128 v[148:151], v8 offset:3072
	s_add_u32 s82, s24, 0x18200
	s_addc_u32 s83, s25, 0
	s_mov_b32 m0, s40
	v_lshl_add_u64 v[62:63], s[82:83], 0, v[64:65]
	ds_read_b128 v[152:155], v105 offset:32768
	ds_read_b128 v[180:183], v105 offset:33792
	ds_read_b128 v[184:187], v105 offset:34816
	ds_read_b128 v[188:191], v105 offset:35840
	ds_read_b128 v[192:195], v105 offset:36864
	ds_read_b128 v[196:199], v105 offset:37888
	ds_read_b128 v[200:203], v105 offset:38912
	ds_read_b128 v[204:207], v105 offset:39936
	global_load_lds_dwordx4 v[62:63], off
	v_lshl_add_u64 v[62:63], s[82:83], 0, v[68:69]
	s_mov_b32 m0, s41
	s_nop 0
	global_load_lds_dwordx4 v[62:63], off
	s_waitcnt lgkmcnt(8)
	s_barrier
	s_waitcnt lgkmcnt(0)
	v_mfma_f32_16x16x32_bf16 v[50:53], v[136:139], v[152:155], v[50:53]
	v_mfma_f32_16x16x32_bf16 v[54:57], v[144:147], v[152:155], v[54:57]
	v_mfma_f32_16x16x32_bf16 v[58:61], v[136:139], v[184:187], v[58:61]
	v_mfma_f32_16x16x32_bf16 v[78:81], v[144:147], v[184:187], v[78:81]
	v_mfma_f32_16x16x32_bf16 v[82:85], v[136:139], v[192:195], v[82:85]
	v_mfma_f32_16x16x32_bf16 v[86:89], v[144:147], v[192:195], v[86:89]
	v_mfma_f32_16x16x32_bf16 v[90:93], v[136:139], v[200:203], v[90:93]
	v_mfma_f32_16x16x32_bf16 v[94:97], v[144:147], v[200:203], v[94:97]
	v_mfma_f32_16x16x32_bf16 v[50:53], v[140:143], v[180:183], v[50:53]
	v_mfma_f32_16x16x32_bf16 v[54:57], v[148:151], v[180:183], v[54:57]
	v_mfma_f32_16x16x32_bf16 v[58:61], v[140:143], v[188:191], v[58:61]
	v_mfma_f32_16x16x32_bf16 v[78:81], v[148:151], v[188:191], v[78:81]
	v_mfma_f32_16x16x32_bf16 v[82:85], v[140:143], v[196:199], v[82:85]
	v_mfma_f32_16x16x32_bf16 v[86:89], v[148:151], v[196:199], v[86:89]
	v_mfma_f32_16x16x32_bf16 v[90:93], v[140:143], v[204:207], v[90:93]
	v_mfma_f32_16x16x32_bf16 v[94:97], v[148:151], v[204:207], v[94:97]
	s_barrier
	s_mov_b32 m0, s80
	v_lshl_add_u64 v[0:1], v[0:1], 0, s[18:19]
	ds_read_b128 v[208:211], v9
	ds_read_b128 v[212:215], v9 offset:1024
	ds_read_b128 v[216:219], v9 offset:2048
	ds_read_b128 v[220:223], v9 offset:3072
	global_load_lds_dwordx4 v[0:1], off
	v_lshl_add_u64 v[0:1], v[2:3], 0, s[18:19]
	s_mov_b32 m0, s77
	s_nop 0
	global_load_lds_dwordx4 v[0:1], off
	s_barrier
; #define PG8_STAGE(bufoff, gbase, voff) do { _Pragma("unroll") for (int _i = 0; _i < 2; ++_i) \
;         __builtin_amdgcn_global_load_lds((const unsigned*)((const char*)(gbase) + (voff)[_i]), (PG8_LAS unsigned*)(lds + (bufoff) + ldsw + _i * 8192), 16, 0, 0); } while (0)
; #define PG8_LDA(dst, b, h) do { _Pragma("unroll") for (int m = 0; m < 4; ++m) _Pragma("unroll") for (int k = 0; k < 2; ++k) dst[m][k] = *(const PG8_LAS bf16x8*)(lds + PG8_SA(b, h) + aoff + m * 2048 + k * 1024); } while (0)
; #define PG8_LDB(dst, b, h) do { _Pragma("unroll") for (int n = 0; n < 2; ++n) _Pragma("unroll") for (int k = 0; k < 2; ++k) dst[n][k] = *(const PG8_LAS bf16x8*)(lds + PG8_SB(b, h) + boff + n * 2048 + k * 1024); } while (0)
; #define PG8_MMA(ai, bj, At, Bt) do { __builtin_amdgcn_s_setprio(1); _Pragma("unroll") for (int m = 0; m < 4; ++m) _Pragma("unroll") for (int n = 0; n < 2; ++n) _Pragma("unroll") for (int k = 0; k < 2; ++k) \
;         acc[ai][bj][m][n] = __builtin_amdgcn_mfma_f32_16x16x32_bf16(Bt[n][k], At[m][k], acc[ai][bj][m][n], 0, 0, 0); __builtin_amdgcn_s_setprio(0); } while (0)
; #define PG8_WAIT_V(n) asm volatile("s_waitcnt vmcnt(" #n ")" ::: "memory")
; #define PG8_WAIT_L(n) asm volatile("s_waitcnt lgkmcnt(" #n ")" ::: "memory")
; #define PG8_BAR __builtin_amdgcn_s_barrier()
; #define PG8_SCHED __builtin_amdgcn_sched_barrier(0)
; template <class Epi, class Sched>
; __device__ __forceinline__ void gemm_phase(PG8_LAS unsigned char* lds, const Gemm g, const Sched& S, const Epi& E) {
;     ...
;             PG8_LDB(B0, 0, 0); PG8_SCHED; PG8_LDA(At, 0, 0); PG8_STAGE(PG8_SA(1, 1), a1 + hstep, voffA);
;             PG8_WAIT_L(8); PG8_BAR; PG8_WAIT_L(0); PG8_MMA(0, 0, At, B0); PG8_BAR; PG8_SCHED;
;             PG8_LDB(B1, 0, 1); PG8_STAGE(PG8_SB(0, 0), b2, voffB);
;     ...
;             PG8_LDB(B1, 1, 1); PG8_STAGE(PG8_SB(1, 0), b3, voffB);
;             PG8_BAR; PG8_WAIT_L(0); PG8_MMA(0, 1, At, B1); PG8_BAR;
;             PG8_LDA(At, 1, 1); PG8_STAGE(PG8_SA(1, 0), a3, voffA);
;             PG8_BAR; PG8_WAIT_L(0); PG8_MMA(1, 0, At, B0); PG8_BAR; PG8_SCHED;
;             PG8_STAGE(PG8_SB(1, 1), b3 + hstep, voffB);
;             PG8_WAIT_V(6); PG8_BAR; PG8_MMA(1, 1, At, B1); PG8_BAR;
	s_waitcnt lgkmcnt(0)
	v_mfma_f32_16x16x32_bf16 v[0:3], v[208:211], v[152:155], v[120:123]
	v_mfma_f32_16x16x32_bf16 v[22:25], v[216:219], v[152:155], v[22:25]
	v_mfma_f32_16x16x32_bf16 v[120:123], v[208:211], v[184:187], v[124:127]
	v_mfma_f32_16x16x32_bf16 v[26:29], v[216:219], v[184:187], v[26:29]
	v_mfma_f32_16x16x32_bf16 v[30:33], v[208:211], v[192:195], v[30:33]
	v_mfma_f32_16x16x32_bf16 v[34:37], v[216:219], v[192:195], v[34:37]
	v_mfma_f32_16x16x32_bf16 v[38:41], v[208:211], v[200:203], v[38:41]
	v_mfma_f32_16x16x32_bf16 v[42:45], v[216:219], v[200:203], v[42:45]
	v_mfma_f32_16x16x32_bf16 v[0:3], v[212:215], v[180:183], v[0:3]
	v_mfma_f32_16x16x32_bf16 v[22:25], v[220:223], v[180:183], v[22:25]
	v_mfma_f32_16x16x32_bf16 v[120:123], v[212:215], v[188:191], v[120:123]
	v_mfma_f32_16x16x32_bf16 v[26:29], v[220:223], v[188:191], v[26:29]
	v_mfma_f32_16x16x32_bf16 v[30:33], v[212:215], v[196:199], v[30:33]
	v_mfma_f32_16x16x32_bf16 v[34:37], v[220:223], v[196:199], v[34:37]
	v_mfma_f32_16x16x32_bf16 v[38:41], v[212:215], v[204:207], v[38:41]
	v_mfma_f32_16x16x32_bf16 v[42:45], v[220:223], v[204:207], v[42:45]
	s_mov_b32 m0, s43
	v_lshl_add_u64 v[4:5], v[4:5], 0, s[18:19]
	s_barrier
	ds_read_b128 v[124:127], v105 offset:49152
	ds_read_b128 v[152:155], v105 offset:50176
	ds_read_b128 v[180:183], v105 offset:51200
	ds_read_b128 v[184:187], v105 offset:52224
	ds_read_b128 v[188:191], v105 offset:53248
	ds_read_b128 v[192:195], v105 offset:54272
	ds_read_b128 v[196:199], v105 offset:55296
	ds_read_b128 v[200:203], v105 offset:56320
	global_load_lds_dwordx4 v[4:5], off
	v_lshl_add_u64 v[4:5], v[6:7], 0, s[18:19]
	s_mov_b32 m0, s60
	s_nop 0
	global_load_lds_dwordx4 v[4:5], off
	s_barrier
	s_waitcnt lgkmcnt(0)
	v_mfma_f32_16x16x32_bf16 v[4:7], v[136:139], v[124:127], v[156:159]
	v_mfma_f32_16x16x32_bf16 v[156:159], v[144:147], v[124:127], v[160:163]
	v_mfma_f32_16x16x32_bf16 v[160:163], v[136:139], v[180:183], v[164:167]
	v_mfma_f32_16x16x32_bf16 v[164:167], v[144:147], v[180:183], v[168:171]
	v_mfma_f32_16x16x32_bf16 v[168:171], v[136:139], v[188:191], v[172:175]
	v_mfma_f32_16x16x32_bf16 v[172:175], v[144:147], v[188:191], v[176:179]
	v_mfma_f32_16x16x32_bf16 v[10:13], v[136:139], v[196:199], v[10:13]
	v_mfma_f32_16x16x32_bf16 v[14:17], v[144:147], v[196:199], v[14:17]
	v_mfma_f32_16x16x32_bf16 v[4:7], v[140:143], v[152:155], v[4:7]
	v_mfma_f32_16x16x32_bf16 v[156:159], v[148:151], v[152:155], v[156:159]
	v_mfma_f32_16x16x32_bf16 v[160:163], v[140:143], v[184:187], v[160:163]
	v_mfma_f32_16x16x32_bf16 v[164:167], v[148:151], v[184:187], v[164:167]
	v_mfma_f32_16x16x32_bf16 v[168:171], v[140:143], v[192:195], v[168:171]
	v_mfma_f32_16x16x32_bf16 v[172:175], v[148:151], v[192:195], v[172:175]
	v_mfma_f32_16x16x32_bf16 v[10:13], v[140:143], v[200:203], v[10:13]
	v_mfma_f32_16x16x32_bf16 v[14:17], v[148:151], v[200:203], v[14:17]
	s_barrier
	s_add_u32 s26, s26, 0x18280
	s_addc_u32 s27, s27, 0
	s_mov_b32 m0, s81
	v_lshl_add_u64 v[62:63], s[26:27], 0, v[66:67]
	global_load_lds_dwordx4 v[62:63], off
	v_lshl_add_u64 v[62:63], s[26:27], 0, v[70:71]
	s_mov_b32 m0, s78
	s_nop 0
	global_load_lds_dwordx4 v[62:63], off
	s_waitcnt vmcnt(6)
	s_barrier
	v_mfma_f32_16x16x32_bf16 v[18:21], v[208:211], v[124:127], v[18:21]
	v_mfma_f32_16x16x32_bf16 v[46:49], v[216:219], v[124:127], v[46:49]
	v_mfma_f32_16x16x32_bf16 v[112:115], v[208:211], v[180:183], v[112:115]
	v_mfma_f32_16x16x32_bf16 v[116:119], v[216:219], v[180:183], v[116:119]
	v_mfma_f32_16x16x32_bf16 v[124:127], v[208:211], v[188:191], v[128:131]
	v_mfma_f32_16x16x32_bf16 v[128:131], v[216:219], v[188:191], v[132:135]
	v_mfma_f32_16x16x32_bf16 v[98:101], v[208:211], v[196:199], v[98:101]
	v_mfma_f32_16x16x32_bf16 v[108:111], v[216:219], v[196:199], v[108:111]
	v_mfma_f32_16x16x32_bf16 v[18:21], v[212:215], v[152:155], v[18:21]
	v_mfma_f32_16x16x32_bf16 v[46:49], v[220:223], v[152:155], v[46:49]
	v_mfma_f32_16x16x32_bf16 v[112:115], v[212:215], v[184:187], v[112:115]
	v_mfma_f32_16x16x32_bf16 v[116:119], v[220:223], v[184:187], v[116:119]
	v_mfma_f32_16x16x32_bf16 v[124:127], v[212:215], v[192:195], v[124:127]
	v_mfma_f32_16x16x32_bf16 v[128:131], v[220:223], v[192:195], v[128:131]
	v_mfma_f32_16x16x32_bf16 v[98:101], v[212:215], v[200:203], v[98:101]
	v_mfma_f32_16x16x32_bf16 v[108:111], v[220:223], v[200:203], v[108:111]
	s_barrier
	ds_read_b128 v[132:135], v106
	ds_read_b128 v[136:139], v106 offset:1024
	ds_read_b128 v[140:143], v106 offset:2048
	ds_read_b128 v[144:147], v106 offset:3072
	s_add_u32 s24, s24, 0x18280
	s_addc_u32 s25, s25, 0
	s_mov_b32 m0, s79
	v_lshl_add_u64 v[62:63], s[24:25], 0, v[64:65]
	ds_read_b128 v[148:151], v105
	ds_read_b128 v[152:155], v105 offset:1024
	ds_read_b128 v[176:179], v105 offset:2048
	ds_read_b128 v[180:183], v105 offset:3072
	ds_read_b128 v[184:187], v105 offset:4096
	ds_read_b128 v[188:191], v105 offset:5120
	ds_read_b128 v[192:195], v105 offset:6144
	ds_read_b128 v[196:199], v105 offset:7168
	global_load_lds_dwordx4 v[62:63], off
	v_lshl_add_u64 v[62:63], s[24:25], 0, v[68:69]
	s_mov_b32 m0, s72
	s_nop 0
	global_load_lds_dwordx4 v[62:63], off
	s_waitcnt lgkmcnt(8)
	s_barrier
; #define PG8_STAGE(bufoff, gbase, voff) do { _Pragma("unroll") for (int _i = 0; _i < 2; ++_i) \
;         __builtin_amdgcn_global_load_lds((const unsigned*)((const char*)(gbase) + (voff)[_i]), (PG8_LAS unsigned*)(lds + (bufoff) + ldsw + _i * 8192), 16, 0, 0); } while (0)
; #define PG8_LDA(dst, b, h) do { _Pragma("unroll") for (int m = 0; m < 4; ++m) _Pragma("unroll") for (int k = 0; k < 2; ++k) dst[m][k] = *(const PG8_LAS bf16x8*)(lds + PG8_SA(b, h) + aoff + m * 2048 + k * 1024); } while (0)
; #define PG8_LDB(dst, b, h) do { _Pragma("unroll") for (int n = 0; n < 2; ++n) _Pragma("unroll") for (int k = 0; k < 2; ++k) dst[n][k] = *(const PG8_LAS bf16x8*)(lds + PG8_SB(b, h) + boff + n * 2048 + k * 1024); } while (0)
; #define PG8_MMA(ai, bj, At, Bt) do { __builtin_amdgcn_s_setprio(1); _Pragma("unroll") for (int m = 0; m < 4; ++m) _Pragma("unroll") for (int n = 0; n < 2; ++n) _Pragma("unroll") for (int k = 0; k < 2; ++k) \
;         acc[ai][bj][m][n] = __builtin_amdgcn_mfma_f32_16x16x32_bf16(Bt[n][k], At[m][k], acc[ai][bj][m][n], 0, 0, 0); __builtin_amdgcn_s_setprio(0); } while (0)
; #define PG8_WAIT_V(n) asm volatile("s_waitcnt vmcnt(" #n ")" ::: "memory")
; #define PG8_WAIT_L(n) asm volatile("s_waitcnt lgkmcnt(" #n ")" ::: "memory")
; template <class Epi, class Sched>
; __device__ __forceinline__ void gemm_phase(PG8_LAS unsigned char* lds, const Gemm g, const Sched& S, const Epi& E) {
;     ...
;             const char* a2 = last ? nA : cA + (size_t)(t + 2) * kstep; const char* b2 = last ? nB : cB + (size_t)(t + 2) * kstep;
;     ...
;             PG8_LDB(B0, 0, 0); PG8_SCHED; PG8_LDA(At, 0, 0); PG8_STAGE(PG8_SA(1, 1), a1 + hstep, voffA);
;             PG8_WAIT_L(8); PG8_BAR; PG8_WAIT_L(0); PG8_MMA(0, 0, At, B0); PG8_BAR; PG8_SCHED;
;             PG8_LDB(B1, 0, 1); PG8_STAGE(PG8_SB(0, 0), b2, voffB);
;             PG8_BAR; PG8_WAIT_L(0); PG8_MMA(0, 1, At, B1); PG8_BAR;
;             PG8_LDA(At, 0, 1); PG8_STAGE(PG8_SA(0, 0), a2, voffA);
;             PG8_BAR; PG8_WAIT_L(0); PG8_MMA(1, 0, At, B0); PG8_BAR; PG8_SCHED;
;             PG8_STAGE(PG8_SB(0, 1), b2 + hstep, voffB);
;             PG8_WAIT_V(6); PG8_BAR; PG8_MMA(1, 1, At, B1); PG8_BAR;
;             PG8_LDB(B0, 1, 0); PG8_SCHED; PG8_LDA(At, 1, 0); PG8_STAGE(PG8_SA(0, 1), a2 + hstep, voffA);
;             PG8_WAIT_L(8); PG8_BAR; PG8_WAIT_L(0); PG8_MMA(0, 0, At, B0); PG8_BAR; PG8_SCHED;
	s_waitcnt lgkmcnt(0)
	v_mfma_f32_16x16x32_bf16 v[58:61], v[132:135], v[176:179], v[58:61]
	v_mfma_f32_16x16x32_bf16 v[200:203], v[136:139], v[180:183], v[58:61]
	v_mfma_f32_16x16x32_bf16 v[58:61], v[140:143], v[176:179], v[78:81]
	v_mfma_f32_16x16x32_bf16 v[78:81], v[144:147], v[180:183], v[58:61]
	v_mfma_f32_16x16x32_bf16 v[58:61], v[132:135], v[184:187], v[82:85]
	v_mfma_f32_16x16x32_bf16 v[82:85], v[136:139], v[188:191], v[58:61]
	v_mfma_f32_16x16x32_bf16 v[58:61], v[140:143], v[184:187], v[86:89]
	v_mfma_f32_16x16x32_bf16 v[86:89], v[144:147], v[188:191], v[58:61]
	v_mfma_f32_16x16x32_bf16 v[58:61], v[132:135], v[192:195], v[90:93]
	v_mfma_f32_16x16x32_bf16 v[50:53], v[132:135], v[148:151], v[50:53]
	v_mfma_f32_16x16x32_bf16 v[54:57], v[140:143], v[148:151], v[54:57]
	v_mfma_f32_16x16x32_bf16 v[90:93], v[136:139], v[196:199], v[58:61]
	v_mfma_f32_16x16x32_bf16 v[58:61], v[140:143], v[192:195], v[94:97]
	v_mfma_f32_16x16x32_bf16 v[50:53], v[136:139], v[152:155], v[50:53]
	v_mfma_f32_16x16x32_bf16 v[54:57], v[144:147], v[152:155], v[54:57]
	v_mfma_f32_16x16x32_bf16 v[94:97], v[144:147], v[196:199], v[58:61]
	s_barrier
	s_mov_b32 m0, s75
	v_lshl_add_u64 v[224:225], s[8:9], 0, v[66:67]
	s_nop 0
	ds_read_b128 v[58:61], v107
	ds_read_b128 v[204:207], v107 offset:1024
	ds_read_b128 v[208:211], v107 offset:2048
	ds_read_b128 v[212:215], v107 offset:3072
	global_load_lds_dwordx4 v[224:225], off
	v_lshl_add_u64 v[226:227], s[8:9], 0, v[70:71]
	s_mov_b32 m0, s73
	s_nop 0
	global_load_lds_dwordx4 v[226:227], off
	s_barrier
	s_waitcnt lgkmcnt(0)
	v_mfma_f32_16x16x32_bf16 v[30:33], v[58:61], v[184:187], v[30:33]
	v_mfma_f32_16x16x32_bf16 v[0:3], v[58:61], v[148:151], v[0:3]
	v_mfma_f32_16x16x32_bf16 v[22:25], v[208:211], v[148:151], v[22:25]
	v_mfma_f32_16x16x32_bf16 v[148:151], v[204:207], v[188:191], v[30:33]
	v_mfma_f32_16x16x32_bf16 v[30:33], v[208:211], v[184:187], v[34:37]
	v_mfma_f32_16x16x32_bf16 v[0:3], v[204:207], v[152:155], v[0:3]
	v_mfma_f32_16x16x32_bf16 v[22:25], v[212:215], v[152:155], v[22:25]
	v_mfma_f32_16x16x32_bf16 v[152:155], v[212:215], v[188:191], v[30:33]
	v_mfma_f32_16x16x32_bf16 v[30:33], v[58:61], v[192:195], v[38:41]
	v_mfma_f32_16x16x32_bf16 v[120:123], v[58:61], v[176:179], v[120:123]
	v_mfma_f32_16x16x32_bf16 v[26:29], v[208:211], v[176:179], v[26:29]
	v_mfma_f32_16x16x32_bf16 v[176:179], v[204:207], v[196:199], v[30:33]
	v_mfma_f32_16x16x32_bf16 v[30:33], v[208:211], v[192:195], v[42:45]
	v_mfma_f32_16x16x32_bf16 v[120:123], v[204:207], v[180:183], v[120:123]
	v_mfma_f32_16x16x32_bf16 v[26:29], v[212:215], v[180:183], v[26:29]
	v_mfma_f32_16x16x32_bf16 v[180:183], v[212:215], v[196:199], v[30:33]
	s_mov_b32 m0, s38
	v_lshl_add_u64 v[240:241], s[0:1], 0, v[64:65]
	s_barrier
	s_nop 0
	ds_read_b128 v[30:33], v105 offset:16384
	ds_read_b128 v[34:37], v105 offset:17408
	ds_read_b128 v[38:41], v105 offset:18432
	ds_read_b128 v[42:45], v105 offset:19456
	ds_read_b128 v[184:187], v105 offset:20480
	ds_read_b128 v[188:191], v105 offset:21504
	ds_read_b128 v[192:195], v105 offset:22528
	ds_read_b128 v[196:199], v105 offset:23552
	global_load_lds_dwordx4 v[240:241], off
	v_lshl_add_u64 v[242:243], s[0:1], 0, v[68:69]
	s_mov_b32 m0, s39
	s_nop 0
	global_load_lds_dwordx4 v[242:243], off
	s_barrier
	s_waitcnt lgkmcnt(0)
	v_mfma_f32_16x16x32_bf16 v[10:13], v[132:135], v[192:195], v[10:13]
	v_mfma_f32_16x16x32_bf16 v[4:7], v[132:135], v[30:33], v[4:7]
	v_mfma_f32_16x16x32_bf16 v[156:159], v[140:143], v[30:33], v[156:159]
	v_mfma_f32_16x16x32_bf16 v[160:163], v[132:135], v[38:41], v[160:163]
	v_mfma_f32_16x16x32_bf16 v[164:167], v[140:143], v[38:41], v[164:167]
	v_mfma_f32_16x16x32_bf16 v[168:171], v[132:135], v[184:187], v[168:171]
	v_mfma_f32_16x16x32_bf16 v[172:175], v[140:143], v[184:187], v[172:175]
	v_mfma_f32_16x16x32_bf16 v[132:135], v[136:139], v[196:199], v[10:13]
	v_mfma_f32_16x16x32_bf16 v[10:13], v[140:143], v[192:195], v[14:17]
	v_mfma_f32_16x16x32_bf16 v[4:7], v[136:139], v[34:37], v[4:7]
	v_mfma_f32_16x16x32_bf16 v[156:159], v[144:147], v[34:37], v[156:159]
	v_mfma_f32_16x16x32_bf16 v[160:163], v[136:139], v[42:45], v[160:163]
	v_mfma_f32_16x16x32_bf16 v[164:167], v[144:147], v[42:45], v[164:167]
	v_mfma_f32_16x16x32_bf16 v[168:171], v[136:139], v[188:191], v[168:171]
	v_mfma_f32_16x16x32_bf16 v[172:175], v[144:147], v[188:191], v[172:175]
	v_mfma_f32_16x16x32_bf16 v[136:139], v[144:147], v[196:199], v[10:13]
	s_barrier
	s_add_u32 s24, s8, 0x18000
	s_addc_u32 s25, s9, 0
	s_mov_b32 m0, s76
	v_lshl_add_u64 v[10:11], s[24:25], 0, v[66:67]
	global_load_lds_dwordx4 v[10:11], off
	v_lshl_add_u64 v[10:11], s[24:25], 0, v[70:71]
	s_mov_b32 m0, s74
	s_nop 0
	global_load_lds_dwordx4 v[10:11], off
	s_waitcnt vmcnt(6)
	s_barrier
	v_mfma_f32_16x16x32_bf16 v[10:13], v[58:61], v[30:33], v[18:21]
	v_mfma_f32_16x16x32_bf16 v[140:143], v[204:207], v[34:37], v[10:13]
	v_mfma_f32_16x16x32_bf16 v[10:13], v[208:211], v[30:33], v[46:49]
	v_mfma_f32_16x16x32_bf16 v[144:147], v[212:215], v[34:37], v[10:13]
	v_mfma_f32_16x16x32_bf16 v[10:13], v[58:61], v[38:41], v[112:115]
	v_mfma_f32_16x16x32_bf16 v[112:115], v[204:207], v[42:45], v[10:13]
	v_mfma_f32_16x16x32_bf16 v[10:13], v[208:211], v[38:41], v[116:119]
	v_mfma_f32_16x16x32_bf16 v[116:119], v[212:215], v[42:45], v[10:13]
	v_mfma_f32_16x16x32_bf16 v[10:13], v[58:61], v[184:187], v[124:127]
	v_mfma_f32_16x16x32_bf16 v[124:127], v[204:207], v[188:191], v[10:13]
	v_mfma_f32_16x16x32_bf16 v[10:13], v[208:211], v[184:187], v[128:131]
	v_mfma_f32_16x16x32_bf16 v[128:131], v[212:215], v[188:191], v[10:13]
	v_mfma_f32_16x16x32_bf16 v[10:13], v[58:61], v[192:195], v[98:101]
	v_mfma_f32_16x16x32_bf16 v[98:101], v[204:207], v[196:199], v[10:13]
	v_mfma_f32_16x16x32_bf16 v[10:13], v[208:211], v[192:195], v[108:111]
	v_mfma_f32_16x16x32_bf16 v[108:111], v[212:215], v[196:199], v[10:13]
	s_barrier
; #define PG8_STAGE(bufoff, gbase, voff) do { _Pragma("unroll") for (int _i = 0; _i < 2; ++_i) \
;         __builtin_amdgcn_global_load_lds((const unsigned*)((const char*)(gbase) + (voff)[_i]), (PG8_LAS unsigned*)(lds + (bufoff) + ldsw + _i * 8192), 16, 0, 0); } while (0)
; #define PG8_LDA(dst, b, h) do { _Pragma("unroll") for (int m = 0; m < 4; ++m) _Pragma("unroll") for (int k = 0; k < 2; ++k) dst[m][k] = *(const PG8_LAS bf16x8*)(lds + PG8_SA(b, h) + aoff + m * 2048 + k * 1024); } while (0)
; #define PG8_LDB(dst, b, h) do { _Pragma("unroll") for (int n = 0; n < 2; ++n) _Pragma("unroll") for (int k = 0; k < 2; ++k) dst[n][k] = *(const PG8_LAS bf16x8*)(lds + PG8_SB(b, h) + boff + n * 2048 + k * 1024); } while (0)
; #define PG8_MMA(ai, bj, At, Bt) do { __builtin_amdgcn_s_setprio(1); _Pragma("unroll") for (int m = 0; m < 4; ++m) _Pragma("unroll") for (int n = 0; n < 2; ++n) _Pragma("unroll") for (int k = 0; k < 2; ++k) \
;         acc[ai][bj][m][n] = __builtin_amdgcn_mfma_f32_16x16x32_bf16(Bt[n][k], At[m][k], acc[ai][bj][m][n], 0, 0, 0); __builtin_amdgcn_s_setprio(0); } while (0)
; #define PG8_WAIT_V(n) asm volatile("s_waitcnt vmcnt(" #n ")" ::: "memory")
; #define PG8_WAIT_L(n) asm volatile("s_waitcnt lgkmcnt(" #n ")" ::: "memory")
; #define PG8_BAR __builtin_amdgcn_s_barrier()
; #define PG8_SCHED __builtin_amdgcn_sched_barrier(0)
; template <class Epi, class Sched>
; __device__ __forceinline__ void gemm_phase(PG8_LAS unsigned char* lds, const Gemm g, const Sched& S, const Epi& E) {
;     ...
;             PG8_LDB(B0, 1, 0); PG8_SCHED; PG8_LDA(At, 1, 0); PG8_STAGE(PG8_SA(0, 1), a2 + hstep, voffA);
;             PG8_WAIT_L(8); PG8_BAR; PG8_WAIT_L(0); PG8_MMA(0, 0, At, B0); PG8_BAR; PG8_SCHED;
;             PG8_LDB(B1, 1, 1); PG8_STAGE(PG8_SB(1, 0), b3, voffB);
;             PG8_BAR; PG8_WAIT_L(0); PG8_MMA(0, 1, At, B1); PG8_BAR;
;             PG8_LDA(At, 1, 1); PG8_STAGE(PG8_SA(1, 0), a3, voffA);
;             PG8_BAR; PG8_WAIT_L(0); PG8_MMA(1, 0, At, B0); PG8_BAR; PG8_SCHED;
;             PG8_STAGE(PG8_SB(1, 1), b3 + hstep, voffB);
;             PG8_WAIT_V(6); PG8_BAR; PG8_MMA(1, 1, At, B1); PG8_BAR;
	ds_read_b128 v[184:187], v8
	ds_read_b128 v[188:191], v8 offset:1024
	ds_read_b128 v[192:195], v8 offset:2048
	ds_read_b128 v[196:199], v8 offset:3072
	s_add_u32 s24, s0, 0x18000
	s_addc_u32 s25, s1, 0
	s_mov_b32 m0, s40
	v_lshl_add_u64 v[30:31], s[24:25], 0, v[64:65]
	ds_read_b128 v[10:13], v105 offset:32768
	ds_read_b128 v[14:17], v105 offset:33792
	ds_read_b128 v[18:21], v105 offset:34816
	ds_read_b128 v[204:207], v105 offset:35840
	ds_read_b128 v[208:211], v105 offset:36864
	ds_read_b128 v[212:215], v105 offset:37888
	ds_read_b128 v[216:219], v105 offset:38912
	ds_read_b128 v[220:223], v105 offset:39936
	global_load_lds_dwordx4 v[30:31], off
	v_lshl_add_u64 v[30:31], s[24:25], 0, v[68:69]
	s_mov_b32 m0, s41
	s_nop 0
	global_load_lds_dwordx4 v[30:31], off
	s_waitcnt lgkmcnt(8)
	s_barrier
	s_waitcnt lgkmcnt(0)
	v_mfma_f32_16x16x32_bf16 v[30:33], v[184:187], v[10:13], v[50:53]
	v_mfma_f32_16x16x32_bf16 v[60:63], v[188:191], v[14:17], v[30:33]
	v_mfma_f32_16x16x32_bf16 v[30:33], v[192:195], v[10:13], v[54:57]
	v_mfma_f32_16x16x32_bf16 v[56:59], v[196:199], v[14:17], v[30:33]
	v_mfma_f32_16x16x32_bf16 v[30:33], v[184:187], v[18:21], v[200:203]
	v_mfma_f32_16x16x32_bf16 v[48:51], v[188:191], v[204:207], v[30:33]
	v_mfma_f32_16x16x32_bf16 v[30:33], v[192:195], v[18:21], v[78:81]
	v_mfma_f32_16x16x32_bf16 v[52:55], v[196:199], v[204:207], v[30:33]
	v_mfma_f32_16x16x32_bf16 v[30:33], v[184:187], v[208:211], v[82:85]
	v_mfma_f32_16x16x32_bf16 v[40:43], v[188:191], v[212:215], v[30:33]
	v_mfma_f32_16x16x32_bf16 v[30:33], v[192:195], v[208:211], v[86:89]
	v_mfma_f32_16x16x32_bf16 v[44:47], v[196:199], v[212:215], v[30:33]
	v_mfma_f32_16x16x32_bf16 v[30:33], v[184:187], v[216:219], v[90:93]
	v_mfma_f32_16x16x32_bf16 v[36:39], v[192:195], v[216:219], v[94:97]
	v_mfma_f32_16x16x32_bf16 v[32:35], v[188:191], v[220:223], v[30:33]
	v_mfma_f32_16x16x32_bf16 v[36:39], v[196:199], v[220:223], v[36:39]
	s_barrier
	s_mov_b32 m0, s80
	ds_read_b128 v[78:81], v9
	ds_read_b128 v[82:85], v9 offset:1024
	ds_read_b128 v[86:89], v9 offset:2048
	ds_read_b128 v[90:93], v9 offset:3072
	v_lshl_add_u64 v[8:9], v[224:225], 0, s[10:11]
	global_load_lds_dwordx4 v[8:9], off
	v_lshl_add_u64 v[8:9], v[226:227], 0, s[10:11]
	s_mov_b32 m0, s77
	s_nop 0
	global_load_lds_dwordx4 v[8:9], off
	s_barrier
	s_waitcnt lgkmcnt(0)
	v_mfma_f32_16x16x32_bf16 v[0:3], v[78:81], v[10:13], v[0:3]
	v_mfma_f32_16x16x32_bf16 v[94:97], v[82:85], v[14:17], v[0:3]
	v_mfma_f32_16x16x32_bf16 v[0:3], v[86:89], v[10:13], v[22:25]
	v_mfma_f32_16x16x32_bf16 v[200:203], v[90:93], v[14:17], v[0:3]
	v_mfma_f32_16x16x32_bf16 v[0:3], v[78:81], v[18:21], v[120:123]
	v_mfma_f32_16x16x32_bf16 v[120:123], v[82:85], v[204:207], v[0:3]
	v_mfma_f32_16x16x32_bf16 v[0:3], v[86:89], v[18:21], v[26:29]
	v_mfma_f32_16x16x32_bf16 v[204:207], v[90:93], v[204:207], v[0:3]
	v_mfma_f32_16x16x32_bf16 v[0:3], v[78:81], v[208:211], v[148:151]
	v_mfma_f32_16x16x32_bf16 v[148:151], v[82:85], v[212:215], v[0:3]
	v_mfma_f32_16x16x32_bf16 v[0:3], v[86:89], v[208:211], v[152:155]
	v_mfma_f32_16x16x32_bf16 v[152:155], v[90:93], v[212:215], v[0:3]
	v_mfma_f32_16x16x32_bf16 v[0:3], v[78:81], v[216:219], v[176:179]
	v_mfma_f32_16x16x32_bf16 v[176:179], v[82:85], v[220:223], v[0:3]
	v_mfma_f32_16x16x32_bf16 v[0:3], v[86:89], v[216:219], v[180:183]
	v_mfma_f32_16x16x32_bf16 v[180:183], v[90:93], v[220:223], v[0:3]
	s_mov_b32 m0, s43
	s_nop 4
	v_lshl_add_u64 v[0:1], v[240:241], 0, s[10:11]
	s_barrier
	ds_read_b128 v[208:211], v105 offset:49152
	ds_read_b128 v[212:215], v105 offset:50176
	ds_read_b128 v[216:219], v105 offset:51200
	ds_read_b128 v[220:223], v105 offset:52224
	ds_read_b128 v[224:227], v105 offset:53248
	ds_read_b128 v[228:231], v105 offset:54272
	ds_read_b128 v[232:235], v105 offset:55296
	ds_read_b128 v[236:239], v105 offset:56320
	global_load_lds_dwordx4 v[0:1], off
	v_lshl_add_u64 v[0:1], v[242:243], 0, s[10:11]
	s_mov_b32 m0, s60
	s_nop 0
	global_load_lds_dwordx4 v[0:1], off
	s_barrier
	s_waitcnt lgkmcnt(0)
	v_mfma_f32_16x16x32_bf16 v[0:3], v[184:187], v[208:211], v[4:7]
	v_mfma_f32_16x16x32_bf16 v[24:27], v[188:191], v[212:215], v[0:3]
	v_mfma_f32_16x16x32_bf16 v[0:3], v[192:195], v[208:211], v[156:159]
	v_mfma_f32_16x16x32_bf16 v[28:31], v[196:199], v[212:215], v[0:3]
	v_mfma_f32_16x16x32_bf16 v[0:3], v[184:187], v[216:219], v[160:163]
	v_mfma_f32_16x16x32_bf16 v[16:19], v[188:191], v[220:223], v[0:3]
	v_mfma_f32_16x16x32_bf16 v[0:3], v[192:195], v[216:219], v[164:167]
	v_mfma_f32_16x16x32_bf16 v[20:23], v[196:199], v[220:223], v[0:3]
	v_mfma_f32_16x16x32_bf16 v[0:3], v[184:187], v[224:227], v[168:171]
	v_mfma_f32_16x16x32_bf16 v[8:11], v[188:191], v[228:231], v[0:3]
	v_mfma_f32_16x16x32_bf16 v[0:3], v[192:195], v[224:227], v[172:175]
	v_mfma_f32_16x16x32_bf16 v[12:15], v[196:199], v[228:231], v[0:3]
	v_mfma_f32_16x16x32_bf16 v[0:3], v[184:187], v[232:235], v[132:135]
	v_mfma_f32_16x16x32_bf16 v[4:7], v[192:195], v[232:235], v[136:139]
	v_mfma_f32_16x16x32_bf16 v[0:3], v[188:191], v[236:239], v[0:3]
	v_mfma_f32_16x16x32_bf16 v[4:7], v[196:199], v[236:239], v[4:7]
	s_barrier
	s_add_u32 s24, s8, 0x18080
	s_addc_u32 s25, s9, 0
	s_mov_b32 m0, s81
	v_lshl_add_u64 v[132:133], s[24:25], 0, v[66:67]
	global_load_lds_dwordx4 v[132:133], off
	v_lshl_add_u64 v[132:133], s[24:25], 0, v[70:71]
	s_mov_b32 m0, s78
	s_nop 0
	global_load_lds_dwordx4 v[132:133], off
	s_waitcnt vmcnt(6)
	s_barrier
; #define PG8_MMA(ai, bj, At, Bt) do { __builtin_amdgcn_s_setprio(1); _Pragma("unroll") for (int m = 0; m < 4; ++m) _Pragma("unroll") for (int n = 0; n < 2; ++n) _Pragma("unroll") for (int k = 0; k < 2; ++k) \
;         acc[ai][bj][m][n] = __builtin_amdgcn_mfma_f32_16x16x32_bf16(Bt[n][k], At[m][k], acc[ai][bj][m][n], 0, 0, 0); __builtin_amdgcn_s_setprio(0); } while (0)
; #define PG8_WAIT_V(n) asm volatile("s_waitcnt vmcnt(" #n ")" ::: "memory")
; #define PG8_BAR __builtin_amdgcn_s_barrier()
; template <class Epi, class Sched>
; __device__ __forceinline__ void gemm_phase(PG8_LAS unsigned char* lds, const Gemm g, const Sched& S, const Epi& E) {
;     ...
;             PG8_WAIT_V(6); PG8_BAR; PG8_MMA(1, 1, At, B1); PG8_BAR;
;     __device__ __forceinline__ void operator()(const f32x4 (&acc)[2][2][4][2], const Unit& u, int wr, int wc, int fr, int fq) const {
;     ...
;         for (int ai = 0; ai < 2; ++ai)
; #pragma unroll
;             for (int m = 0; m < 4; ++m) { const f32x4 g0 = acc[ai][1][m][0], g1 = acc[ai][1][m][1]; u32x4 w; w.x = pk2(g0[0], g0[1]); w.y = pk2(g0[2], g0[3]); w.z = pk2(g1[0], g1[1]); w.w = pk2(g1[2], g1[3]);
;                 *(u32x4*)(G + (size_t)(row0 + ai * HALF + m * 16) * 512 + cb) = w; }
;         asm volatile("" ::: "memory");
; #pragma unroll
;         for (int ai = 0; ai < 2; ++ai)
; #pragma unroll
;             for (int m = 0; m < 4; ++m) { const int row = row0 + ai * HALF + m * 16; const size_t off = (size_t)row * 512 + cb; bf16_t* kp = RKV + (size_t)row * 1536 + 512 + cb;
;                 float ks[8], av[8], t[8]; unpack8(*(const u32x4*)kp, ks);
;                 { const f32x4 c0 = *(const f32x4*)(a0 + cb), c1 = *(const f32x4*)(a0 + cb + 4); const f32x4 x0 = acc[ai][0][m][0], x1 = acc[ai][0][m][1];
; #pragma unroll
;                   for (int j = 0; j < 4; ++j) { av[j] = sigmoidf_(c0[j] + x0[j]); av[4 + j] = sigmoidf_(c1[j] + x1[j]); } }
;                 { const f32x4 c0 = *(const f32x4*)(k_a + cb), c1 = *(const f32x4*)(k_a + cb + 4);
; #pragma unroll
;                   for (int j = 0; j < 4; ++j) { t[j] = ks[j] * (1.0f + (av[j] - 1.0f) * c0[j]); t[4 + j] = ks[4 + j] * (1.0f + (av[4 + j] - 1.0f) * c1[j]); } }
;                 *(u32x4*)kp = pack8(t);
;                 { const f32x4 c0 = *(const f32x4*)(k_k + cb), c1 = *(const f32x4*)(k_k + cb + 4); const float ri = rinv[row * 8 + (cb >> 6)];
	v_mfma_f32_16x16x32_bf16 v[132:135], v[78:81], v[208:211], v[140:143]
	v_mfma_f32_16x16x32_bf16 v[112:115], v[78:81], v[216:219], v[112:115]
	v_mfma_f32_16x16x32_bf16 v[124:127], v[78:81], v[224:227], v[124:127]
	v_mfma_f32_16x16x32_bf16 v[78:81], v[78:81], v[232:235], v[98:101]
	v_mfma_f32_16x16x32_bf16 v[136:139], v[86:89], v[208:211], v[144:147]
	v_mfma_f32_16x16x32_bf16 v[116:119], v[86:89], v[216:219], v[116:119]
	v_mfma_f32_16x16x32_bf16 v[128:131], v[86:89], v[224:227], v[128:131]
	v_mfma_f32_16x16x32_bf16 v[140:143], v[82:85], v[236:239], v[78:81]
	v_mfma_f32_16x16x32_bf16 v[78:81], v[86:89], v[232:235], v[108:111]
	v_mfma_f32_16x16x32_bf16 v[132:135], v[82:85], v[212:215], v[132:135]
	v_mfma_f32_16x16x32_bf16 v[136:139], v[90:93], v[212:215], v[136:139]
	v_mfma_f32_16x16x32_bf16 v[112:115], v[82:85], v[220:223], v[112:115]
	v_mfma_f32_16x16x32_bf16 v[116:119], v[90:93], v[220:223], v[116:119]
	v_mfma_f32_16x16x32_bf16 v[124:127], v[82:85], v[228:231], v[124:127]
	v_mfma_f32_16x16x32_bf16 v[128:131], v[90:93], v[228:231], v[128:131]
	v_mfma_f32_16x16x32_bf16 v[84:87], v[90:93], v[236:239], v[78:81]
	s_lshl_b32 s24, s71, 7
	v_lshl_add_u32 v100, s70, 8, v102
	s_or_b32 s24, s24, s42
	v_or_b32_e32 v78, s24, v103
	v_ashrrev_i32_e32 v101, 31, v100
	v_ashrrev_i32_e32 v79, 31, v78
	v_lshlrev_b64 v[80:81], 10, v[100:101]
	v_lshl_add_u64 v[80:81], s[52:53], 0, v[80:81]
	v_lshlrev_b64 v[82:83], 1, v[78:79]
	v_or_b32_e32 v98, 16, v100
	v_lshl_add_u64 v[80:81], v[80:81], 0, v[82:83]
	v_ashrrev_i32_e32 v99, 31, v98
	s_barrier
	v_cvt_pk_bf16_f32 v88, v94, v95
	v_cvt_pk_bf16_f32 v89, v96, v97
	v_cvt_pk_bf16_f32 v90, v200, v201
	v_cvt_pk_bf16_f32 v91, v202, v203
	global_store_dwordx4 v[80:81], v[88:91], off
	v_lshlrev_b64 v[80:81], 10, v[98:99]
	v_lshl_add_u64 v[80:81], s[52:53], 0, v[80:81]
	v_or_b32_e32 v96, 32, v100
	v_lshl_add_u64 v[80:81], v[80:81], 0, v[82:83]
	v_ashrrev_i32_e32 v97, 31, v96
	v_cvt_pk_bf16_f32 v88, v120, v121
	v_cvt_pk_bf16_f32 v89, v122, v123
	v_cvt_pk_bf16_f32 v90, v204, v205
	v_cvt_pk_bf16_f32 v91, v206, v207
	global_store_dwordx4 v[80:81], v[88:91], off
	v_lshlrev_b64 v[80:81], 10, v[96:97]
	v_lshl_add_u64 v[80:81], s[52:53], 0, v[80:81]
	v_or_b32_e32 v94, 48, v100
	v_lshl_add_u64 v[80:81], v[80:81], 0, v[82:83]
	v_ashrrev_i32_e32 v95, 31, v94
	v_cvt_pk_bf16_f32 v88, v148, v149
	v_cvt_pk_bf16_f32 v89, v150, v151
	v_cvt_pk_bf16_f32 v90, v152, v153
	v_cvt_pk_bf16_f32 v91, v154, v155
	global_store_dwordx4 v[80:81], v[88:91], off
	v_lshlrev_b64 v[80:81], 10, v[94:95]
	v_lshl_add_u64 v[80:81], s[52:53], 0, v[80:81]
	v_add_u32_e32 v92, 0x80, v100
	v_lshl_add_u64 v[80:81], v[80:81], 0, v[82:83]
	v_ashrrev_i32_e32 v93, 31, v92
	v_cvt_pk_bf16_f32 v88, v176, v177
	v_cvt_pk_bf16_f32 v89, v178, v179
	v_cvt_pk_bf16_f32 v90, v180, v181
	v_cvt_pk_bf16_f32 v91, v182, v183
	global_store_dwordx4 v[80:81], v[88:91], off
	v_lshlrev_b64 v[80:81], 10, v[92:93]
	v_lshl_add_u64 v[80:81], s[52:53], 0, v[80:81]
	v_cvt_pk_bf16_f32 v90, v136, v137
	v_lshl_add_u64 v[80:81], v[80:81], 0, v[82:83]
	v_cvt_pk_bf16_f32 v88, v132, v133
	v_cvt_pk_bf16_f32 v89, v134, v135
	v_cvt_pk_bf16_f32 v91, v138, v139
	global_store_dwordx4 v[80:81], v[88:91], off
	v_cvt_pk_bf16_f32 v108, v112, v113
	v_cvt_pk_bf16_f32 v109, v114, v115
	v_cvt_pk_bf16_f32 v110, v116, v117
	v_cvt_pk_bf16_f32 v111, v118, v119
	s_ashr_i32 s24, s24, 6
	s_nop 0
	v_add_u32_e32 v90, 0x90, v100
	v_ashrrev_i32_e32 v91, 31, v90
	v_lshlrev_b64 v[80:81], 10, v[90:91]
	v_lshl_add_u64 v[80:81], s[52:53], 0, v[80:81]
	v_add_u32_e32 v88, 0xa0, v100
	v_lshl_add_u64 v[80:81], v[80:81], 0, v[82:83]
	v_ashrrev_i32_e32 v89, 31, v88
	global_store_dwordx4 v[80:81], v[108:111], off
	v_lshlrev_b64 v[80:81], 10, v[88:89]
	v_lshl_add_u64 v[80:81], s[52:53], 0, v[80:81]
	v_lshl_add_u64 v[80:81], v[80:81], 0, v[82:83]
	v_cvt_pk_bf16_f32 v108, v124, v125
	v_cvt_pk_bf16_f32 v109, v126, v127
	v_cvt_pk_bf16_f32 v110, v128, v129
	v_cvt_pk_bf16_f32 v111, v130, v131
	global_store_dwordx4 v[80:81], v[108:111], off
	v_add_u32_e32 v80, 0xb0, v100
	v_ashrrev_i32_e32 v81, 31, v80
	v_cvt_pk_bf16_f32 v110, v84, v85
	v_lshlrev_b64 v[84:85], 10, v[80:81]
	v_lshl_add_u64 v[84:85], s[52:53], 0, v[84:85]
	v_lshl_add_u64 v[84:85], v[84:85], 0, v[82:83]
	v_cvt_pk_bf16_f32 v108, v140, v141
	v_cvt_pk_bf16_f32 v109, v142, v143
	v_cvt_pk_bf16_f32 v111, v86, v87
	global_store_dwordx4 v[84:85], v[108:111], off
	v_mad_i64_i32 v[84:85], s[26:27], v100, s68, v[76:77]
	v_lshlrev_b64 v[130:131], 2, v[78:79]
	v_lshl_add_u64 v[128:129], v[84:85], 0, v[82:83]
	v_lshl_add_u64 v[84:85], s[22:23], 0, v[130:131]
	global_load_dwordx4 v[108:111], v[128:129], off offset:1024
	global_load_dwordx4 v[112:115], v[84:85], off
	global_load_dwordx4 v[116:119], v[84:85], off offset:16
	v_lshl_add_u64 v[86:87], s[30:31], 0, v[130:131]
	global_load_dwordx4 v[120:123], v[86:87], off
	global_load_dwordx4 v[124:127], v[86:87], off offset:16
	global_load_dwordx4 v[156:159], v130, s[22:23]
	global_load_dwordx4 v[160:163], v130, s[22:23] offset:16
	global_load_dwordx4 v[164:167], v130, s[30:31]
	global_load_dwordx4 v[168:171], v130, s[30:31] offset:16
	global_load_dwordx4 v[184:187], v130, s[28:29]
	global_load_dwordx4 v[188:191], v130, s[28:29] offset:16
	v_lshl_add_u32 v238, v100, 3, s24
	v_lshlrev_b32_e32 v238, 2, v238
	v_add_u32_e32 v239, 0x1000, v238
	global_load_dword v228, v238, s[4:5]
	global_load_dword v229, v238, s[4:5] offset:512
	global_load_dword v230, v238, s[4:5] offset:1024
	global_load_dword v231, v238, s[4:5] offset:1536
	global_load_dword v232, v239, s[4:5]
	global_load_dword v233, v239, s[4:5] offset:512
	global_load_dword v234, v239, s[4:5] offset:1024
	global_load_dword v235, v239, s[4:5] offset:1536
	s_mov_b32 s98, 0xc000
	s_mov_b32 s99, 0
	v_lshl_add_u64 v[236:237], v[128:129], 0, s[98:99]
	global_load_dwordx4 v[192:195], v[236:237], off offset:1024
	s_mov_b32 s98, 0x18000
	s_mov_b32 s99, 0
	v_lshl_add_u64 v[236:237], v[128:129], 0, s[98:99]
	global_load_dwordx4 v[196:199], v[236:237], off offset:1024
	s_mov_b32 s98, 0x24000
	s_mov_b32 s99, 0
	v_lshl_add_u64 v[236:237], v[128:129], 0, s[98:99]
	global_load_dwordx4 v[208:211], v[236:237], off offset:1024
	s_mov_b32 s98, 0x60000
	s_mov_b32 s99, 0
	v_lshl_add_u64 v[236:237], v[128:129], 0, s[98:99]
	global_load_dwordx4 v[212:215], v[236:237], off offset:1024
	s_mov_b32 s98, 0x6c000
	s_mov_b32 s99, 0
	v_lshl_add_u64 v[236:237], v[128:129], 0, s[98:99]
	global_load_dwordx4 v[216:219], v[236:237], off offset:1024
	s_mov_b32 s98, 0x78000
	s_mov_b32 s99, 0
	v_lshl_add_u64 v[236:237], v[128:129], 0, s[98:99]
	global_load_dwordx4 v[220:223], v[236:237], off offset:1024
	s_mov_b32 s98, 0x84000
	s_mov_b32 s99, 0
	v_lshl_add_u64 v[236:237], v[128:129], 0, s[98:99]
	global_load_dwordx4 v[224:227], v[236:237], off offset:1024
	s_add_i32 s65, s65, s96
	s_andn2_b64 vcc, exec, s[6:7]
	s_mov_b32 s71, s3
	s_mov_b32 s70, s69
	s_waitcnt vmcnt(0)
; __device__ __forceinline__ void unpack8(const u32x4 w, float (&f)[8]) { f[0] = bflo(w.x); f[1] = bfhi(w.x); f[2] = bflo(w.y); f[3] = bfhi(w.y); f[4] = bflo(w.z); f[5] = bfhi(w.z); f[6] = bflo(w.w); f[7] = bfhi(w.w); }
; __device__ __forceinline__ u32x4 pack8(const float (&f)[8]) { u32x4 o; o.x = pk2(f[0], f[1]); o.y = pk2(f[2], f[3]); o.z = pk2(f[4], f[5]); o.w = pk2(f[6], f[7]); return o; }
; __device__ __forceinline__ float sigmoidf_(float x) { return __builtin_amdgcn_rcpf(1.0f + __expf(-x)); }
;     __device__ __forceinline__ void operator()(const f32x4 (&acc)[2][2][4][2], const Unit& u, int wr, int wc, int fr, int fq) const {
;     ...
;             for (int m = 0; m < 4; ++m) { const int row = row0 + ai * HALF + m * 16; const size_t off = (size_t)row * 512 + cb; bf16_t* kp = RKV + (size_t)row * 1536 + 512 + cb;
;                 float ks[8], av[8], t[8]; unpack8(*(const u32x4*)kp, ks);
;                 { const f32x4 c0 = *(const f32x4*)(a0 + cb), c1 = *(const f32x4*)(a0 + cb + 4); const f32x4 x0 = acc[ai][0][m][0], x1 = acc[ai][0][m][1];
; #pragma unroll
;                   for (int j = 0; j < 4; ++j) { av[j] = sigmoidf_(c0[j] + x0[j]); av[4 + j] = sigmoidf_(c1[j] + x1[j]); } }
;                 { const f32x4 c0 = *(const f32x4*)(k_a + cb), c1 = *(const f32x4*)(k_a + cb + 4);
; #pragma unroll
;                   for (int j = 0; j < 4; ++j) { t[j] = ks[j] * (1.0f + (av[j] - 1.0f) * c0[j]); t[4 + j] = ks[4 + j] * (1.0f + (av[4 + j] - 1.0f) * c1[j]); } }
;                 *(u32x4*)kp = pack8(t);
;                 { const f32x4 c0 = *(const f32x4*)(k_k + cb), c1 = *(const f32x4*)(k_k + cb + 4); const float ri = rinv[row * 8 + (cb >> 6)];
; #pragma unroll
;                   for (int j = 0; j < 4; ++j) { t[j] = ks[j] * c0[j] * ri; t[4 + j] = ks[4 + j] * c1[j] * ri; } }
;                 *(u32x4*)(KK + off) = pack8(t);
; #pragma unroll
;                 for (int e = 0; e < 8; ++e) t[e] = -t[e] * av[e];
;                 *(u32x4*)(NB + off) = pack8(t);
;                 asm volatile("" ::: "memory"); }
	v_add_f32_e32 v60, v60, v112
	v_mul_f32_e32 v60, 0xbfb8aa3b, v60
	v_exp_f32_e32 v60, v60
	v_add_f32_e32 v56, v56, v116
	v_mul_f32_e32 v56, 0xbfb8aa3b, v56
	v_exp_f32_e32 v56, v56
	v_add_f32_e32 v60, 1.0, v60
	v_rcp_f32_e32 v116, v60
	v_add_f32_e32 v60, v61, v113
	v_mul_f32_e32 v60, 0xbfb8aa3b, v60
	v_add_f32_e32 v57, v57, v117
	v_exp_f32_e32 v60, v60
	v_mul_f32_e32 v57, 0xbfb8aa3b, v57
	v_exp_f32_e32 v57, v57
	v_add_f32_e32 v56, 1.0, v56
	v_rcp_f32_e32 v113, v56
	v_add_f32_e32 v56, 1.0, v60
	v_rcp_f32_e32 v117, v56
	v_add_f32_e32 v56, 1.0, v57
	v_add_f32_e32 v57, v62, v114
	v_mul_f32_e32 v57, 0xbfb8aa3b, v57
	v_add_f32_e32 v58, v58, v118
	v_exp_f32_e32 v57, v57
	v_mul_f32_e32 v58, 0xbfb8aa3b, v58
	v_exp_f32_e32 v58, v58
	v_rcp_f32_e32 v114, v56
	v_add_f32_e32 v56, 1.0, v57
	v_add_f32_e32 v57, v63, v115
	v_rcp_f32_e32 v118, v56
	v_add_f32_e32 v56, 1.0, v58
	v_mul_f32_e32 v57, 0xbfb8aa3b, v57
	v_add_f32_e32 v58, v59, v119
	v_exp_f32_e32 v57, v57
	v_mul_f32_e32 v58, 0xbfb8aa3b, v58
	v_exp_f32_e32 v58, v58
	v_rcp_f32_e32 v115, v56
	v_add_f32_e32 v56, 1.0, v57
	v_rcp_f32_e32 v119, v56
	v_add_f32_e32 v56, 1.0, v58
	v_rcp_f32_e32 v139, v56
	v_add_f32_e32 v57, -1.0, v113
	v_lshlrev_b32_e32 v136, 16, v110
	v_fma_f32 v57, v124, v57, 1.0
	v_add_f32_e32 v56, -1.0, v116
	v_mul_f32_e32 v58, v57, v136
	v_add_f32_e32 v57, -1.0, v117
	v_add_f32_e32 v62, -1.0, v119
	v_lshlrev_b32_e32 v132, 16, v108
	v_and_b32_e32 v133, 0xffff0000, v108
	v_and_b32_e32 v135, 0xffff0000, v109
	v_fma_f32 v56, v120, v56, 1.0
	v_fma_f32 v57, v121, v57, 1.0
	v_add_f32_e32 v59, -1.0, v114
	v_add_f32_e32 v60, -1.0, v118
	v_fma_f32 v62, v123, v62, 1.0
	v_add_f32_e32 v63, -1.0, v139
	v_lshlrev_b32_e32 v134, 16, v109
	v_and_b32_e32 v137, 0xffff0000, v110
	v_and_b32_e32 v112, 0xffff0000, v111
	v_mul_f32_e32 v56, v56, v132
	v_mul_f32_e32 v57, v57, v133
	v_fma_f32 v59, v125, v59, 1.0
	v_fma_f32 v60, v122, v60, 1.0
	v_add_f32_e32 v61, -1.0, v115
	v_mul_f32_e32 v62, v62, v135
	v_fma_f32 v63, v127, v63, 1.0
	v_lshlrev_b32_e32 v138, 16, v111
	v_mul_f32_e32 v59, v59, v137
	v_mul_f32_e32 v60, v60, v134
	v_fma_f32 v61, v126, v61, 1.0
	v_mul_f32_e32 v63, v63, v112
	v_cvt_pk_bf16_f32 v56, v56, v57
	v_cvt_pk_bf16_f32 v57, v60, v62
	v_lshl_add_u32 v62, v100, 3, s24
	v_mul_f32_e32 v61, v61, v138
	v_cvt_pk_bf16_f32 v58, v58, v59
	v_cvt_pk_bf16_f32 v59, v61, v63
	global_store_dwordx4 v[128:129], v[56:59], off offset:1024
	v_ashrrev_i32_e32 v63, 31, v62
	v_lshl_add_u64 v[62:63], v[62:63], 2, s[4:5]
	v_lshl_add_u64 v[56:57], s[28:29], 0, v[130:131]
	s_nop 1
	v_mov_b32_e32 v58, v184
	v_mov_b32_e32 v59, v185
	v_mov_b32_e32 v60, v186
	v_mov_b32_e32 v61, v187
	s_nop 1
	v_mov_b32_e32 v120, v228
	s_nop 1
	v_mov_b32_e32 v108, v188
	v_mov_b32_e32 v109, v189
	v_mov_b32_e32 v110, v190
	v_mov_b32_e32 v111, v191
	v_lshlrev_b64 v[62:63], 9, v[100:101]
	v_lshl_add_u64 v[62:63], v[62:63], 0, v[78:79]
	v_lshlrev_b64 v[62:63], 1, v[62:63]
	v_lshl_add_u64 v[100:101], s[50:51], 0, v[62:63]
	v_lshl_add_u64 v[62:63], s[62:63], 0, v[62:63]
	v_mul_f32_e32 v58, v58, v132
	v_mul_f32_e32 v121, v58, v120
	v_mul_f32_e32 v58, v108, v136
	v_mul_f32_e32 v108, v120, v58
	v_mul_f32_e32 v58, v59, v133
	v_mul_f32_e32 v122, v58, v120
	v_mul_f32_e32 v58, v109, v137
	v_mul_f32_e32 v109, v120, v58
	v_mul_f32_e32 v58, v60, v134
	v_mul_f32_e32 v123, v58, v120
	v_mul_f32_e32 v58, v110, v138
	v_mul_f32_e32 v110, v120, v58
	v_mul_f32_e32 v58, v61, v135
	v_mul_f32_e32 v124, v58, v120
	v_mul_f32_e32 v58, v111, v112
	v_mul_f32_e32 v111, v120, v58
	v_cvt_pk_bf16_f32 v58, v121, v122
	v_cvt_pk_bf16_f32 v59, v123, v124
	v_cvt_pk_bf16_f32 v60, v108, v109
	v_cvt_pk_bf16_f32 v61, v110, v111
	global_store_dwordx4 v[100:101], v[58:61], off
	v_mul_f32_e64 v100, v113, -v108
	v_mul_f32_e64 v101, v114, -v109
	v_mul_f32_e64 v58, v116, -v121
	v_mul_f32_e64 v59, v117, -v122
	v_mul_f32_e64 v60, v118, -v123
	v_mul_f32_e64 v61, v119, -v124
	v_cvt_pk_bf16_f32 v58, v58, v59
	v_cvt_pk_bf16_f32 v59, v60, v61
	v_mul_f32_e64 v108, v115, -v110
	v_mul_f32_e64 v109, v139, -v111
	v_cvt_pk_bf16_f32 v60, v100, v101
	v_cvt_pk_bf16_f32 v61, v108, v109
	global_store_dwordx4 v[62:63], v[58:61], off
	s_nop 1
	v_mad_i64_i32 v[58:59], s[26:27], v98, s68, v[76:77]
	v_lshl_add_u64 v[62:63], v[58:59], 0, v[82:83]
	s_nop 1
	v_mov_b32_e32 v58, v192
	v_mov_b32_e32 v59, v193
	v_mov_b32_e32 v60, v194
	v_mov_b32_e32 v61, v195
	s_nop 1
	v_mov_b32_e32 v108, v156
	v_mov_b32_e32 v109, v157
	v_mov_b32_e32 v110, v158
	v_mov_b32_e32 v111, v159
	s_nop 1
	v_mov_b32_e32 v112, v160
	v_mov_b32_e32 v113, v161
	v_mov_b32_e32 v114, v162
	v_mov_b32_e32 v115, v163
	s_nop 1
	v_mov_b32_e32 v116, v164
	v_mov_b32_e32 v117, v165
	v_mov_b32_e32 v118, v166
	v_mov_b32_e32 v119, v167
	s_nop 1
	v_mov_b32_e32 v120, v168
	v_mov_b32_e32 v121, v169
	v_mov_b32_e32 v122, v170
	v_mov_b32_e32 v123, v171
	v_lshlrev_b32_e32 v126, 16, v60
	v_add_f32_e32 v48, v48, v108
	v_add_f32_e32 v52, v52, v112
	v_mul_f32_e32 v52, 0xbfb8aa3b, v52
	v_add_f32_e32 v49, v49, v109
	v_add_f32_e32 v53, v53, v113
	v_exp_f32_e32 v52, v52
	v_add_f32_e32 v50, v50, v110
	v_add_f32_e32 v54, v54, v114
	v_add_f32_e32 v51, v51, v111
	v_add_f32_e32 v55, v55, v115
	v_mul_f32_e32 v48, 0xbfb8aa3b, v48
	v_mul_f32_e32 v49, 0xbfb8aa3b, v49
	v_mul_f32_e32 v53, 0xbfb8aa3b, v53
	v_mul_f32_e32 v50, 0xbfb8aa3b, v50
	v_mul_f32_e32 v54, 0xbfb8aa3b, v54
	v_mul_f32_e32 v51, 0xbfb8aa3b, v51
	v_mul_f32_e32 v55, 0xbfb8aa3b, v55
	v_exp_f32_e32 v48, v48
	v_exp_f32_e32 v49, v49
	v_exp_f32_e32 v53, v53
	v_exp_f32_e32 v50, v50
	v_exp_f32_e32 v54, v54
	v_exp_f32_e32 v51, v51
	v_exp_f32_e32 v55, v55
	v_add_f32_e32 v52, 1.0, v52
	v_rcp_f32_e32 v109, v52
	v_add_f32_e32 v48, 1.0, v48
; __device__ __forceinline__ void unpack8(const u32x4 w, float (&f)[8]) { f[0] = bflo(w.x); f[1] = bfhi(w.x); f[2] = bflo(w.y); f[3] = bfhi(w.y); f[4] = bflo(w.z); f[5] = bfhi(w.z); f[6] = bflo(w.w); f[7] = bfhi(w.w); }
; __device__ __forceinline__ u32x4 pack8(const float (&f)[8]) { u32x4 o; o.x = pk2(f[0], f[1]); o.y = pk2(f[2], f[3]); o.z = pk2(f[4], f[5]); o.w = pk2(f[6], f[7]); return o; }
; __device__ __forceinline__ float sigmoidf_(float x) { return __builtin_amdgcn_rcpf(1.0f + __expf(-x)); }
;     __device__ __forceinline__ void operator()(const f32x4 (&acc)[2][2][4][2], const Unit& u, int wr, int wc, int fr, int fq) const {
;     ...
;             for (int m = 0; m < 4; ++m) { const int row = row0 + ai * HALF + m * 16; const size_t off = (size_t)row * 512 + cb; bf16_t* kp = RKV + (size_t)row * 1536 + 512 + cb;
;                 float ks[8], av[8], t[8]; unpack8(*(const u32x4*)kp, ks);
;                 { const f32x4 c0 = *(const f32x4*)(a0 + cb), c1 = *(const f32x4*)(a0 + cb + 4); const f32x4 x0 = acc[ai][0][m][0], x1 = acc[ai][0][m][1];
; #pragma unroll
;                   for (int j = 0; j < 4; ++j) { av[j] = sigmoidf_(c0[j] + x0[j]); av[4 + j] = sigmoidf_(c1[j] + x1[j]); } }
;                 { const f32x4 c0 = *(const f32x4*)(k_a + cb), c1 = *(const f32x4*)(k_a + cb + 4);
; #pragma unroll
;                   for (int j = 0; j < 4; ++j) { t[j] = ks[j] * (1.0f + (av[j] - 1.0f) * c0[j]); t[4 + j] = ks[4 + j] * (1.0f + (av[4 + j] - 1.0f) * c1[j]); } }
;                 *(u32x4*)kp = pack8(t);
;                 { const f32x4 c0 = *(const f32x4*)(k_k + cb), c1 = *(const f32x4*)(k_k + cb + 4); const float ri = rinv[row * 8 + (cb >> 6)];
; #pragma unroll
;                   for (int j = 0; j < 4; ++j) { t[j] = ks[j] * c0[j] * ri; t[4 + j] = ks[4 + j] * c1[j] * ri; } }
;                 *(u32x4*)(KK + off) = pack8(t);
; #pragma unroll
;                 for (int e = 0; e < 8; ++e) t[e] = -t[e] * av[e];
;                 *(u32x4*)(NB + off) = pack8(t);
;                 asm volatile("" ::: "memory"); }
	v_add_f32_e32 v49, 1.0, v49
	v_add_f32_e32 v53, 1.0, v53
	v_add_f32_e32 v50, 1.0, v50
	v_add_f32_e32 v54, 1.0, v54
	v_add_f32_e32 v51, 1.0, v51
	v_add_f32_e32 v55, 1.0, v55
	v_rcp_f32_e32 v108, v48
	v_rcp_f32_e32 v110, v49
	v_rcp_f32_e32 v111, v53
	v_rcp_f32_e32 v112, v50
	v_rcp_f32_e32 v113, v54
	v_rcp_f32_e32 v114, v51
	v_rcp_f32_e32 v115, v55
	v_add_f32_e32 v49, -1.0, v109
	v_fma_f32 v49, v120, v49, 1.0
	v_add_f32_e32 v48, -1.0, v108
	v_mul_f32_e32 v50, v49, v126
	v_add_f32_e32 v49, -1.0, v110
	v_add_f32_e32 v51, -1.0, v111
	v_lshlrev_b32_e32 v100, 16, v58
	v_and_b32_e32 v101, 0xffff0000, v58
	v_and_b32_e32 v127, 0xffff0000, v60
	v_fma_f32 v48, v116, v48, 1.0
	v_fma_f32 v49, v117, v49, 1.0
	v_fma_f32 v51, v121, v51, 1.0
	v_add_f32_e32 v52, -1.0, v112
	v_add_f32_e32 v53, -1.0, v113
	v_add_f32_e32 v54, -1.0, v114
	v_add_f32_e32 v55, -1.0, v115
	v_lshlrev_b32_e32 v124, 16, v59
	v_and_b32_e32 v125, 0xffff0000, v59
	v_lshlrev_b32_e32 v128, 16, v61
	v_and_b32_e32 v129, 0xffff0000, v61
	v_mul_f32_e32 v48, v48, v100
	v_mul_f32_e32 v49, v49, v101
	v_mul_f32_e32 v51, v51, v127
	v_fma_f32 v52, v118, v52, 1.0
	v_fma_f32 v53, v122, v53, 1.0
	v_fma_f32 v54, v119, v54, 1.0
	v_fma_f32 v55, v123, v55, 1.0
	v_lshl_add_u32 v58, v98, 3, s24
	v_mul_f32_e32 v52, v52, v124
	v_mul_f32_e32 v53, v53, v128
	v_mul_f32_e32 v54, v54, v125
	v_mul_f32_e32 v55, v55, v129
	v_cvt_pk_bf16_f32 v48, v48, v49
	v_cvt_pk_bf16_f32 v49, v52, v54
	v_cvt_pk_bf16_f32 v50, v50, v51
	v_cvt_pk_bf16_f32 v51, v53, v55
	global_store_dwordx4 v[62:63], v[48:51], off offset:1024
	v_ashrrev_i32_e32 v59, 31, v58
	s_nop 1
	v_mov_b32_e32 v48, v184
	v_mov_b32_e32 v49, v185
	v_mov_b32_e32 v50, v186
	v_mov_b32_e32 v51, v187
	s_nop 1
	v_mov_b32_e32 v52, v188
	v_mov_b32_e32 v53, v189
	v_mov_b32_e32 v54, v190
	v_mov_b32_e32 v55, v191
	v_lshl_add_u64 v[58:59], v[58:59], 2, s[4:5]
	s_nop 1
	v_mov_b32_e32 v116, v229
	v_lshlrev_b64 v[60:61], 9, v[98:99]
	v_lshl_add_u64 v[60:61], v[60:61], 0, v[78:79]
	v_mad_i64_i32 v[58:59], s[26:27], v96, s68, v[76:77]
	v_lshlrev_b64 v[60:61], 1, v[60:61]
	v_lshl_add_u64 v[62:63], v[58:59], 0, v[82:83]
	v_lshl_add_u64 v[58:59], s[50:51], 0, v[60:61]
	v_lshl_add_u64 v[60:61], s[62:63], 0, v[60:61]
	v_mul_f32_e32 v48, v48, v100
	v_mul_f32_e32 v52, v52, v126
	v_mul_f32_e32 v49, v49, v101
	v_mul_f32_e32 v53, v53, v127
	v_mul_f32_e32 v50, v50, v124
	v_mul_f32_e32 v54, v54, v128
	v_mul_f32_e32 v51, v51, v125
	v_mul_f32_e32 v55, v55, v129
	v_mul_f32_e32 v98, v48, v116
	v_mul_f32_e32 v52, v116, v52
	v_mul_f32_e32 v99, v49, v116
	v_mul_f32_e32 v53, v116, v53
	v_mul_f32_e32 v100, v50, v116
	v_mul_f32_e32 v54, v116, v54
	v_mul_f32_e32 v101, v51, v116
	v_mul_f32_e32 v55, v116, v55
	v_cvt_pk_bf16_f32 v48, v98, v99
	v_cvt_pk_bf16_f32 v49, v100, v101
	v_cvt_pk_bf16_f32 v50, v52, v53
	v_cvt_pk_bf16_f32 v51, v54, v55
	v_mul_f32_e64 v98, v108, -v98
	v_mul_f32_e64 v99, v110, -v99
	v_mul_f32_e64 v100, v112, -v100
	v_mul_f32_e64 v101, v114, -v101
	v_mul_f32_e64 v52, v109, -v52
	v_mul_f32_e64 v53, v111, -v53
	v_mul_f32_e64 v54, v113, -v54
	v_mul_f32_e64 v55, v115, -v55
	global_store_dwordx4 v[58:59], v[48:51], off
	s_nop 1
	v_cvt_pk_bf16_f32 v48, v98, v99
	v_cvt_pk_bf16_f32 v49, v100, v101
	v_cvt_pk_bf16_f32 v50, v52, v53
	v_cvt_pk_bf16_f32 v51, v54, v55
	global_store_dwordx4 v[60:61], v[48:51], off
	s_nop 1
	v_mov_b32_e32 v48, v196
	v_mov_b32_e32 v49, v197
	v_mov_b32_e32 v50, v198
	v_mov_b32_e32 v51, v199
	s_nop 1
	v_mov_b32_e32 v52, v156
	v_mov_b32_e32 v53, v157
	v_mov_b32_e32 v54, v158
	v_mov_b32_e32 v55, v159
	s_nop 1
	v_mov_b32_e32 v58, v160
	v_mov_b32_e32 v59, v161
	v_mov_b32_e32 v60, v162
	v_mov_b32_e32 v61, v163
	s_nop 1
	v_mov_b32_e32 v98, v164
	v_mov_b32_e32 v99, v165
	v_mov_b32_e32 v100, v166
	v_mov_b32_e32 v101, v167
	s_nop 1
	v_mov_b32_e32 v108, v168
	v_mov_b32_e32 v109, v169
	v_mov_b32_e32 v110, v170
	v_mov_b32_e32 v111, v171
	v_and_b32_e32 v113, 0xffff0000, v48
	v_add_f32_e32 v41, v41, v53
	v_add_f32_e32 v44, v44, v58
	v_add_f32_e32 v45, v45, v59
	v_add_f32_e32 v40, v40, v52
	v_add_f32_e32 v42, v42, v54
	v_mul_f32_e32 v44, 0xbfb8aa3b, v44
	v_mul_f32_e32 v41, 0xbfb8aa3b, v41
	v_mul_f32_e32 v45, 0xbfb8aa3b, v45
	v_add_f32_e32 v46, v46, v60
	v_add_f32_e32 v43, v43, v55
	v_add_f32_e32 v47, v47, v61
	v_mul_f32_e32 v40, 0xbfb8aa3b, v40
	v_mul_f32_e32 v42, 0xbfb8aa3b, v42
	v_exp_f32_e32 v44, v44
	v_exp_f32_e32 v41, v41
	v_exp_f32_e32 v45, v45
	v_mul_f32_e32 v46, 0xbfb8aa3b, v46
	v_mul_f32_e32 v43, 0xbfb8aa3b, v43
	v_mul_f32_e32 v47, 0xbfb8aa3b, v47
	v_exp_f32_e32 v40, v40
	v_exp_f32_e32 v42, v42
	v_exp_f32_e32 v46, v46
	v_exp_f32_e32 v43, v43
	v_exp_f32_e32 v47, v47
	v_add_f32_e32 v44, 1.0, v44
	v_add_f32_e32 v41, 1.0, v41
	v_add_f32_e32 v45, 1.0, v45
	v_add_f32_e32 v40, 1.0, v40
	v_add_f32_e32 v42, 1.0, v42
	v_rcp_f32_e32 v53, v44
	v_rcp_f32_e32 v54, v41
	v_rcp_f32_e32 v55, v45
	v_add_f32_e32 v46, 1.0, v46
	v_add_f32_e32 v43, 1.0, v43
	v_add_f32_e32 v47, 1.0, v47
	v_rcp_f32_e32 v52, v40
	v_rcp_f32_e32 v58, v42
	v_rcp_f32_e32 v59, v46
	v_rcp_f32_e32 v60, v43
	v_rcp_f32_e32 v61, v47
	v_add_f32_e32 v41, -1.0, v53
	v_add_f32_e32 v42, -1.0, v54
	v_add_f32_e32 v43, -1.0, v55
	v_lshlrev_b32_e32 v116, 16, v50
	v_and_b32_e32 v117, 0xffff0000, v50
	v_add_f32_e32 v40, -1.0, v52
	v_add_f32_e32 v44, -1.0, v58
	v_fma_f32 v41, v108, v41, 1.0
	v_fma_f32 v42, v99, v42, 1.0
	v_fma_f32 v43, v109, v43, 1.0
	v_lshlrev_b32_e32 v112, 16, v48
	v_lshlrev_b32_e32 v114, 16, v49
	v_add_f32_e32 v45, -1.0, v59
	v_add_f32_e32 v46, -1.0, v60
	v_add_f32_e32 v47, -1.0, v61
	v_fma_f32 v40, v98, v40, 1.0
	v_fma_f32 v44, v100, v44, 1.0
	v_mul_f32_e32 v48, v41, v116
	v_mul_f32_e32 v41, v42, v113
	v_mul_f32_e32 v42, v43, v117
; __device__ __forceinline__ void unpack8(const u32x4 w, float (&f)[8]) { f[0] = bflo(w.x); f[1] = bfhi(w.x); f[2] = bflo(w.y); f[3] = bfhi(w.y); f[4] = bflo(w.z); f[5] = bfhi(w.z); f[6] = bflo(w.w); f[7] = bfhi(w.w); }
; __device__ __forceinline__ u32x4 pack8(const float (&f)[8]) { u32x4 o; o.x = pk2(f[0], f[1]); o.y = pk2(f[2], f[3]); o.z = pk2(f[4], f[5]); o.w = pk2(f[6], f[7]); return o; }
; __device__ __forceinline__ float sigmoidf_(float x) { return __builtin_amdgcn_rcpf(1.0f + __expf(-x)); }
;     __device__ __forceinline__ void operator()(const f32x4 (&acc)[2][2][4][2], const Unit& u, int wr, int wc, int fr, int fq) const {
;     ...
;             for (int m = 0; m < 4; ++m) { const int row = row0 + ai * HALF + m * 16; const size_t off = (size_t)row * 512 + cb; bf16_t* kp = RKV + (size_t)row * 1536 + 512 + cb;
;                 float ks[8], av[8], t[8]; unpack8(*(const u32x4*)kp, ks);
;                 { const f32x4 c0 = *(const f32x4*)(a0 + cb), c1 = *(const f32x4*)(a0 + cb + 4); const f32x4 x0 = acc[ai][0][m][0], x1 = acc[ai][0][m][1];
; #pragma unroll
;                   for (int j = 0; j < 4; ++j) { av[j] = sigmoidf_(c0[j] + x0[j]); av[4 + j] = sigmoidf_(c1[j] + x1[j]); } }
;                 { const f32x4 c0 = *(const f32x4*)(k_a + cb), c1 = *(const f32x4*)(k_a + cb + 4);
; #pragma unroll
;                   for (int j = 0; j < 4; ++j) { t[j] = ks[j] * (1.0f + (av[j] - 1.0f) * c0[j]); t[4 + j] = ks[4 + j] * (1.0f + (av[4 + j] - 1.0f) * c1[j]); } }
;                 *(u32x4*)kp = pack8(t);
;                 { const f32x4 c0 = *(const f32x4*)(k_k + cb), c1 = *(const f32x4*)(k_k + cb + 4); const float ri = rinv[row * 8 + (cb >> 6)];
; #pragma unroll
;                   for (int j = 0; j < 4; ++j) { t[j] = ks[j] * c0[j] * ri; t[4 + j] = ks[4 + j] * c1[j] * ri; } }
;                 *(u32x4*)(KK + off) = pack8(t);
; #pragma unroll
;                 for (int e = 0; e < 8; ++e) t[e] = -t[e] * av[e];
;                 *(u32x4*)(NB + off) = pack8(t);
;                 asm volatile("" ::: "memory"); }
	v_and_b32_e32 v115, 0xffff0000, v49
	v_lshlrev_b32_e32 v118, 16, v51
	v_and_b32_e32 v119, 0xffff0000, v51
	v_fma_f32 v45, v110, v45, 1.0
	v_fma_f32 v46, v101, v46, 1.0
	v_fma_f32 v47, v111, v47, 1.0
	v_mul_f32_e32 v40, v40, v112
	v_mul_f32_e32 v43, v44, v114
	v_cvt_pk_bf16_f32 v42, v48, v42
	v_lshl_add_u32 v48, v96, 3, s24
	v_mul_f32_e32 v44, v45, v118
	v_mul_f32_e32 v45, v46, v115
	v_mul_f32_e32 v46, v47, v119
	v_cvt_pk_bf16_f32 v40, v40, v41
	v_cvt_pk_bf16_f32 v41, v43, v45
	v_cvt_pk_bf16_f32 v43, v44, v46
	global_store_dwordx4 v[62:63], v[40:43], off offset:1024
	v_ashrrev_i32_e32 v49, 31, v48
	s_nop 1
	v_mov_b32_e32 v40, v184
	v_mov_b32_e32 v41, v185
	v_mov_b32_e32 v42, v186
	v_mov_b32_e32 v43, v187
	s_nop 1
	v_mov_b32_e32 v44, v188
	v_mov_b32_e32 v45, v189
	v_mov_b32_e32 v46, v190
	v_mov_b32_e32 v47, v191
	v_lshl_add_u64 v[48:49], v[48:49], 2, s[4:5]
	s_nop 1
	v_mov_b32_e32 v98, v230
	v_lshlrev_b64 v[50:51], 9, v[96:97]
	v_lshl_add_u64 v[50:51], v[50:51], 0, v[78:79]
	v_mad_i64_i32 v[48:49], s[26:27], v94, s68, v[76:77]
	v_lshlrev_b64 v[50:51], 1, v[50:51]
	v_lshl_add_u64 v[62:63], v[48:49], 0, v[82:83]
	v_lshl_add_u64 v[48:49], s[50:51], 0, v[50:51]
	v_lshl_add_u64 v[50:51], s[62:63], 0, v[50:51]
	v_mul_f32_e32 v40, v40, v112
	v_mul_f32_e32 v44, v44, v116
	v_mul_f32_e32 v41, v41, v113
	v_mul_f32_e32 v45, v45, v117
	v_mul_f32_e32 v42, v42, v114
	v_mul_f32_e32 v46, v46, v118
	v_mul_f32_e32 v43, v43, v115
	v_mul_f32_e32 v47, v47, v119
	v_mul_f32_e32 v96, v40, v98
	v_mul_f32_e32 v44, v98, v44
	v_mul_f32_e32 v97, v41, v98
	v_mul_f32_e32 v45, v98, v45
	v_mul_f32_e32 v99, v42, v98
	v_mul_f32_e32 v46, v98, v46
	v_mul_f32_e32 v100, v43, v98
	v_mul_f32_e32 v47, v98, v47
	v_cvt_pk_bf16_f32 v40, v96, v97
	v_cvt_pk_bf16_f32 v41, v99, v100
	v_cvt_pk_bf16_f32 v42, v44, v45
	v_cvt_pk_bf16_f32 v43, v46, v47
	v_mul_f32_e64 v52, v52, -v96
	v_mul_f32_e64 v54, v54, -v97
	v_mul_f32_e64 v58, v58, -v99
	v_mul_f32_e64 v60, v60, -v100
	v_mul_f32_e64 v44, v53, -v44
	v_mul_f32_e64 v45, v55, -v45
	v_mul_f32_e64 v46, v59, -v46
	v_mul_f32_e64 v47, v61, -v47
	global_store_dwordx4 v[48:49], v[40:43], off
	s_nop 1
	v_cvt_pk_bf16_f32 v40, v52, v54
	v_cvt_pk_bf16_f32 v41, v58, v60
	v_cvt_pk_bf16_f32 v42, v44, v45
	v_cvt_pk_bf16_f32 v43, v46, v47
	global_store_dwordx4 v[50:51], v[40:43], off
	s_nop 1
	v_mov_b32_e32 v40, v208
	v_mov_b32_e32 v41, v209
	v_mov_b32_e32 v42, v210
	v_mov_b32_e32 v43, v211
	s_nop 1
	v_mov_b32_e32 v44, v156
	v_mov_b32_e32 v45, v157
	v_mov_b32_e32 v46, v158
	v_mov_b32_e32 v47, v159
	s_nop 1
	v_mov_b32_e32 v48, v160
	v_mov_b32_e32 v49, v161
	v_mov_b32_e32 v50, v162
	v_mov_b32_e32 v51, v163
	s_nop 1
	v_mov_b32_e32 v52, v164
	v_mov_b32_e32 v53, v165
	v_mov_b32_e32 v54, v166
	v_mov_b32_e32 v55, v167
	s_nop 1
	v_mov_b32_e32 v58, v168
	v_mov_b32_e32 v59, v169
	v_mov_b32_e32 v60, v170
	v_mov_b32_e32 v61, v171
	v_and_b32_e32 v97, 0xffff0000, v40
	v_add_f32_e32 v33, v33, v45
	v_add_f32_e32 v36, v36, v48
	v_add_f32_e32 v37, v37, v49
	v_add_f32_e32 v32, v32, v44
	v_add_f32_e32 v34, v34, v46
	v_mul_f32_e32 v36, 0xbfb8aa3b, v36
	v_mul_f32_e32 v33, 0xbfb8aa3b, v33
	v_mul_f32_e32 v37, 0xbfb8aa3b, v37
	v_add_f32_e32 v38, v38, v50
	v_add_f32_e32 v35, v35, v47
	v_add_f32_e32 v39, v39, v51
	v_mul_f32_e32 v32, 0xbfb8aa3b, v32
	v_mul_f32_e32 v34, 0xbfb8aa3b, v34
	v_exp_f32_e32 v36, v36
	v_exp_f32_e32 v33, v33
	v_exp_f32_e32 v37, v37
	v_mul_f32_e32 v38, 0xbfb8aa3b, v38
	v_mul_f32_e32 v35, 0xbfb8aa3b, v35
	v_mul_f32_e32 v39, 0xbfb8aa3b, v39
	v_exp_f32_e32 v32, v32
	v_exp_f32_e32 v34, v34
	v_exp_f32_e32 v38, v38
	v_exp_f32_e32 v35, v35
	v_exp_f32_e32 v39, v39
	v_add_f32_e32 v36, 1.0, v36
	v_add_f32_e32 v33, 1.0, v33
	v_add_f32_e32 v37, 1.0, v37
	v_add_f32_e32 v32, 1.0, v32
	v_add_f32_e32 v34, 1.0, v34
	v_rcp_f32_e32 v45, v36
	v_rcp_f32_e32 v46, v33
	v_rcp_f32_e32 v47, v37
	v_add_f32_e32 v38, 1.0, v38
	v_add_f32_e32 v35, 1.0, v35
	v_add_f32_e32 v39, 1.0, v39
	v_rcp_f32_e32 v44, v32
	v_rcp_f32_e32 v48, v34
	v_rcp_f32_e32 v49, v38
	v_rcp_f32_e32 v50, v35
	v_rcp_f32_e32 v51, v39
	v_add_f32_e32 v33, -1.0, v45
	v_add_f32_e32 v34, -1.0, v46
	v_add_f32_e32 v35, -1.0, v47
	v_lshlrev_b32_e32 v100, 16, v42
	v_and_b32_e32 v101, 0xffff0000, v42
	v_add_f32_e32 v32, -1.0, v44
	v_add_f32_e32 v36, -1.0, v48
	v_fma_f32 v33, v58, v33, 1.0
	v_fma_f32 v34, v53, v34, 1.0
	v_fma_f32 v35, v59, v35, 1.0
	v_lshlrev_b32_e32 v96, 16, v40
	v_lshlrev_b32_e32 v98, 16, v41
	v_add_f32_e32 v37, -1.0, v49
	v_add_f32_e32 v38, -1.0, v50
	v_add_f32_e32 v39, -1.0, v51
	v_fma_f32 v32, v52, v32, 1.0
	v_fma_f32 v36, v54, v36, 1.0
	v_mul_f32_e32 v40, v33, v100
	v_mul_f32_e32 v33, v34, v97
	v_mul_f32_e32 v34, v35, v101
	v_and_b32_e32 v99, 0xffff0000, v41
	v_lshlrev_b32_e32 v108, 16, v43
	v_and_b32_e32 v109, 0xffff0000, v43
	v_fma_f32 v37, v60, v37, 1.0
	v_fma_f32 v38, v55, v38, 1.0
	v_fma_f32 v39, v61, v39, 1.0
	v_mul_f32_e32 v32, v32, v96
	v_mul_f32_e32 v35, v36, v98
	v_cvt_pk_bf16_f32 v34, v40, v34
	v_lshl_add_u32 v40, v94, 3, s24
	v_mul_f32_e32 v36, v37, v108
	v_mul_f32_e32 v37, v38, v99
	v_mul_f32_e32 v38, v39, v109
	v_cvt_pk_bf16_f32 v32, v32, v33
	v_cvt_pk_bf16_f32 v33, v35, v37
	v_cvt_pk_bf16_f32 v35, v36, v38
	global_store_dwordx4 v[62:63], v[32:35], off offset:1024
	v_ashrrev_i32_e32 v41, 31, v40
	s_nop 1
	v_mov_b32_e32 v32, v184
	v_mov_b32_e32 v33, v185
	v_mov_b32_e32 v34, v186
	v_mov_b32_e32 v35, v187
	s_nop 1
	v_mov_b32_e32 v36, v188
	v_mov_b32_e32 v37, v189
	v_mov_b32_e32 v38, v190
	v_mov_b32_e32 v39, v191
	v_lshl_add_u64 v[40:41], v[40:41], 2, s[4:5]
	s_nop 1
	v_mov_b32_e32 v54, v231
	v_lshlrev_b64 v[42:43], 9, v[94:95]
	v_lshl_add_u64 v[42:43], v[42:43], 0, v[78:79]
; __device__ __forceinline__ void unpack8(const u32x4 w, float (&f)[8]) { f[0] = bflo(w.x); f[1] = bfhi(w.x); f[2] = bflo(w.y); f[3] = bfhi(w.y); f[4] = bflo(w.z); f[5] = bfhi(w.z); f[6] = bflo(w.w); f[7] = bfhi(w.w); }
; __device__ __forceinline__ u32x4 pack8(const float (&f)[8]) { u32x4 o; o.x = pk2(f[0], f[1]); o.y = pk2(f[2], f[3]); o.z = pk2(f[4], f[5]); o.w = pk2(f[6], f[7]); return o; }
; __device__ __forceinline__ float sigmoidf_(float x) { return __builtin_amdgcn_rcpf(1.0f + __expf(-x)); }
;     __device__ __forceinline__ void operator()(const f32x4 (&acc)[2][2][4][2], const Unit& u, int wr, int wc, int fr, int fq) const {
;     ...
;             for (int m = 0; m < 4; ++m) { const int row = row0 + ai * HALF + m * 16; const size_t off = (size_t)row * 512 + cb; bf16_t* kp = RKV + (size_t)row * 1536 + 512 + cb;
;                 float ks[8], av[8], t[8]; unpack8(*(const u32x4*)kp, ks);
;                 { const f32x4 c0 = *(const f32x4*)(a0 + cb), c1 = *(const f32x4*)(a0 + cb + 4); const f32x4 x0 = acc[ai][0][m][0], x1 = acc[ai][0][m][1];
; #pragma unroll
;                   for (int j = 0; j < 4; ++j) { av[j] = sigmoidf_(c0[j] + x0[j]); av[4 + j] = sigmoidf_(c1[j] + x1[j]); } }
;                 { const f32x4 c0 = *(const f32x4*)(k_a + cb), c1 = *(const f32x4*)(k_a + cb + 4);
; #pragma unroll
;                   for (int j = 0; j < 4; ++j) { t[j] = ks[j] * (1.0f + (av[j] - 1.0f) * c0[j]); t[4 + j] = ks[4 + j] * (1.0f + (av[4 + j] - 1.0f) * c1[j]); } }
;                 *(u32x4*)kp = pack8(t);
;                 { const f32x4 c0 = *(const f32x4*)(k_k + cb), c1 = *(const f32x4*)(k_k + cb + 4); const float ri = rinv[row * 8 + (cb >> 6)];
; #pragma unroll
;                   for (int j = 0; j < 4; ++j) { t[j] = ks[j] * c0[j] * ri; t[4 + j] = ks[4 + j] * c1[j] * ri; } }
;                 *(u32x4*)(KK + off) = pack8(t);
; #pragma unroll
;                 for (int e = 0; e < 8; ++e) t[e] = -t[e] * av[e];
;                 *(u32x4*)(NB + off) = pack8(t);
;                 asm volatile("" ::: "memory"); }
	v_mad_i64_i32 v[40:41], s[26:27], v92, s68, v[76:77]
	v_lshlrev_b64 v[42:43], 1, v[42:43]
	v_lshl_add_u64 v[52:53], v[40:41], 0, v[82:83]
	v_lshl_add_u64 v[40:41], s[50:51], 0, v[42:43]
	v_lshl_add_u64 v[42:43], s[62:63], 0, v[42:43]
	v_mul_f32_e32 v32, v32, v96
	v_mul_f32_e32 v36, v36, v100
	v_mul_f32_e32 v33, v33, v97
	v_mul_f32_e32 v37, v37, v101
	v_mul_f32_e32 v34, v34, v98
	v_mul_f32_e32 v38, v38, v108
	v_mul_f32_e32 v35, v35, v99
	v_mul_f32_e32 v39, v39, v109
	v_mul_f32_e32 v55, v32, v54
	v_mul_f32_e32 v36, v54, v36
	v_mul_f32_e32 v58, v33, v54
	v_mul_f32_e32 v37, v54, v37
	v_mul_f32_e32 v59, v34, v54
	v_mul_f32_e32 v38, v54, v38
	v_mul_f32_e32 v60, v35, v54
	v_mul_f32_e32 v39, v54, v39
	v_cvt_pk_bf16_f32 v32, v55, v58
	v_cvt_pk_bf16_f32 v33, v59, v60
	v_cvt_pk_bf16_f32 v34, v36, v37
	v_cvt_pk_bf16_f32 v35, v38, v39
	v_mul_f32_e64 v44, v44, -v55
	v_mul_f32_e64 v46, v46, -v58
	v_mul_f32_e64 v48, v48, -v59
	v_mul_f32_e64 v50, v50, -v60
	v_mul_f32_e64 v36, v45, -v36
	v_mul_f32_e64 v37, v47, -v37
	v_mul_f32_e64 v38, v49, -v38
	v_mul_f32_e64 v39, v51, -v39
	global_store_dwordx4 v[40:41], v[32:35], off
	s_nop 1
	v_cvt_pk_bf16_f32 v32, v44, v46
	v_cvt_pk_bf16_f32 v33, v48, v50
	v_cvt_pk_bf16_f32 v34, v36, v37
	v_cvt_pk_bf16_f32 v35, v38, v39
	global_store_dwordx4 v[42:43], v[32:35], off
	s_nop 1
	v_mov_b32_e32 v32, v212
	v_mov_b32_e32 v33, v213
	v_mov_b32_e32 v34, v214
	v_mov_b32_e32 v35, v215
	s_nop 1
	v_mov_b32_e32 v36, v156
	v_mov_b32_e32 v37, v157
	v_mov_b32_e32 v38, v158
	v_mov_b32_e32 v39, v159
	s_nop 1
	v_mov_b32_e32 v40, v160
	v_mov_b32_e32 v41, v161
	v_mov_b32_e32 v42, v162
	v_mov_b32_e32 v43, v163
	s_nop 1
	v_mov_b32_e32 v44, v164
	v_mov_b32_e32 v45, v165
	v_mov_b32_e32 v46, v166
	v_mov_b32_e32 v47, v167
	s_nop 1
	v_mov_b32_e32 v48, v168
	v_mov_b32_e32 v49, v169
	v_mov_b32_e32 v50, v170
	v_mov_b32_e32 v51, v171
	v_and_b32_e32 v55, 0xffff0000, v32
	v_add_f32_e32 v25, v25, v37
	v_add_f32_e32 v28, v28, v40
	v_add_f32_e32 v29, v29, v41
	v_add_f32_e32 v24, v24, v36
	v_add_f32_e32 v26, v26, v38
	v_mul_f32_e32 v28, 0xbfb8aa3b, v28
	v_mul_f32_e32 v25, 0xbfb8aa3b, v25
	v_mul_f32_e32 v29, 0xbfb8aa3b, v29
	v_add_f32_e32 v30, v30, v42
	v_add_f32_e32 v27, v27, v39
	v_add_f32_e32 v31, v31, v43
	v_mul_f32_e32 v24, 0xbfb8aa3b, v24
	v_mul_f32_e32 v26, 0xbfb8aa3b, v26
	v_exp_f32_e32 v28, v28
	v_exp_f32_e32 v25, v25
	v_exp_f32_e32 v29, v29
	v_mul_f32_e32 v30, 0xbfb8aa3b, v30
	v_mul_f32_e32 v27, 0xbfb8aa3b, v27
	v_mul_f32_e32 v31, 0xbfb8aa3b, v31
	v_exp_f32_e32 v24, v24
	v_exp_f32_e32 v26, v26
	v_exp_f32_e32 v30, v30
	v_exp_f32_e32 v27, v27
	v_exp_f32_e32 v31, v31
	v_add_f32_e32 v28, 1.0, v28
	v_add_f32_e32 v25, 1.0, v25
	v_add_f32_e32 v29, 1.0, v29
	v_add_f32_e32 v24, 1.0, v24
	v_add_f32_e32 v26, 1.0, v26
	v_rcp_f32_e32 v37, v28
	v_rcp_f32_e32 v38, v25
	v_rcp_f32_e32 v39, v29
	v_add_f32_e32 v30, 1.0, v30
	v_add_f32_e32 v27, 1.0, v27
	v_add_f32_e32 v31, 1.0, v31
	v_rcp_f32_e32 v36, v24
	v_rcp_f32_e32 v40, v26
	v_rcp_f32_e32 v41, v30
	v_rcp_f32_e32 v42, v27
	v_rcp_f32_e32 v43, v31
	v_add_f32_e32 v25, -1.0, v37
	v_add_f32_e32 v26, -1.0, v38
	v_add_f32_e32 v27, -1.0, v39
	v_lshlrev_b32_e32 v60, 16, v34
	v_and_b32_e32 v61, 0xffff0000, v34
	v_add_f32_e32 v24, -1.0, v36
	v_add_f32_e32 v28, -1.0, v40
	v_fma_f32 v25, v48, v25, 1.0
	v_fma_f32 v26, v45, v26, 1.0
	v_fma_f32 v27, v49, v27, 1.0
	v_lshlrev_b32_e32 v54, 16, v32
	v_lshlrev_b32_e32 v58, 16, v33
	v_add_f32_e32 v29, -1.0, v41
	v_add_f32_e32 v30, -1.0, v42
	v_add_f32_e32 v31, -1.0, v43
	v_fma_f32 v24, v44, v24, 1.0
	v_fma_f32 v28, v46, v28, 1.0
	v_mul_f32_e32 v32, v25, v60
	v_mul_f32_e32 v25, v26, v55
	v_mul_f32_e32 v26, v27, v61
	v_and_b32_e32 v59, 0xffff0000, v33
	v_lshlrev_b32_e32 v62, 16, v35
	v_and_b32_e32 v63, 0xffff0000, v35
	v_fma_f32 v29, v50, v29, 1.0
	v_fma_f32 v30, v47, v30, 1.0
	v_fma_f32 v31, v51, v31, 1.0
	v_mul_f32_e32 v24, v24, v54
	v_mul_f32_e32 v27, v28, v58
	v_cvt_pk_bf16_f32 v26, v32, v26
	v_lshl_add_u32 v32, v92, 3, s24
	v_mul_f32_e32 v28, v29, v62
	v_mul_f32_e32 v29, v30, v59
	v_mul_f32_e32 v30, v31, v63
	v_cvt_pk_bf16_f32 v24, v24, v25
	v_cvt_pk_bf16_f32 v25, v27, v29
	v_cvt_pk_bf16_f32 v27, v28, v30
	global_store_dwordx4 v[52:53], v[24:27], off offset:1024
	v_ashrrev_i32_e32 v33, 31, v32
	s_nop 1
	v_mov_b32_e32 v24, v184
	v_mov_b32_e32 v25, v185
	v_mov_b32_e32 v26, v186
	v_mov_b32_e32 v27, v187
	s_nop 1
	v_mov_b32_e32 v28, v188
	v_mov_b32_e32 v29, v189
	v_mov_b32_e32 v30, v190
	v_mov_b32_e32 v31, v191
	v_lshl_add_u64 v[32:33], v[32:33], 2, s[4:5]
	s_nop 1
	v_mov_b32_e32 v46, v232
	v_lshlrev_b64 v[34:35], 9, v[92:93]
	v_lshl_add_u64 v[34:35], v[34:35], 0, v[78:79]
	v_mad_i64_i32 v[32:33], s[26:27], v90, s68, v[76:77]
	v_lshlrev_b64 v[34:35], 1, v[34:35]
	v_lshl_add_u64 v[44:45], v[32:33], 0, v[82:83]
	v_lshl_add_u64 v[32:33], s[50:51], 0, v[34:35]
	v_lshl_add_u64 v[34:35], s[62:63], 0, v[34:35]
	v_mul_f32_e32 v24, v24, v54
	v_mul_f32_e32 v28, v28, v60
	v_mul_f32_e32 v25, v25, v55
	v_mul_f32_e32 v29, v29, v61
	v_mul_f32_e32 v26, v26, v58
	v_mul_f32_e32 v30, v30, v62
	v_mul_f32_e32 v27, v27, v59
	v_mul_f32_e32 v31, v31, v63
	v_mul_f32_e32 v47, v24, v46
	v_mul_f32_e32 v28, v46, v28
	v_mul_f32_e32 v48, v25, v46
	v_mul_f32_e32 v29, v46, v29
	v_mul_f32_e32 v49, v26, v46
	v_mul_f32_e32 v30, v46, v30
	v_mul_f32_e32 v50, v27, v46
	v_mul_f32_e32 v31, v46, v31
	v_cvt_pk_bf16_f32 v24, v47, v48
	v_cvt_pk_bf16_f32 v25, v49, v50
	v_cvt_pk_bf16_f32 v26, v28, v29
	v_cvt_pk_bf16_f32 v27, v30, v31
	v_mul_f32_e64 v36, v36, -v47
	v_mul_f32_e64 v38, v38, -v48
	v_mul_f32_e64 v40, v40, -v49
	v_mul_f32_e64 v42, v42, -v50
	v_mul_f32_e64 v28, v37, -v28
	v_mul_f32_e64 v29, v39, -v29
	v_mul_f32_e64 v30, v41, -v30
; __device__ __forceinline__ void unpack8(const u32x4 w, float (&f)[8]) { f[0] = bflo(w.x); f[1] = bfhi(w.x); f[2] = bflo(w.y); f[3] = bfhi(w.y); f[4] = bflo(w.z); f[5] = bfhi(w.z); f[6] = bflo(w.w); f[7] = bfhi(w.w); }
; __device__ __forceinline__ u32x4 pack8(const float (&f)[8]) { u32x4 o; o.x = pk2(f[0], f[1]); o.y = pk2(f[2], f[3]); o.z = pk2(f[4], f[5]); o.w = pk2(f[6], f[7]); return o; }
; __device__ __forceinline__ float sigmoidf_(float x) { return __builtin_amdgcn_rcpf(1.0f + __expf(-x)); }
;     __device__ __forceinline__ void operator()(const f32x4 (&acc)[2][2][4][2], const Unit& u, int wr, int wc, int fr, int fq) const {
;     ...
;             for (int m = 0; m < 4; ++m) { const int row = row0 + ai * HALF + m * 16; const size_t off = (size_t)row * 512 + cb; bf16_t* kp = RKV + (size_t)row * 1536 + 512 + cb;
;                 float ks[8], av[8], t[8]; unpack8(*(const u32x4*)kp, ks);
;                 { const f32x4 c0 = *(const f32x4*)(a0 + cb), c1 = *(const f32x4*)(a0 + cb + 4); const f32x4 x0 = acc[ai][0][m][0], x1 = acc[ai][0][m][1];
; #pragma unroll
;                   for (int j = 0; j < 4; ++j) { av[j] = sigmoidf_(c0[j] + x0[j]); av[4 + j] = sigmoidf_(c1[j] + x1[j]); } }
;                 { const f32x4 c0 = *(const f32x4*)(k_a + cb), c1 = *(const f32x4*)(k_a + cb + 4);
; #pragma unroll
;                   for (int j = 0; j < 4; ++j) { t[j] = ks[j] * (1.0f + (av[j] - 1.0f) * c0[j]); t[4 + j] = ks[4 + j] * (1.0f + (av[4 + j] - 1.0f) * c1[j]); } }
;                 *(u32x4*)kp = pack8(t);
;                 { const f32x4 c0 = *(const f32x4*)(k_k + cb), c1 = *(const f32x4*)(k_k + cb + 4); const float ri = rinv[row * 8 + (cb >> 6)];
; #pragma unroll
;                   for (int j = 0; j < 4; ++j) { t[j] = ks[j] * c0[j] * ri; t[4 + j] = ks[4 + j] * c1[j] * ri; } }
;                 *(u32x4*)(KK + off) = pack8(t);
; #pragma unroll
;                 for (int e = 0; e < 8; ++e) t[e] = -t[e] * av[e];
;                 *(u32x4*)(NB + off) = pack8(t);
;                 asm volatile("" ::: "memory"); }
	v_mul_f32_e64 v31, v43, -v31
	global_store_dwordx4 v[32:33], v[24:27], off
	s_nop 1
	v_cvt_pk_bf16_f32 v24, v36, v38
	v_cvt_pk_bf16_f32 v25, v40, v42
	v_cvt_pk_bf16_f32 v26, v28, v29
	v_cvt_pk_bf16_f32 v27, v30, v31
	global_store_dwordx4 v[34:35], v[24:27], off
	s_nop 1
	v_mov_b32_e32 v24, v216
	v_mov_b32_e32 v25, v217
	v_mov_b32_e32 v26, v218
	v_mov_b32_e32 v27, v219
	s_nop 1
	v_mov_b32_e32 v28, v156
	v_mov_b32_e32 v29, v157
	v_mov_b32_e32 v30, v158
	v_mov_b32_e32 v31, v159
	s_nop 1
	v_mov_b32_e32 v32, v160
	v_mov_b32_e32 v33, v161
	v_mov_b32_e32 v34, v162
	v_mov_b32_e32 v35, v163
	s_nop 1
	v_mov_b32_e32 v36, v164
	v_mov_b32_e32 v37, v165
	v_mov_b32_e32 v38, v166
	v_mov_b32_e32 v39, v167
	s_nop 1
	v_mov_b32_e32 v40, v168
	v_mov_b32_e32 v41, v169
	v_mov_b32_e32 v42, v170
	v_mov_b32_e32 v43, v171
	v_and_b32_e32 v47, 0xffff0000, v24
	v_add_f32_e32 v17, v17, v29
	v_add_f32_e32 v20, v20, v32
	v_add_f32_e32 v21, v21, v33
	v_add_f32_e32 v16, v16, v28
	v_add_f32_e32 v18, v18, v30
	v_mul_f32_e32 v20, 0xbfb8aa3b, v20
	v_mul_f32_e32 v17, 0xbfb8aa3b, v17
	v_mul_f32_e32 v21, 0xbfb8aa3b, v21
	v_add_f32_e32 v22, v22, v34
	v_add_f32_e32 v19, v19, v31
	v_add_f32_e32 v23, v23, v35
	v_mul_f32_e32 v16, 0xbfb8aa3b, v16
	v_mul_f32_e32 v18, 0xbfb8aa3b, v18
	v_exp_f32_e32 v20, v20
	v_exp_f32_e32 v17, v17
	v_exp_f32_e32 v21, v21
	v_mul_f32_e32 v22, 0xbfb8aa3b, v22
	v_mul_f32_e32 v19, 0xbfb8aa3b, v19
	v_mul_f32_e32 v23, 0xbfb8aa3b, v23
	v_exp_f32_e32 v16, v16
	v_exp_f32_e32 v18, v18
	v_exp_f32_e32 v22, v22
	v_exp_f32_e32 v19, v19
	v_exp_f32_e32 v23, v23
	v_add_f32_e32 v20, 1.0, v20
	v_add_f32_e32 v17, 1.0, v17
	v_add_f32_e32 v21, 1.0, v21
	v_add_f32_e32 v16, 1.0, v16
	v_add_f32_e32 v18, 1.0, v18
	v_rcp_f32_e32 v29, v20
	v_rcp_f32_e32 v30, v17
	v_rcp_f32_e32 v31, v21
	v_add_f32_e32 v22, 1.0, v22
	v_add_f32_e32 v19, 1.0, v19
	v_add_f32_e32 v23, 1.0, v23
	v_rcp_f32_e32 v28, v16
	v_rcp_f32_e32 v32, v18
	v_rcp_f32_e32 v33, v22
	v_rcp_f32_e32 v34, v19
	v_rcp_f32_e32 v35, v23
	v_add_f32_e32 v17, -1.0, v29
	v_add_f32_e32 v18, -1.0, v30
	v_add_f32_e32 v19, -1.0, v31
	v_lshlrev_b32_e32 v50, 16, v26
	v_and_b32_e32 v51, 0xffff0000, v26
	v_add_f32_e32 v16, -1.0, v28
	v_add_f32_e32 v20, -1.0, v32
	v_fma_f32 v17, v40, v17, 1.0
	v_fma_f32 v18, v37, v18, 1.0
	v_fma_f32 v19, v41, v19, 1.0
	v_lshlrev_b32_e32 v46, 16, v24
	v_lshlrev_b32_e32 v48, 16, v25
	v_add_f32_e32 v21, -1.0, v33
	v_add_f32_e32 v22, -1.0, v34
	v_add_f32_e32 v23, -1.0, v35
	v_fma_f32 v16, v36, v16, 1.0
	v_fma_f32 v20, v38, v20, 1.0
	v_mul_f32_e32 v24, v17, v50
	v_mul_f32_e32 v17, v18, v47
	v_mul_f32_e32 v18, v19, v51
	v_and_b32_e32 v49, 0xffff0000, v25
	v_lshlrev_b32_e32 v52, 16, v27
	v_and_b32_e32 v53, 0xffff0000, v27
	v_fma_f32 v21, v42, v21, 1.0
	v_fma_f32 v22, v39, v22, 1.0
	v_fma_f32 v23, v43, v23, 1.0
	v_mul_f32_e32 v16, v16, v46
	v_mul_f32_e32 v19, v20, v48
	v_cvt_pk_bf16_f32 v18, v24, v18
	v_lshl_add_u32 v24, v90, 3, s24
	v_mul_f32_e32 v20, v21, v52
	v_mul_f32_e32 v21, v22, v49
	v_mul_f32_e32 v22, v23, v53
	v_cvt_pk_bf16_f32 v16, v16, v17
	v_cvt_pk_bf16_f32 v17, v19, v21
	v_cvt_pk_bf16_f32 v19, v20, v22
	global_store_dwordx4 v[44:45], v[16:19], off offset:1024
	v_ashrrev_i32_e32 v25, 31, v24
	s_nop 1
	v_mov_b32_e32 v16, v184
	v_mov_b32_e32 v17, v185
	v_mov_b32_e32 v18, v186
	v_mov_b32_e32 v19, v187
	s_nop 1
	v_mov_b32_e32 v20, v188
	v_mov_b32_e32 v21, v189
	v_mov_b32_e32 v22, v190
	v_mov_b32_e32 v23, v191
	v_lshl_add_u64 v[24:25], v[24:25], 2, s[4:5]
	s_nop 1
	v_mov_b32_e32 v38, v233
	v_lshlrev_b64 v[26:27], 9, v[90:91]
	v_lshl_add_u64 v[26:27], v[26:27], 0, v[78:79]
	v_mad_i64_i32 v[24:25], s[26:27], v88, s68, v[76:77]
	v_lshlrev_b64 v[26:27], 1, v[26:27]
	v_lshl_add_u64 v[36:37], v[24:25], 0, v[82:83]
	v_lshl_add_u64 v[24:25], s[50:51], 0, v[26:27]
	v_lshl_add_u64 v[26:27], s[62:63], 0, v[26:27]
	v_mul_f32_e32 v16, v16, v46
	v_mul_f32_e32 v20, v20, v50
	v_mul_f32_e32 v17, v17, v47
	v_mul_f32_e32 v21, v21, v51
	v_mul_f32_e32 v18, v18, v48
	v_mul_f32_e32 v22, v22, v52
	v_mul_f32_e32 v19, v19, v49
	v_mul_f32_e32 v23, v23, v53
	v_mul_f32_e32 v39, v16, v38
	v_mul_f32_e32 v20, v38, v20
	v_mul_f32_e32 v40, v17, v38
	v_mul_f32_e32 v21, v38, v21
	v_mul_f32_e32 v41, v18, v38
	v_mul_f32_e32 v22, v38, v22
	v_mul_f32_e32 v42, v19, v38
	v_mul_f32_e32 v23, v38, v23
	v_cvt_pk_bf16_f32 v16, v39, v40
	v_cvt_pk_bf16_f32 v17, v41, v42
	v_cvt_pk_bf16_f32 v18, v20, v21
	v_cvt_pk_bf16_f32 v19, v22, v23
	v_mul_f32_e64 v28, v28, -v39
	v_mul_f32_e64 v30, v30, -v40
	v_mul_f32_e64 v32, v32, -v41
	v_mul_f32_e64 v34, v34, -v42
	v_mul_f32_e64 v20, v29, -v20
	v_mul_f32_e64 v21, v31, -v21
	v_mul_f32_e64 v22, v33, -v22
	v_mul_f32_e64 v23, v35, -v23
	global_store_dwordx4 v[24:25], v[16:19], off
	s_nop 1
	v_cvt_pk_bf16_f32 v16, v28, v30
	v_cvt_pk_bf16_f32 v17, v32, v34
	v_cvt_pk_bf16_f32 v18, v20, v21
	v_cvt_pk_bf16_f32 v19, v22, v23
	global_store_dwordx4 v[26:27], v[16:19], off
	s_nop 1
	v_mov_b32_e32 v16, v220
	v_mov_b32_e32 v17, v221
	v_mov_b32_e32 v18, v222
	v_mov_b32_e32 v19, v223
	s_nop 1
	v_mov_b32_e32 v20, v156
	v_mov_b32_e32 v21, v157
	v_mov_b32_e32 v22, v158
	v_mov_b32_e32 v23, v159
	s_nop 1
	v_mov_b32_e32 v24, v160
	v_mov_b32_e32 v25, v161
	v_mov_b32_e32 v26, v162
	v_mov_b32_e32 v27, v163
	s_nop 1
	v_mov_b32_e32 v28, v164
	v_mov_b32_e32 v29, v165
	v_mov_b32_e32 v30, v166
	v_mov_b32_e32 v31, v167
	s_nop 1
	v_mov_b32_e32 v32, v168
	v_mov_b32_e32 v33, v169
	v_mov_b32_e32 v34, v170
	v_mov_b32_e32 v35, v171
	v_and_b32_e32 v39, 0xffff0000, v16
	v_add_f32_e32 v9, v9, v21
	v_add_f32_e32 v12, v12, v24
	v_add_f32_e32 v13, v13, v25
	v_add_f32_e32 v8, v8, v20
	v_add_f32_e32 v10, v10, v22
	v_mul_f32_e32 v12, 0xbfb8aa3b, v12
; __device__ __forceinline__ void unpack8(const u32x4 w, float (&f)[8]) { f[0] = bflo(w.x); f[1] = bfhi(w.x); f[2] = bflo(w.y); f[3] = bfhi(w.y); f[4] = bflo(w.z); f[5] = bfhi(w.z); f[6] = bflo(w.w); f[7] = bfhi(w.w); }
; __device__ __forceinline__ u32x4 pack8(const float (&f)[8]) { u32x4 o; o.x = pk2(f[0], f[1]); o.y = pk2(f[2], f[3]); o.z = pk2(f[4], f[5]); o.w = pk2(f[6], f[7]); return o; }
; __device__ __forceinline__ float sigmoidf_(float x) { return __builtin_amdgcn_rcpf(1.0f + __expf(-x)); }
;     __device__ __forceinline__ void operator()(const f32x4 (&acc)[2][2][4][2], const Unit& u, int wr, int wc, int fr, int fq) const {
;     ...
;             for (int m = 0; m < 4; ++m) { const int row = row0 + ai * HALF + m * 16; const size_t off = (size_t)row * 512 + cb; bf16_t* kp = RKV + (size_t)row * 1536 + 512 + cb;
;                 float ks[8], av[8], t[8]; unpack8(*(const u32x4*)kp, ks);
;                 { const f32x4 c0 = *(const f32x4*)(a0 + cb), c1 = *(const f32x4*)(a0 + cb + 4); const f32x4 x0 = acc[ai][0][m][0], x1 = acc[ai][0][m][1];
; #pragma unroll
;                   for (int j = 0; j < 4; ++j) { av[j] = sigmoidf_(c0[j] + x0[j]); av[4 + j] = sigmoidf_(c1[j] + x1[j]); } }
;                 { const f32x4 c0 = *(const f32x4*)(k_a + cb), c1 = *(const f32x4*)(k_a + cb + 4);
; #pragma unroll
;                   for (int j = 0; j < 4; ++j) { t[j] = ks[j] * (1.0f + (av[j] - 1.0f) * c0[j]); t[4 + j] = ks[4 + j] * (1.0f + (av[4 + j] - 1.0f) * c1[j]); } }
;                 *(u32x4*)kp = pack8(t);
;                 { const f32x4 c0 = *(const f32x4*)(k_k + cb), c1 = *(const f32x4*)(k_k + cb + 4); const float ri = rinv[row * 8 + (cb >> 6)];
; #pragma unroll
;                   for (int j = 0; j < 4; ++j) { t[j] = ks[j] * c0[j] * ri; t[4 + j] = ks[4 + j] * c1[j] * ri; } }
;                 *(u32x4*)(KK + off) = pack8(t);
; #pragma unroll
;                 for (int e = 0; e < 8; ++e) t[e] = -t[e] * av[e];
;                 *(u32x4*)(NB + off) = pack8(t);
;                 asm volatile("" ::: "memory"); }
	v_mul_f32_e32 v9, 0xbfb8aa3b, v9
	v_mul_f32_e32 v13, 0xbfb8aa3b, v13
	v_add_f32_e32 v14, v14, v26
	v_add_f32_e32 v11, v11, v23
	v_add_f32_e32 v15, v15, v27
	v_mul_f32_e32 v8, 0xbfb8aa3b, v8
	v_mul_f32_e32 v10, 0xbfb8aa3b, v10
	v_exp_f32_e32 v12, v12
	v_exp_f32_e32 v9, v9
	v_exp_f32_e32 v13, v13
	v_mul_f32_e32 v14, 0xbfb8aa3b, v14
	v_mul_f32_e32 v11, 0xbfb8aa3b, v11
	v_mul_f32_e32 v15, 0xbfb8aa3b, v15
	v_exp_f32_e32 v8, v8
	v_exp_f32_e32 v10, v10
	v_exp_f32_e32 v14, v14
	v_exp_f32_e32 v11, v11
	v_exp_f32_e32 v15, v15
	v_add_f32_e32 v12, 1.0, v12
	v_add_f32_e32 v9, 1.0, v9
	v_add_f32_e32 v13, 1.0, v13
	v_add_f32_e32 v8, 1.0, v8
	v_add_f32_e32 v10, 1.0, v10
	v_rcp_f32_e32 v21, v12
	v_rcp_f32_e32 v22, v9
	v_rcp_f32_e32 v23, v13
	v_add_f32_e32 v14, 1.0, v14
	v_add_f32_e32 v11, 1.0, v11
	v_add_f32_e32 v15, 1.0, v15
	v_rcp_f32_e32 v20, v8
	v_rcp_f32_e32 v24, v10
	v_rcp_f32_e32 v25, v14
	v_rcp_f32_e32 v26, v11
	v_rcp_f32_e32 v27, v15
	v_add_f32_e32 v9, -1.0, v21
	v_add_f32_e32 v10, -1.0, v22
	v_add_f32_e32 v11, -1.0, v23
	v_lshlrev_b32_e32 v42, 16, v18
	v_and_b32_e32 v43, 0xffff0000, v18
	v_add_f32_e32 v8, -1.0, v20
	v_add_f32_e32 v12, -1.0, v24
	v_fma_f32 v9, v32, v9, 1.0
	v_fma_f32 v10, v29, v10, 1.0
	v_fma_f32 v11, v33, v11, 1.0
	v_lshlrev_b32_e32 v38, 16, v16
	v_lshlrev_b32_e32 v40, 16, v17
	v_add_f32_e32 v13, -1.0, v25
	v_add_f32_e32 v14, -1.0, v26
	v_add_f32_e32 v15, -1.0, v27
	v_fma_f32 v8, v28, v8, 1.0
	v_fma_f32 v12, v30, v12, 1.0
	v_mul_f32_e32 v16, v9, v42
	v_mul_f32_e32 v9, v10, v39
	v_mul_f32_e32 v10, v11, v43
	v_and_b32_e32 v41, 0xffff0000, v17
	v_lshlrev_b32_e32 v44, 16, v19
	v_and_b32_e32 v45, 0xffff0000, v19
	v_fma_f32 v13, v34, v13, 1.0
	v_fma_f32 v14, v31, v14, 1.0
	v_fma_f32 v15, v35, v15, 1.0
	v_mul_f32_e32 v8, v8, v38
	v_mul_f32_e32 v11, v12, v40
	v_cvt_pk_bf16_f32 v10, v16, v10
	v_lshl_add_u32 v16, v88, 3, s24
	v_mul_f32_e32 v12, v13, v44
	v_mul_f32_e32 v13, v14, v41
	v_mul_f32_e32 v14, v15, v45
	v_cvt_pk_bf16_f32 v8, v8, v9
	v_cvt_pk_bf16_f32 v9, v11, v13
	v_cvt_pk_bf16_f32 v11, v12, v14
	global_store_dwordx4 v[36:37], v[8:11], off offset:1024
	v_ashrrev_i32_e32 v17, 31, v16
	s_nop 1
	v_mov_b32_e32 v8, v184
	v_mov_b32_e32 v9, v185
	v_mov_b32_e32 v10, v186
	v_mov_b32_e32 v11, v187
	s_nop 1
	v_mov_b32_e32 v12, v188
	v_mov_b32_e32 v13, v189
	v_mov_b32_e32 v14, v190
	v_mov_b32_e32 v15, v191
	v_lshl_add_u64 v[16:17], v[16:17], 2, s[4:5]
	s_nop 1
	v_mov_b32_e32 v30, v234
	v_lshlrev_b64 v[18:19], 9, v[88:89]
	v_lshl_add_u64 v[18:19], v[18:19], 0, v[78:79]
	v_mad_i64_i32 v[16:17], s[26:27], v80, s68, v[76:77]
	v_lshlrev_b64 v[18:19], 1, v[18:19]
	v_lshl_add_u64 v[28:29], v[16:17], 0, v[82:83]
	v_lshl_add_u64 v[16:17], s[50:51], 0, v[18:19]
	v_lshl_add_u64 v[18:19], s[62:63], 0, v[18:19]
	s_mov_b64 s[26:27], s[8:9]
	v_mul_f32_e32 v8, v8, v38
	v_mul_f32_e32 v12, v12, v42
	v_mul_f32_e32 v9, v9, v39
	v_mul_f32_e32 v13, v13, v43
	v_mul_f32_e32 v10, v10, v40
	v_mul_f32_e32 v14, v14, v44
	v_mul_f32_e32 v11, v11, v41
	v_mul_f32_e32 v15, v15, v45
	v_mul_f32_e32 v31, v8, v30
	v_mul_f32_e32 v12, v30, v12
	v_mul_f32_e32 v32, v9, v30
	v_mul_f32_e32 v13, v30, v13
	v_mul_f32_e32 v33, v10, v30
	v_mul_f32_e32 v14, v30, v14
	v_mul_f32_e32 v34, v11, v30
	v_mul_f32_e32 v15, v30, v15
	v_cvt_pk_bf16_f32 v8, v31, v32
	v_cvt_pk_bf16_f32 v9, v33, v34
	v_cvt_pk_bf16_f32 v10, v12, v13
	v_cvt_pk_bf16_f32 v11, v14, v15
	v_mul_f32_e64 v20, v20, -v31
	v_mul_f32_e64 v22, v22, -v32
	v_mul_f32_e64 v24, v24, -v33
	v_mul_f32_e64 v26, v26, -v34
	v_mul_f32_e64 v12, v21, -v12
	v_mul_f32_e64 v13, v23, -v13
	v_mul_f32_e64 v14, v25, -v14
	v_mul_f32_e64 v15, v27, -v15
	global_store_dwordx4 v[16:17], v[8:11], off
	s_nop 1
	v_cvt_pk_bf16_f32 v8, v20, v22
	v_cvt_pk_bf16_f32 v9, v24, v26
	v_cvt_pk_bf16_f32 v10, v12, v13
	v_cvt_pk_bf16_f32 v11, v14, v15
	global_store_dwordx4 v[18:19], v[8:11], off
	s_nop 1
	v_mov_b32_e32 v8, v224
	v_mov_b32_e32 v9, v225
	v_mov_b32_e32 v10, v226
	v_mov_b32_e32 v11, v227
	s_nop 1
	v_mov_b32_e32 v12, v156
	v_mov_b32_e32 v13, v157
	v_mov_b32_e32 v14, v158
	v_mov_b32_e32 v15, v159
	s_nop 1
	v_mov_b32_e32 v16, v160
; __device__ __forceinline__ void unpack8(const u32x4 w, float (&f)[8]) { f[0] = bflo(w.x); f[1] = bfhi(w.x); f[2] = bflo(w.y); f[3] = bfhi(w.y); f[4] = bflo(w.z); f[5] = bfhi(w.z); f[6] = bflo(w.w); f[7] = bfhi(w.w); }
; __device__ __forceinline__ u32x4 pack8(const float (&f)[8]) { u32x4 o; o.x = pk2(f[0], f[1]); o.y = pk2(f[2], f[3]); o.z = pk2(f[4], f[5]); o.w = pk2(f[6], f[7]); return o; }
; __device__ __forceinline__ float sigmoidf_(float x) { return __builtin_amdgcn_rcpf(1.0f + __expf(-x)); }
;     __device__ __forceinline__ void operator()(const f32x4 (&acc)[2][2][4][2], const Unit& u, int wr, int wc, int fr, int fq) const {
;     ...
;             for (int m = 0; m < 4; ++m) { const int row = row0 + ai * HALF + m * 16; const size_t off = (size_t)row * 512 + cb; bf16_t* kp = RKV + (size_t)row * 1536 + 512 + cb;
;                 float ks[8], av[8], t[8]; unpack8(*(const u32x4*)kp, ks);
;                 { const f32x4 c0 = *(const f32x4*)(a0 + cb), c1 = *(const f32x4*)(a0 + cb + 4); const f32x4 x0 = acc[ai][0][m][0], x1 = acc[ai][0][m][1];
; #pragma unroll
;                   for (int j = 0; j < 4; ++j) { av[j] = sigmoidf_(c0[j] + x0[j]); av[4 + j] = sigmoidf_(c1[j] + x1[j]); } }
;                 { const f32x4 c0 = *(const f32x4*)(k_a + cb), c1 = *(const f32x4*)(k_a + cb + 4);
; #pragma unroll
;                   for (int j = 0; j < 4; ++j) { t[j] = ks[j] * (1.0f + (av[j] - 1.0f) * c0[j]); t[4 + j] = ks[4 + j] * (1.0f + (av[4 + j] - 1.0f) * c1[j]); } }
;                 *(u32x4*)kp = pack8(t);
;                 { const f32x4 c0 = *(const f32x4*)(k_k + cb), c1 = *(const f32x4*)(k_k + cb + 4); const float ri = rinv[row * 8 + (cb >> 6)];
; #pragma unroll
;                   for (int j = 0; j < 4; ++j) { t[j] = ks[j] * c0[j] * ri; t[4 + j] = ks[4 + j] * c1[j] * ri; } }
;                 *(u32x4*)(KK + off) = pack8(t);
; #pragma unroll
;                 for (int e = 0; e < 8; ++e) t[e] = -t[e] * av[e];
;                 *(u32x4*)(NB + off) = pack8(t);
;                 asm volatile("" ::: "memory"); }
	v_mov_b32_e32 v17, v161
	v_mov_b32_e32 v18, v162
	v_mov_b32_e32 v19, v163
	s_nop 1
	v_mov_b32_e32 v20, v164
	v_mov_b32_e32 v21, v165
	v_mov_b32_e32 v22, v166
	v_mov_b32_e32 v23, v167
	s_nop 1
	v_mov_b32_e32 v24, v168
	v_mov_b32_e32 v25, v169
	v_mov_b32_e32 v26, v170
	v_mov_b32_e32 v27, v171
	v_and_b32_e32 v31, 0xffff0000, v8
	v_add_f32_e32 v1, v1, v13
	v_add_f32_e32 v4, v4, v16
	v_add_f32_e32 v5, v5, v17
	v_add_f32_e32 v0, v0, v12
	v_add_f32_e32 v2, v2, v14
	v_mul_f32_e32 v4, 0xbfb8aa3b, v4
	v_mul_f32_e32 v1, 0xbfb8aa3b, v1
	v_mul_f32_e32 v5, 0xbfb8aa3b, v5
	v_add_f32_e32 v6, v6, v18
	v_add_f32_e32 v3, v3, v15
	v_add_f32_e32 v7, v7, v19
	v_mul_f32_e32 v0, 0xbfb8aa3b, v0
	v_mul_f32_e32 v2, 0xbfb8aa3b, v2
	v_exp_f32_e32 v4, v4
	v_exp_f32_e32 v1, v1
	v_exp_f32_e32 v5, v5
	v_mul_f32_e32 v6, 0xbfb8aa3b, v6
	v_mul_f32_e32 v3, 0xbfb8aa3b, v3
	v_mul_f32_e32 v7, 0xbfb8aa3b, v7
	v_exp_f32_e32 v0, v0
	v_exp_f32_e32 v2, v2
	v_exp_f32_e32 v6, v6
	v_exp_f32_e32 v3, v3
	v_exp_f32_e32 v7, v7
	v_add_f32_e32 v4, 1.0, v4
	v_add_f32_e32 v1, 1.0, v1
	v_add_f32_e32 v5, 1.0, v5
	v_add_f32_e32 v0, 1.0, v0
	v_add_f32_e32 v2, 1.0, v2
	v_rcp_f32_e32 v13, v4
	v_rcp_f32_e32 v14, v1
	v_rcp_f32_e32 v15, v5
	v_add_f32_e32 v6, 1.0, v6
	v_add_f32_e32 v3, 1.0, v3
	v_add_f32_e32 v7, 1.0, v7
	v_rcp_f32_e32 v12, v0
	v_rcp_f32_e32 v16, v2
	v_rcp_f32_e32 v17, v6
	v_rcp_f32_e32 v18, v3
	v_rcp_f32_e32 v19, v7
	v_add_f32_e32 v1, -1.0, v13
	v_add_f32_e32 v2, -1.0, v14
	v_add_f32_e32 v3, -1.0, v15
	v_lshlrev_b32_e32 v34, 16, v10
	v_and_b32_e32 v35, 0xffff0000, v10
	v_add_f32_e32 v0, -1.0, v12
	v_add_f32_e32 v4, -1.0, v16
	v_fma_f32 v1, v24, v1, 1.0
	v_fma_f32 v2, v21, v2, 1.0
	v_fma_f32 v3, v25, v3, 1.0
	v_lshlrev_b32_e32 v30, 16, v8
	v_lshlrev_b32_e32 v32, 16, v9
	v_add_f32_e32 v5, -1.0, v17
	v_add_f32_e32 v6, -1.0, v18
	v_add_f32_e32 v7, -1.0, v19
	v_fma_f32 v0, v20, v0, 1.0
	v_fma_f32 v4, v22, v4, 1.0
	v_mul_f32_e32 v8, v1, v34
	v_mul_f32_e32 v1, v2, v31
	v_mul_f32_e32 v2, v3, v35
	v_and_b32_e32 v33, 0xffff0000, v9
	v_lshlrev_b32_e32 v36, 16, v11
	v_and_b32_e32 v37, 0xffff0000, v11
	v_fma_f32 v5, v26, v5, 1.0
	v_fma_f32 v6, v23, v6, 1.0
	v_fma_f32 v7, v27, v7, 1.0
	v_mul_f32_e32 v0, v0, v30
	v_mul_f32_e32 v3, v4, v32
	v_cvt_pk_bf16_f32 v2, v8, v2
	v_lshl_add_u32 v8, v80, 3, s24
	v_mul_f32_e32 v4, v5, v36
	v_mul_f32_e32 v5, v6, v33
	v_mul_f32_e32 v6, v7, v37
	v_cvt_pk_bf16_f32 v0, v0, v1
	v_cvt_pk_bf16_f32 v1, v3, v5
	v_cvt_pk_bf16_f32 v3, v4, v6
	global_store_dwordx4 v[28:29], v[0:3], off offset:1024
	v_ashrrev_i32_e32 v9, 31, v8
	s_nop 1
	v_mov_b32_e32 v0, v184
	v_mov_b32_e32 v1, v185
	v_mov_b32_e32 v2, v186
	v_mov_b32_e32 v3, v187
	s_nop 1
	v_mov_b32_e32 v4, v188
	v_mov_b32_e32 v5, v189
	v_mov_b32_e32 v6, v190
	v_mov_b32_e32 v7, v191
	v_lshl_add_u64 v[8:9], v[8:9], 2, s[4:5]
	s_nop 1
	v_mov_b32_e32 v20, v235
	v_lshlrev_b64 v[8:9], 9, v[80:81]
	v_lshl_add_u64 v[8:9], v[8:9], 0, v[78:79]
	v_lshlrev_b64 v[8:9], 1, v[8:9]
	v_lshl_add_u64 v[10:11], s[50:51], 0, v[8:9]
	v_lshl_add_u64 v[8:9], s[62:63], 0, v[8:9]
	s_mov_b64 s[24:25], s[0:1]
	v_mul_f32_e32 v0, v0, v30
	v_mul_f32_e32 v4, v4, v34
	v_mul_f32_e32 v1, v1, v31
	v_mul_f32_e32 v5, v5, v35
	v_mul_f32_e32 v2, v2, v32
	v_mul_f32_e32 v6, v6, v36
	v_mul_f32_e32 v3, v3, v33
	v_mul_f32_e32 v7, v7, v37
	v_mul_f32_e32 v21, v0, v20
	v_mul_f32_e32 v4, v20, v4
	v_mul_f32_e32 v22, v1, v20
	v_mul_f32_e32 v5, v20, v5
	v_mul_f32_e32 v23, v2, v20
	v_mul_f32_e32 v6, v20, v6
	v_mul_f32_e32 v24, v3, v20
	v_mul_f32_e32 v7, v20, v7
	v_cvt_pk_bf16_f32 v0, v21, v22
	v_cvt_pk_bf16_f32 v1, v23, v24
	v_cvt_pk_bf16_f32 v2, v4, v5
	v_cvt_pk_bf16_f32 v3, v6, v7
	v_mul_f32_e64 v12, v12, -v21
	v_mul_f32_e64 v14, v14, -v22
	v_mul_f32_e64 v16, v16, -v23
	v_mul_f32_e64 v18, v18, -v24
	v_mul_f32_e64 v4, v13, -v4
	v_mul_f32_e64 v5, v15, -v5
	v_mul_f32_e64 v6, v17, -v6
	v_mul_f32_e64 v7, v19, -v7
	global_store_dwordx4 v[10:11], v[0:3], off
	s_nop 1
	v_cvt_pk_bf16_f32 v0, v12, v14
	v_cvt_pk_bf16_f32 v1, v16, v18
	v_cvt_pk_bf16_f32 v2, v4, v5
	v_cvt_pk_bf16_f32 v3, v6, v7
	global_store_dwordx4 v[8:9], v[0:3], off
	s_cbranch_vccz .LBB0_472

; #define PG8_STAGE(bufoff, gbase, voff) do { _Pragma("unroll") for (int _i = 0; _i < 2; ++_i) \
;         __builtin_amdgcn_global_load_lds((const unsigned*)((const char*)(gbase) + (voff)[_i]), (PG8_LAS unsigned*)(lds + (bufoff) + ldsw + _i * 8192), 16, 0, 0); } while (0)
; #define PG8_LDA(dst, b, h) do { _Pragma("unroll") for (int m = 0; m < 4; ++m) _Pragma("unroll") for (int k = 0; k < 2; ++k) dst[m][k] = *(const PG8_LAS bf16x8*)(lds + PG8_SA(b, h) + aoff + m * 2048 + k * 1024); } while (0)
; #define PG8_LDB(dst, b, h) do { _Pragma("unroll") for (int n = 0; n < 2; ++n) _Pragma("unroll") for (int k = 0; k < 2; ++k) dst[n][k] = *(const PG8_LAS bf16x8*)(lds + PG8_SB(b, h) + boff + n * 2048 + k * 1024); } while (0)
; #define PG8_MMA(ai, bj, At, Bt) do { __builtin_amdgcn_s_setprio(1); _Pragma("unroll") for (int m = 0; m < 4; ++m) _Pragma("unroll") for (int n = 0; n < 2; ++n) _Pragma("unroll") for (int k = 0; k < 2; ++k) \
;         acc[ai][bj][m][n] = __builtin_amdgcn_mfma_f32_16x16x32_bf16(Bt[n][k], At[m][k], acc[ai][bj][m][n], 0, 0, 0); __builtin_amdgcn_s_setprio(0); } while (0)
; #define PG8_WAIT_V(n) asm volatile("s_waitcnt vmcnt(" #n ")" ::: "memory")
; #define PG8_WAIT_L(n) asm volatile("s_waitcnt lgkmcnt(" #n ")" ::: "memory")
; #define PG8_BAR __builtin_amdgcn_s_barrier()
; #define PG8_SCHED __builtin_amdgcn_sched_barrier(0)
; template <class Epi, class Sched>
; __device__ __forceinline__ void gemm_phase(PG8_LAS unsigned char* lds, const Gemm g, const Sched& S, const Epi& E) {
;     ...
;             PG8_LDB(B0, 0, 0); PG8_SCHED; PG8_LDA(At, 0, 0); PG8_STAGE(PG8_SA(1, 1), a1 + hstep, voffA);
;             PG8_WAIT_L(8); PG8_BAR; PG8_WAIT_L(0); PG8_MMA(0, 0, At, B0); PG8_BAR; PG8_SCHED;
;             PG8_LDB(B1, 0, 1); PG8_STAGE(PG8_SB(0, 0), b2, voffB);
;             PG8_BAR; PG8_WAIT_L(0); PG8_MMA(0, 1, At, B1); PG8_BAR;
;             PG8_LDA(At, 0, 1); PG8_STAGE(PG8_SA(0, 0), a2, voffA);
;             PG8_BAR; PG8_WAIT_L(0); PG8_MMA(1, 0, At, B0); PG8_BAR; PG8_SCHED;
;             PG8_STAGE(PG8_SB(0, 1), b2 + hstep, voffB);
;             PG8_WAIT_V(6); PG8_BAR; PG8_MMA(1, 1, At, B1); PG8_BAR;
;             PG8_LDB(B0, 1, 0); PG8_SCHED; PG8_LDA(At, 1, 0); PG8_STAGE(PG8_SA(0, 1), a2 + hstep, voffA);
;             PG8_WAIT_L(8); PG8_BAR; PG8_WAIT_L(0); PG8_MMA(0, 0, At, B0); PG8_BAR; PG8_SCHED;
.LBB0_1150:
	ds_read_b128 v[48:51], v167
	ds_read_b128 v[56:59], v167 offset:1024
	ds_read_b128 v[64:67], v167 offset:2048
	ds_read_b128 v[68:71], v167 offset:3072
	s_add_u32 s26, s24, 0xfffc0080
	s_addc_u32 s27, s25, -1
	s_cmp_eq_u32 s53, 12
	s_cselect_b32 s29, s15, s27
	s_cselect_b32 s28, s21, s26
	s_cselect_b32 s27, s13, s52
	s_cselect_b32 s26, s50, s51
	v_lshl_add_u64 v[198:199], s[24:25], 0, v[152:153]
	s_add_i32 m0, s23, 0xc000
	ds_read_b128 v[160:163], v168
	ds_read_b128 v[170:173], v168 offset:1024
	ds_read_b128 v[174:177], v168 offset:2048
	ds_read_b128 v[178:181], v168 offset:3072
	ds_read_b128 v[182:185], v168 offset:4096
	ds_read_b128 v[186:189], v168 offset:5120
	ds_read_b128 v[190:193], v168 offset:6144
	ds_read_b128 v[194:197], v168 offset:7168
	global_load_lds_dwordx4 v[198:199], off
	v_lshl_add_u64 v[198:199], s[24:25], 0, v[154:155]
	s_add_i32 m0, s23, 0xe000
	s_nop 0
	global_load_lds_dwordx4 v[198:199], off
	s_waitcnt lgkmcnt(8)
	s_barrier
	s_waitcnt lgkmcnt(0)
	v_mfma_f32_16x16x32_bf16 v[140:143], v[48:51], v[160:163], v[140:143]
	v_mfma_f32_16x16x32_bf16 v[136:139], v[64:67], v[160:163], v[136:139]
	v_mfma_f32_16x16x32_bf16 v[124:127], v[48:51], v[174:177], v[124:127]
	v_mfma_f32_16x16x32_bf16 v[120:123], v[64:67], v[174:177], v[120:123]
	v_mfma_f32_16x16x32_bf16 v[108:111], v[48:51], v[182:185], v[108:111]
	v_mfma_f32_16x16x32_bf16 v[104:107], v[64:67], v[182:185], v[104:107]
	v_mfma_f32_16x16x32_bf16 v[92:95], v[48:51], v[190:193], v[92:95]
	v_mfma_f32_16x16x32_bf16 v[88:91], v[64:67], v[190:193], v[88:91]
	v_mfma_f32_16x16x32_bf16 v[140:143], v[56:59], v[170:173], v[140:143]
	v_mfma_f32_16x16x32_bf16 v[136:139], v[68:71], v[170:173], v[136:139]
	v_mfma_f32_16x16x32_bf16 v[124:127], v[56:59], v[178:181], v[124:127]
	v_mfma_f32_16x16x32_bf16 v[120:123], v[68:71], v[178:181], v[120:123]
	v_mfma_f32_16x16x32_bf16 v[108:111], v[56:59], v[186:189], v[108:111]
	v_mfma_f32_16x16x32_bf16 v[104:107], v[68:71], v[186:189], v[104:107]
	v_mfma_f32_16x16x32_bf16 v[92:95], v[56:59], v[194:197], v[92:95]
	v_mfma_f32_16x16x32_bf16 v[88:91], v[68:71], v[194:197], v[88:91]
	s_barrier
	s_add_i32 s60, s46, s34
	v_lshl_add_u64 v[214:215], s[26:27], 0, v[146:147]
	s_mov_b32 m0, s60
	ds_read_b128 v[198:201], v169
	ds_read_b128 v[202:205], v169 offset:1024
	ds_read_b128 v[206:209], v169 offset:2048
	ds_read_b128 v[210:213], v169 offset:3072
	global_load_lds_dwordx4 v[214:215], off
	v_lshl_add_u64 v[216:217], s[26:27], 0, v[150:151]
	s_add_i32 m0, s60, 0x2000
	s_nop 0
	global_load_lds_dwordx4 v[216:217], off
	s_barrier
	s_waitcnt lgkmcnt(0)
	v_mfma_f32_16x16x32_bf16 v[132:135], v[198:201], v[160:163], v[132:135]
	v_mfma_f32_16x16x32_bf16 v[128:131], v[206:209], v[160:163], v[128:131]
	v_mfma_f32_16x16x32_bf16 v[116:119], v[198:201], v[174:177], v[116:119]
	v_mfma_f32_16x16x32_bf16 v[112:115], v[206:209], v[174:177], v[112:115]
	v_mfma_f32_16x16x32_bf16 v[100:103], v[198:201], v[182:185], v[100:103]
	v_mfma_f32_16x16x32_bf16 v[96:99], v[206:209], v[182:185], v[96:99]
	v_mfma_f32_16x16x32_bf16 v[84:87], v[198:201], v[190:193], v[84:87]
	v_mfma_f32_16x16x32_bf16 v[80:83], v[206:209], v[190:193], v[80:83]
	v_mfma_f32_16x16x32_bf16 v[132:135], v[202:205], v[170:173], v[132:135]
	v_mfma_f32_16x16x32_bf16 v[128:131], v[210:213], v[170:173], v[128:131]
	v_mfma_f32_16x16x32_bf16 v[116:119], v[202:205], v[178:181], v[116:119]
	v_mfma_f32_16x16x32_bf16 v[112:115], v[210:213], v[178:181], v[112:115]
	v_mfma_f32_16x16x32_bf16 v[100:103], v[202:205], v[186:189], v[100:103]
	v_mfma_f32_16x16x32_bf16 v[96:99], v[210:213], v[186:189], v[96:99]
	v_mfma_f32_16x16x32_bf16 v[84:87], v[202:205], v[194:197], v[84:87]
	v_mfma_f32_16x16x32_bf16 v[80:83], v[210:213], v[194:197], v[80:83]
	s_mov_b32 m0, s23
	v_lshl_add_u64 v[218:219], s[28:29], 0, v[144:145]
	s_barrier
	ds_read_b128 v[160:163], v168 offset:16384
	ds_read_b128 v[170:173], v168 offset:17408
	ds_read_b128 v[174:177], v168 offset:18432
	ds_read_b128 v[178:181], v168 offset:19456
	ds_read_b128 v[182:185], v168 offset:20480
	ds_read_b128 v[186:189], v168 offset:21504
	ds_read_b128 v[190:193], v168 offset:22528
	ds_read_b128 v[194:197], v168 offset:23552
	global_load_lds_dwordx4 v[218:219], off
	v_lshl_add_u64 v[220:221], s[28:29], 0, v[148:149]
	s_mov_b32 m0, s35
	s_nop 0
	global_load_lds_dwordx4 v[220:221], off
	s_barrier
	s_waitcnt lgkmcnt(0)
	v_mfma_f32_16x16x32_bf16 v[76:79], v[48:51], v[160:163], v[76:79]
	v_mfma_f32_16x16x32_bf16 v[72:75], v[64:67], v[160:163], v[72:75]
	v_mfma_f32_16x16x32_bf16 v[44:47], v[48:51], v[174:177], v[44:47]
	v_mfma_f32_16x16x32_bf16 v[40:43], v[64:67], v[174:177], v[40:43]
	v_mfma_f32_16x16x32_bf16 v[28:31], v[48:51], v[182:185], v[28:31]
	v_mfma_f32_16x16x32_bf16 v[24:27], v[64:67], v[182:185], v[24:27]
	v_mfma_f32_16x16x32_bf16 v[12:15], v[48:51], v[190:193], v[12:15]
	v_mfma_f32_16x16x32_bf16 v[8:11], v[64:67], v[190:193], v[8:11]
	v_mfma_f32_16x16x32_bf16 v[76:79], v[56:59], v[170:173], v[76:79]
	v_mfma_f32_16x16x32_bf16 v[72:75], v[68:71], v[170:173], v[72:75]
	v_mfma_f32_16x16x32_bf16 v[44:47], v[56:59], v[178:181], v[44:47]
	v_mfma_f32_16x16x32_bf16 v[40:43], v[68:71], v[178:181], v[40:43]
	v_mfma_f32_16x16x32_bf16 v[28:31], v[56:59], v[186:189], v[28:31]
	v_mfma_f32_16x16x32_bf16 v[24:27], v[68:71], v[186:189], v[24:27]
	v_mfma_f32_16x16x32_bf16 v[12:15], v[56:59], v[194:197], v[12:15]
	v_mfma_f32_16x16x32_bf16 v[8:11], v[68:71], v[194:197], v[8:11]
	s_barrier
	s_add_u32 s60, s26, 0x40000
	s_addc_u32 s61, s27, 0
	s_add_i32 s62, s47, s34
	v_lshl_add_u64 v[48:49], s[60:61], 0, v[146:147]
	s_mov_b32 m0, s62
	s_nop 0
	global_load_lds_dwordx4 v[48:49], off
	v_lshl_add_u64 v[48:49], s[60:61], 0, v[150:151]
	s_add_i32 m0, s62, 0x2000
	s_nop 0
	global_load_lds_dwordx4 v[48:49], off
	s_waitcnt vmcnt(6)
	s_barrier
; #define PG8_STAGE(bufoff, gbase, voff) do { _Pragma("unroll") for (int _i = 0; _i < 2; ++_i) \
;         __builtin_amdgcn_global_load_lds((const unsigned*)((const char*)(gbase) + (voff)[_i]), (PG8_LAS unsigned*)(lds + (bufoff) + ldsw + _i * 8192), 16, 0, 0); } while (0)
; #define PG8_LDA(dst, b, h) do { _Pragma("unroll") for (int m = 0; m < 4; ++m) _Pragma("unroll") for (int k = 0; k < 2; ++k) dst[m][k] = *(const PG8_LAS bf16x8*)(lds + PG8_SA(b, h) + aoff + m * 2048 + k * 1024); } while (0)
; #define PG8_LDB(dst, b, h) do { _Pragma("unroll") for (int n = 0; n < 2; ++n) _Pragma("unroll") for (int k = 0; k < 2; ++k) dst[n][k] = *(const PG8_LAS bf16x8*)(lds + PG8_SB(b, h) + boff + n * 2048 + k * 1024); } while (0)
; #define PG8_MMA(ai, bj, At, Bt) do { __builtin_amdgcn_s_setprio(1); _Pragma("unroll") for (int m = 0; m < 4; ++m) _Pragma("unroll") for (int n = 0; n < 2; ++n) _Pragma("unroll") for (int k = 0; k < 2; ++k) \
;         acc[ai][bj][m][n] = __builtin_amdgcn_mfma_f32_16x16x32_bf16(Bt[n][k], At[m][k], acc[ai][bj][m][n], 0, 0, 0); __builtin_amdgcn_s_setprio(0); } while (0)
; #define PG8_WAIT_V(n) asm volatile("s_waitcnt vmcnt(" #n ")" ::: "memory")
; #define PG8_WAIT_L(n) asm volatile("s_waitcnt lgkmcnt(" #n ")" ::: "memory")
; #define PG8_BAR __builtin_amdgcn_s_barrier()
; #define PG8_SCHED __builtin_amdgcn_sched_barrier(0)
; template <class Epi, class Sched>
; __device__ __forceinline__ void gemm_phase(PG8_LAS unsigned char* lds, const Gemm g, const Sched& S, const Epi& E) {
;     ...
;             PG8_WAIT_V(6); PG8_BAR; PG8_MMA(1, 1, At, B1); PG8_BAR;
;             PG8_LDB(B0, 1, 0); PG8_SCHED; PG8_LDA(At, 1, 0); PG8_STAGE(PG8_SA(0, 1), a2 + hstep, voffA);
;             PG8_WAIT_L(8); PG8_BAR; PG8_WAIT_L(0); PG8_MMA(0, 0, At, B0); PG8_BAR; PG8_SCHED;
;             PG8_LDB(B1, 1, 1); PG8_STAGE(PG8_SB(1, 0), b3, voffB);
;             PG8_BAR; PG8_WAIT_L(0); PG8_MMA(0, 1, At, B1); PG8_BAR;
;             PG8_LDA(At, 1, 1); PG8_STAGE(PG8_SA(1, 0), a3, voffA);
;             PG8_BAR; PG8_WAIT_L(0); PG8_MMA(1, 0, At, B0); PG8_BAR; PG8_SCHED;
	v_mfma_f32_16x16x32_bf16 v[52:55], v[206:209], v[160:163], v[52:55]
	v_mfma_f32_16x16x32_bf16 v[36:39], v[198:201], v[174:177], v[36:39]
	v_mfma_f32_16x16x32_bf16 v[32:35], v[206:209], v[174:177], v[32:35]
	v_mfma_f32_16x16x32_bf16 v[20:23], v[198:201], v[182:185], v[20:23]
	v_mfma_f32_16x16x32_bf16 v[16:19], v[206:209], v[182:185], v[16:19]
	v_mfma_f32_16x16x32_bf16 v[4:7], v[198:201], v[190:193], v[4:7]
	v_mfma_f32_16x16x32_bf16 v[0:3], v[206:209], v[190:193], v[0:3]
	v_mfma_f32_16x16x32_bf16 v[48:51], v[198:201], v[160:163], v[60:63]
	v_mfma_f32_16x16x32_bf16 v[52:55], v[210:213], v[170:173], v[52:55]
	v_mfma_f32_16x16x32_bf16 v[36:39], v[202:205], v[178:181], v[36:39]
	v_mfma_f32_16x16x32_bf16 v[32:35], v[210:213], v[178:181], v[32:35]
	v_mfma_f32_16x16x32_bf16 v[20:23], v[202:205], v[186:189], v[20:23]
	v_mfma_f32_16x16x32_bf16 v[16:19], v[210:213], v[186:189], v[16:19]
	v_mfma_f32_16x16x32_bf16 v[4:7], v[202:205], v[194:197], v[4:7]
	v_mfma_f32_16x16x32_bf16 v[0:3], v[210:213], v[194:197], v[0:3]
	v_mfma_f32_16x16x32_bf16 v[48:51], v[202:205], v[170:173], v[48:51]
	s_add_i32 s60, 0, 0x18000
	v_add_u32_e32 v68, s60, v165
	s_barrier
	ds_read_b128 v[56:59], v68
	ds_read_b128 v[60:63], v68 offset:1024
	ds_read_b128 v[64:67], v68 offset:2048
	ds_read_b128 v[68:71], v68 offset:3072
	s_add_u32 s28, s28, 0x40000
	s_addc_u32 s29, s29, 0
	s_mov_b32 m0, s36
	v_lshl_add_u64 v[198:199], s[28:29], 0, v[144:145]
	ds_read_b128 v[160:163], v168 offset:32768
	ds_read_b128 v[170:173], v168 offset:33792
	ds_read_b128 v[174:177], v168 offset:34816
	ds_read_b128 v[178:181], v168 offset:35840
	ds_read_b128 v[182:185], v168 offset:36864
	ds_read_b128 v[186:189], v168 offset:37888
	ds_read_b128 v[190:193], v168 offset:38912
	ds_read_b128 v[194:197], v168 offset:39936
	global_load_lds_dwordx4 v[198:199], off
	v_lshl_add_u64 v[198:199], s[28:29], 0, v[148:149]
	s_mov_b32 m0, s37
	s_nop 0
	global_load_lds_dwordx4 v[198:199], off
	s_waitcnt lgkmcnt(8)
	s_barrier
	s_waitcnt lgkmcnt(0)
	v_mfma_f32_16x16x32_bf16 v[140:143], v[56:59], v[160:163], v[140:143]
	v_mfma_f32_16x16x32_bf16 v[136:139], v[64:67], v[160:163], v[136:139]
	v_mfma_f32_16x16x32_bf16 v[124:127], v[56:59], v[174:177], v[124:127]
	v_mfma_f32_16x16x32_bf16 v[120:123], v[64:67], v[174:177], v[120:123]
	v_mfma_f32_16x16x32_bf16 v[108:111], v[56:59], v[182:185], v[108:111]
	v_mfma_f32_16x16x32_bf16 v[104:107], v[64:67], v[182:185], v[104:107]
	v_mfma_f32_16x16x32_bf16 v[92:95], v[56:59], v[190:193], v[92:95]
	v_mfma_f32_16x16x32_bf16 v[88:91], v[64:67], v[190:193], v[88:91]
	v_mfma_f32_16x16x32_bf16 v[140:143], v[60:63], v[170:173], v[140:143]
	v_mfma_f32_16x16x32_bf16 v[136:139], v[68:71], v[170:173], v[136:139]
	v_mfma_f32_16x16x32_bf16 v[124:127], v[60:63], v[178:181], v[124:127]
	v_mfma_f32_16x16x32_bf16 v[120:123], v[68:71], v[178:181], v[120:123]
	v_mfma_f32_16x16x32_bf16 v[108:111], v[60:63], v[186:189], v[108:111]
	v_mfma_f32_16x16x32_bf16 v[104:107], v[68:71], v[186:189], v[104:107]
	v_mfma_f32_16x16x32_bf16 v[92:95], v[60:63], v[194:197], v[92:95]
	v_mfma_f32_16x16x32_bf16 v[88:91], v[68:71], v[194:197], v[88:91]
	s_barrier
	s_add_i32 s28, 0, 0x1c000
	s_add_i32 s29, s60, s34
	v_add_u32_e32 v210, s28, v165
	v_lshl_add_u64 v[214:215], v[214:215], 0, s[10:11]
	s_mov_b32 m0, s29
	ds_read_b128 v[198:201], v210
	ds_read_b128 v[202:205], v210 offset:1024
	ds_read_b128 v[206:209], v210 offset:2048
	ds_read_b128 v[210:213], v210 offset:3072
	global_load_lds_dwordx4 v[214:215], off
	v_lshl_add_u64 v[214:215], v[216:217], 0, s[10:11]
	s_add_i32 m0, s29, 0x2000
	s_nop 0
	global_load_lds_dwordx4 v[214:215], off
	s_barrier
	s_waitcnt lgkmcnt(0)
	v_mfma_f32_16x16x32_bf16 v[132:135], v[198:201], v[160:163], v[132:135]
	v_mfma_f32_16x16x32_bf16 v[128:131], v[206:209], v[160:163], v[128:131]
	v_mfma_f32_16x16x32_bf16 v[116:119], v[198:201], v[174:177], v[116:119]
	v_mfma_f32_16x16x32_bf16 v[112:115], v[206:209], v[174:177], v[112:115]
	v_mfma_f32_16x16x32_bf16 v[100:103], v[198:201], v[182:185], v[100:103]
	v_mfma_f32_16x16x32_bf16 v[96:99], v[206:209], v[182:185], v[96:99]
	v_mfma_f32_16x16x32_bf16 v[84:87], v[198:201], v[190:193], v[84:87]
	v_mfma_f32_16x16x32_bf16 v[80:83], v[206:209], v[190:193], v[80:83]
	v_mfma_f32_16x16x32_bf16 v[132:135], v[202:205], v[170:173], v[132:135]
	v_mfma_f32_16x16x32_bf16 v[128:131], v[210:213], v[170:173], v[128:131]
	v_mfma_f32_16x16x32_bf16 v[116:119], v[202:205], v[178:181], v[116:119]
	v_mfma_f32_16x16x32_bf16 v[112:115], v[210:213], v[178:181], v[112:115]
	v_mfma_f32_16x16x32_bf16 v[100:103], v[202:205], v[186:189], v[100:103]
	v_mfma_f32_16x16x32_bf16 v[96:99], v[210:213], v[186:189], v[96:99]
	v_mfma_f32_16x16x32_bf16 v[84:87], v[202:205], v[194:197], v[84:87]
	v_mfma_f32_16x16x32_bf16 v[80:83], v[210:213], v[194:197], v[80:83]
	s_mov_b32 m0, s39
	v_lshl_add_u64 v[214:215], v[218:219], 0, s[10:11]
	s_barrier
	ds_read_b128 v[160:163], v168 offset:49152
	ds_read_b128 v[170:173], v168 offset:50176
	ds_read_b128 v[174:177], v168 offset:51200
	ds_read_b128 v[178:181], v168 offset:52224
	ds_read_b128 v[182:185], v168 offset:53248
	ds_read_b128 v[186:189], v168 offset:54272
	ds_read_b128 v[190:193], v168 offset:55296
	ds_read_b128 v[194:197], v168 offset:56320
	global_load_lds_dwordx4 v[214:215], off
	v_lshl_add_u64 v[214:215], v[220:221], 0, s[10:11]
	s_mov_b32 m0, s40
	s_nop 0
	global_load_lds_dwordx4 v[214:215], off
	s_barrier
; #define PG8_STAGE(bufoff, gbase, voff) do { _Pragma("unroll") for (int _i = 0; _i < 2; ++_i) \
;         __builtin_amdgcn_global_load_lds((const unsigned*)((const char*)(gbase) + (voff)[_i]), (PG8_LAS unsigned*)(lds + (bufoff) + ldsw + _i * 8192), 16, 0, 0); } while (0)
; #define PG8_MMA(ai, bj, At, Bt) do { __builtin_amdgcn_s_setprio(1); _Pragma("unroll") for (int m = 0; m < 4; ++m) _Pragma("unroll") for (int n = 0; n < 2; ++n) _Pragma("unroll") for (int k = 0; k < 2; ++k) \
;         acc[ai][bj][m][n] = __builtin_amdgcn_mfma_f32_16x16x32_bf16(Bt[n][k], At[m][k], acc[ai][bj][m][n], 0, 0, 0); __builtin_amdgcn_s_setprio(0); } while (0)
; #define PG8_WAIT_V(n) asm volatile("s_waitcnt vmcnt(" #n ")" ::: "memory")
; #define PG8_WAIT_L(n) asm volatile("s_waitcnt lgkmcnt(" #n ")" ::: "memory")
; #define PG8_BAR __builtin_amdgcn_s_barrier()
; #define PG8_SCHED __builtin_amdgcn_sched_barrier(0)
; __device__ __forceinline__ void unpack8(const u32x4 w, float (&f)[8]) { f[0] = bflo(w.x); f[1] = bfhi(w.x); f[2] = bflo(w.y); f[3] = bfhi(w.y); f[4] = bflo(w.z); f[5] = bfhi(w.z); f[6] = bflo(w.w); f[7] = bfhi(w.w); }
; template <class Epi, class Sched>
; __device__ __forceinline__ void gemm_phase(PG8_LAS unsigned char* lds, const Gemm g, const Sched& S, const Epi& E) {
;     ...
;             PG8_BAR; PG8_WAIT_L(0); PG8_MMA(1, 0, At, B0); PG8_BAR; PG8_SCHED;
;             PG8_STAGE(PG8_SB(1, 1), b3 + hstep, voffB);
;             PG8_WAIT_V(6); PG8_BAR; PG8_MMA(1, 1, At, B1); PG8_BAR;
;     __device__ __forceinline__ void operator()(const f32x4 (&acc)[2][2][4][2], const Unit& u, int wr, int wc, int fr, int fq) const {
;         const int row0 = u.pm * BM + wr * 64 + fr, col0 = u.pn * BM + wc * 32 + 8 * fq;
;         f32x4 bv[2][2];
; #pragma unroll
;         for (int bj = 0; bj < 2; ++bj)
; #pragma unroll
;             for (int n = 0; n < 2; ++n) bv[bj][n] = *(const f32x4*)(bias + col0 + bj * HALF + 4 * n);
; #pragma unroll
;         for (int ai = 0; ai < 2; ++ai)
; #pragma unroll
;             for (int m = 0; m < 4; ++m) { const int row = row0 + ai * HALF + m * 16; const size_t off = (size_t)row * DM + col0; float s = 0.f;
; #pragma unroll
;                 for (int bj = 0; bj < 2; ++bj) { float e[8], o[8]; unpack8(*(const u32x4*)(E + off + bj * HALF), e);
	s_waitcnt lgkmcnt(0)
	v_mfma_f32_16x16x32_bf16 v[76:79], v[56:59], v[160:163], v[76:79]
	v_mfma_f32_16x16x32_bf16 v[72:75], v[64:67], v[160:163], v[72:75]
	v_mfma_f32_16x16x32_bf16 v[44:47], v[56:59], v[174:177], v[44:47]
	v_mfma_f32_16x16x32_bf16 v[40:43], v[64:67], v[174:177], v[40:43]
	v_mfma_f32_16x16x32_bf16 v[28:31], v[56:59], v[182:185], v[28:31]
	v_mfma_f32_16x16x32_bf16 v[24:27], v[64:67], v[182:185], v[24:27]
	v_mfma_f32_16x16x32_bf16 v[12:15], v[56:59], v[190:193], v[12:15]
	v_mfma_f32_16x16x32_bf16 v[8:11], v[64:67], v[190:193], v[8:11]
	v_mfma_f32_16x16x32_bf16 v[76:79], v[60:63], v[170:173], v[76:79]
	v_mfma_f32_16x16x32_bf16 v[72:75], v[68:71], v[170:173], v[72:75]
	v_mfma_f32_16x16x32_bf16 v[44:47], v[60:63], v[178:181], v[44:47]
	v_mfma_f32_16x16x32_bf16 v[40:43], v[68:71], v[178:181], v[40:43]
	v_mfma_f32_16x16x32_bf16 v[28:31], v[60:63], v[186:189], v[28:31]
	v_mfma_f32_16x16x32_bf16 v[24:27], v[68:71], v[186:189], v[24:27]
	v_mfma_f32_16x16x32_bf16 v[12:15], v[60:63], v[194:197], v[12:15]
	v_mfma_f32_16x16x32_bf16 v[8:11], v[68:71], v[194:197], v[8:11]
	s_barrier
	s_add_u32 s26, s26, 0x40080
	s_addc_u32 s27, s27, 0
	s_add_i32 s28, s28, s34
	v_lshl_add_u64 v[56:57], s[26:27], 0, v[146:147]
	s_mov_b32 m0, s28
	s_nop 0
	global_load_lds_dwordx4 v[56:57], off
	v_lshl_add_u64 v[56:57], s[26:27], 0, v[150:151]
	s_add_i32 m0, s28, 0x2000
	s_nop 0
	global_load_lds_dwordx4 v[56:57], off
	s_waitcnt vmcnt(6)
	s_barrier
	v_mfma_f32_16x16x32_bf16 v[48:51], v[198:201], v[160:163], v[48:51]
	v_mfma_f32_16x16x32_bf16 v[60:63], v[202:205], v[170:173], v[48:51]
	v_mfma_f32_16x16x32_bf16 v[48:51], v[206:209], v[160:163], v[52:55]
	v_mfma_f32_16x16x32_bf16 v[36:39], v[198:201], v[174:177], v[36:39]
	v_mfma_f32_16x16x32_bf16 v[32:35], v[206:209], v[174:177], v[32:35]
	v_mfma_f32_16x16x32_bf16 v[20:23], v[198:201], v[182:185], v[20:23]
	v_mfma_f32_16x16x32_bf16 v[16:19], v[206:209], v[182:185], v[16:19]
	v_mfma_f32_16x16x32_bf16 v[4:7], v[198:201], v[190:193], v[4:7]
	v_mfma_f32_16x16x32_bf16 v[0:3], v[206:209], v[190:193], v[0:3]
	v_mfma_f32_16x16x32_bf16 v[52:55], v[210:213], v[170:173], v[48:51]
	v_mfma_f32_16x16x32_bf16 v[36:39], v[202:205], v[178:181], v[36:39]
	v_mfma_f32_16x16x32_bf16 v[32:35], v[210:213], v[178:181], v[32:35]
	v_mfma_f32_16x16x32_bf16 v[20:23], v[202:205], v[186:189], v[20:23]
	v_mfma_f32_16x16x32_bf16 v[16:19], v[210:213], v[186:189], v[16:19]
	v_mfma_f32_16x16x32_bf16 v[4:7], v[202:205], v[194:197], v[4:7]
	v_mfma_f32_16x16x32_bf16 v[0:3], v[210:213], v[194:197], v[0:3]
	s_add_i32 s53, s53, 2
	s_add_u32 s24, s24, 0x100
	s_addc_u32 s25, s25, 0
	s_add_u32 s51, s51, 0x100
	s_addc_u32 s52, s52, 0
	s_cmp_gt_u32 s53, 13
	s_barrier
	s_cbranch_scc0 .LBB0_1150
	v_lshl_add_u32 v162, s20, 8, v164
	v_lshl_or_b32 v160, s22, 8, v166
	v_ashrrev_i32_e32 v163, 31, v162
	v_ashrrev_i32_e32 v161, 31, v160
	v_lshlrev_b64 v[58:59], 10, v[162:163]
	v_lshl_add_u64 v[58:59], v[58:59], 0, v[160:161]
	v_lshl_add_u64 v[56:57], v[160:161], 2, s[54:55]
	v_lshlrev_b64 v[178:179], 1, v[58:59]
	global_load_dwordx4 v[68:71], v[56:57], off
	global_load_dwordx4 v[64:67], v[56:57], off offset:16
	global_load_dwordx4 v[48:51], v[56:57], off offset:512
	v_lshl_add_u64 v[58:59], s[8:9], 0, v[178:179]
	global_load_dwordx4 v[170:173], v[58:59], off
	global_load_dwordx4 v[174:177], v[58:59], off offset:256
	s_mov_b32 s98, 0x8000
	s_mov_b32 s99, 0
	v_lshl_add_u64 v[252:253], v[58:59], 0, s[98:99]
	global_load_dwordx4 v[188:191], v[252:253], off
	global_load_dwordx4 v[192:195], v[252:253], off offset:256
	s_mov_b32 s98, 0x10000
	s_mov_b32 s99, 0
	v_lshl_add_u64 v[252:253], v[58:59], 0, s[98:99]
	global_load_dwordx4 v[196:199], v[252:253], off
	global_load_dwordx4 v[200:203], v[252:253], off offset:256
	s_mov_b32 s98, 0x18000
	s_mov_b32 s99, 0
	v_lshl_add_u64 v[252:253], v[58:59], 0, s[98:99]
	global_load_dwordx4 v[204:207], v[252:253], off
	global_load_dwordx4 v[208:211], v[252:253], off offset:256
	s_mov_b32 s98, 0x40000
	s_mov_b32 s99, 0
	v_lshl_add_u64 v[252:253], v[58:59], 0, s[98:99]
	global_load_dwordx4 v[212:215], v[252:253], off
	global_load_dwordx4 v[216:219], v[252:253], off offset:256
	s_mov_b32 s98, 0x48000
	s_mov_b32 s99, 0
	v_lshl_add_u64 v[252:253], v[58:59], 0, s[98:99]
	global_load_dwordx4 v[220:223], v[252:253], off
	global_load_dwordx4 v[224:227], v[252:253], off offset:256
	s_mov_b32 s98, 0x50000
	s_mov_b32 s99, 0
	v_lshl_add_u64 v[252:253], v[58:59], 0, s[98:99]
	global_load_dwordx4 v[228:231], v[252:253], off
	global_load_dwordx4 v[232:235], v[252:253], off offset:256
	s_mov_b32 s98, 0x58000
	s_mov_b32 s99, 0
	v_lshl_add_u64 v[252:253], v[58:59], 0, s[98:99]
	global_load_dwordx4 v[236:239], v[252:253], off
	global_load_dwordx4 v[240:243], v[252:253], off offset:256
	s_nop 0
	global_load_dwordx4 v[56:59], v[56:57], off offset:528
	v_lshl_add_u64 v[178:179], s[48:49], 0, v[178:179]
	s_waitcnt vmcnt(0)
; __device__ __forceinline__ void unpack8(const u32x4 w, float (&f)[8]) { f[0] = bflo(w.x); f[1] = bfhi(w.x); f[2] = bflo(w.y); f[3] = bfhi(w.y); f[4] = bflo(w.z); f[5] = bfhi(w.z); f[6] = bflo(w.w); f[7] = bfhi(w.w); }
; __device__ __forceinline__ u32x4 pack8(const float (&f)[8]) { u32x4 o; o.x = pk2(f[0], f[1]); o.y = pk2(f[2], f[3]); o.z = pk2(f[4], f[5]); o.w = pk2(f[6], f[7]); return o; }
; __device__ __forceinline__ float sigmoidf_(float x) { return __builtin_amdgcn_rcpf(1.0f + __expf(-x)); }
;     __device__ __forceinline__ void operator()(const f32x4 (&acc)[2][2][4][2], const Unit& u, int wr, int wc, int fr, int fq) const {
;     ...
;             for (int m = 0; m < 4; ++m) { const int row = row0 + ai * HALF + m * 16; const size_t off = (size_t)row * DM + col0; float s = 0.f;
; #pragma unroll
;                 for (int bj = 0; bj < 2; ++bj) { float e[8], o[8]; unpack8(*(const u32x4*)(E + off + bj * HALF), e);
; #pragma unroll
;                     for (int n = 0; n < 2; ++n) { const f32x4 v = acc[ai][bj][m][n] + bv[bj][n];
; #pragma unroll
;                         for (int j = 0; j < 4; ++j) { o[4 * n + j] = sigmoidf_(v[j]) * e[4 * n + j]; s += o[4 * n + j] * o[4 * n + j]; } }
;                     *(u32x4*)(C + off + bj * HALF) = pack8(o); }
;                 { auto r16 = __builtin_amdgcn_permlane16_swap(__float_as_uint(s), __float_as_uint(s), false, false); s = __uint_as_float(r16[0]) + __uint_as_float(r16[1]);
;                   auto r32 = __builtin_amdgcn_permlane32_swap(__float_as_uint(s), __float_as_uint(s), false, false); s = __uint_as_float(r32[0]) + __uint_as_float(r32[1]); }
;                 if (fq == 0) atomicAdd(ss + row, s); }
	v_add_f32_e32 v141, v141, v69
	v_add_f32_e32 v140, v140, v68
	v_mul_f32_e32 v141, 0xbfb8aa3b, v141
	v_add_f32_e32 v142, v142, v70
	v_add_f32_e32 v136, v136, v64
	v_mul_f32_e32 v140, 0xbfb8aa3b, v140
	v_exp_f32_e32 v141, v141
	v_add_f32_e32 v143, v143, v71
	v_add_f32_e32 v137, v137, v65
	v_add_f32_e32 v138, v138, v66
	v_add_f32_e32 v139, v139, v67
	v_mul_f32_e32 v142, 0xbfb8aa3b, v142
	v_mul_f32_e32 v136, 0xbfb8aa3b, v136
	v_exp_f32_e32 v140, v140
	v_add_f32_e32 v128, v128, v56
	v_mul_f32_e32 v143, 0xbfb8aa3b, v143
	v_mul_f32_e32 v137, 0xbfb8aa3b, v137
	v_mul_f32_e32 v138, 0xbfb8aa3b, v138
	v_mul_f32_e32 v139, 0xbfb8aa3b, v139
	v_exp_f32_e32 v142, v142
	v_exp_f32_e32 v136, v136
	v_mul_f32_e32 v128, 0xbfb8aa3b, v128
	v_exp_f32_e32 v143, v143
	v_exp_f32_e32 v137, v137
	v_exp_f32_e32 v138, v138
	v_exp_f32_e32 v139, v139
	v_exp_f32_e32 v128, v128
	v_add_f32_e32 v141, 1.0, v141
	v_add_f32_e32 v140, 1.0, v140
	v_rcp_f32_e32 v141, v141
	v_add_f32_e32 v132, v132, v48
	v_add_f32_e32 v142, 1.0, v142
	v_add_f32_e32 v136, 1.0, v136
	v_rcp_f32_e32 v140, v140
	v_add_f32_e32 v129, v129, v57
	v_add_f32_e32 v133, v133, v49
	v_mul_f32_e32 v132, 0xbfb8aa3b, v132
	v_add_f32_e32 v143, 1.0, v143
	v_add_f32_e32 v137, 1.0, v137
	v_add_f32_e32 v138, 1.0, v138
	v_add_f32_e32 v139, 1.0, v139
	v_rcp_f32_e32 v142, v142
	v_rcp_f32_e32 v136, v136
	v_add_f32_e32 v128, 1.0, v128
	v_mul_f32_e32 v129, 0xbfb8aa3b, v129
	v_mul_f32_e32 v133, 0xbfb8aa3b, v133
	v_exp_f32_e32 v132, v132
	v_lshlrev_b32_e32 v180, 16, v170
	v_and_b32_e32 v170, 0xffff0000, v170
	v_rcp_f32_e32 v143, v143
	v_rcp_f32_e32 v137, v137
	v_rcp_f32_e32 v138, v138
	v_rcp_f32_e32 v139, v139
	v_add_f32_e32 v134, v134, v50
	v_rcp_f32_e32 v128, v128
	v_exp_f32_e32 v129, v129
	v_exp_f32_e32 v133, v133
	v_mul_f32_e32 v141, v141, v170
	v_mul_f32_e32 v134, 0xbfb8aa3b, v134
	v_add_f32_e32 v135, v135, v51
	v_lshlrev_b32_e32 v181, 16, v171
	v_lshlrev_b32_e32 v182, 16, v172
	v_mul_f32_e32 v140, v140, v180
	v_mul_f32_e32 v180, v141, v141
	v_exp_f32_e32 v134, v134
	v_mul_f32_e32 v135, 0xbfb8aa3b, v135
	v_and_b32_e32 v171, 0xffff0000, v171
	v_and_b32_e32 v172, 0xffff0000, v172
	v_lshlrev_b32_e32 v183, 16, v173
	v_and_b32_e32 v173, 0xffff0000, v173
	v_lshlrev_b32_e32 v186, 16, v176
	v_mul_f32_e32 v142, v142, v181
	v_mul_f32_e32 v170, v136, v182
	v_cvt_pk_bf16_f32 v136, v140, v141
	v_fmac_f32_e32 v180, v140, v140
	v_exp_f32_e32 v135, v135
	v_add_f32_e32 v132, 1.0, v132
	v_mul_f32_e32 v143, v143, v171
	v_mul_f32_e32 v171, v137, v172
	v_mul_f32_e32 v172, v138, v183
	v_mul_f32_e32 v173, v139, v173
	v_cvt_pk_bf16_f32 v137, v142, v143
	v_cvt_pk_bf16_f32 v138, v170, v171
	v_cvt_pk_bf16_f32 v139, v172, v173
	global_store_dwordx4 v[178:179], v[136:139], off
	v_fmac_f32_e32 v180, v142, v142
	v_add_f32_e32 v133, 1.0, v133
	v_mul_f32_e32 v136, v128, v186
	v_add_f32_e32 v128, 1.0, v129
	v_add_f32_e32 v129, v130, v58
	v_rcp_f32_e32 v132, v132
	v_fmac_f32_e32 v180, v143, v143
	v_mul_f32_e32 v129, 0xbfb8aa3b, v129
	v_add_f32_e32 v130, v131, v59
	v_rcp_f32_e32 v133, v133
	v_fmac_f32_e32 v180, v170, v170
	v_add_f32_e32 v134, 1.0, v134
	v_rcp_f32_e32 v128, v128
	v_exp_f32_e32 v129, v129
	v_mul_f32_e32 v130, 0xbfb8aa3b, v130
	v_fmac_f32_e32 v180, v171, v171
	v_rcp_f32_e32 v134, v134
	v_add_f32_e32 v135, 1.0, v135
	v_exp_f32_e32 v130, v130
	v_lshlrev_b32_e32 v184, 16, v174
	v_fmac_f32_e32 v180, v172, v172
	v_rcp_f32_e32 v135, v135
	v_and_b32_e32 v174, 0xffff0000, v174
	v_and_b32_e32 v176, 0xffff0000, v176
	v_fmac_f32_e32 v180, v173, v173
	v_mul_f32_e32 v132, v132, v184
	v_lshlrev_b32_e32 v185, 16, v175
	v_fmac_f32_e32 v180, v132, v132
	v_mul_f32_e32 v133, v133, v174
	v_mul_f32_e32 v131, v128, v176
	v_add_f32_e32 v128, 1.0, v129
	v_and_b32_e32 v175, 0xffff0000, v175
	v_fmac_f32_e32 v180, v133, v133
	v_mul_f32_e32 v134, v134, v185
	v_rcp_f32_e32 v128, v128
	v_add_f32_e32 v129, 1.0, v130
	v_fmac_f32_e32 v180, v134, v134
	v_mul_f32_e32 v135, v135, v175
	v_rcp_f32_e32 v129, v129
	v_fmac_f32_e32 v180, v135, v135
	v_lshlrev_b32_e32 v187, 16, v177
	v_fmac_f32_e32 v180, v136, v136
	v_and_b32_e32 v177, 0xffff0000, v177
	v_fmac_f32_e32 v180, v131, v131
	v_mul_f32_e32 v137, v128, v187
	v_fmac_f32_e32 v180, v137, v137
	v_mul_f32_e32 v138, v129, v177
	v_fmac_f32_e32 v180, v138, v138
	v_cvt_pk_bf16_f32 v128, v132, v133
	v_cvt_pk_bf16_f32 v129, v134, v135
	v_cvt_pk_bf16_f32 v130, v136, v131
	v_cvt_pk_bf16_f32 v131, v137, v138
	global_store_dwordx4 v[178:179], v[128:131], off offset:256
	s_nop 1
	v_mov_b32_e32 v128, v180
	s_nop 1
	v_permlane16_swap_b32_e32 v180, v128
	v_add_f32_e32 v128, v180, v128
	v_mov_b32_e32 v129, v128
	s_nop 1
	v_permlane32_swap_b32_e32 v128, v129
	s_and_saveexec_b64 s[20:21], s[4:5]
	s_cbranch_execz .LBB0_1153
	v_lshl_add_u64 v[130:131], v[162:163], 2, s[0:1]
	v_add_f32_e32 v128, v128, v129
	global_atomic_add_f32 v[130:131], v128, off
; __device__ __forceinline__ void unpack8(const u32x4 w, float (&f)[8]) { f[0] = bflo(w.x); f[1] = bfhi(w.x); f[2] = bflo(w.y); f[3] = bfhi(w.y); f[4] = bflo(w.z); f[5] = bfhi(w.z); f[6] = bflo(w.w); f[7] = bfhi(w.w); }
; __device__ __forceinline__ u32x4 pack8(const float (&f)[8]) { u32x4 o; o.x = pk2(f[0], f[1]); o.y = pk2(f[2], f[3]); o.z = pk2(f[4], f[5]); o.w = pk2(f[6], f[7]); return o; }
; __device__ __forceinline__ float sigmoidf_(float x) { return __builtin_amdgcn_rcpf(1.0f + __expf(-x)); }
;     __device__ __forceinline__ void operator()(const f32x4 (&acc)[2][2][4][2], const Unit& u, int wr, int wc, int fr, int fq) const {
;     ...
;             for (int m = 0; m < 4; ++m) { const int row = row0 + ai * HALF + m * 16; const size_t off = (size_t)row * DM + col0; float s = 0.f;
; #pragma unroll
;                 for (int bj = 0; bj < 2; ++bj) { float e[8], o[8]; unpack8(*(const u32x4*)(E + off + bj * HALF), e);
; #pragma unroll
;                     for (int n = 0; n < 2; ++n) { const f32x4 v = acc[ai][bj][m][n] + bv[bj][n];
; #pragma unroll
;                         for (int j = 0; j < 4; ++j) { o[4 * n + j] = sigmoidf_(v[j]) * e[4 * n + j]; s += o[4 * n + j] * o[4 * n + j]; } }
;                     *(u32x4*)(C + off + bj * HALF) = pack8(o); }
;                 { auto r16 = __builtin_amdgcn_permlane16_swap(__float_as_uint(s), __float_as_uint(s), false, false); s = __uint_as_float(r16[0]) + __uint_as_float(r16[1]);
;                   auto r32 = __builtin_amdgcn_permlane32_swap(__float_as_uint(s), __float_as_uint(s), false, false); s = __uint_as_float(r32[0]) + __uint_as_float(r32[1]); }
;                 if (fq == 0) atomicAdd(ss + row, s); }
.LBB0_1153:
	s_or_b64 exec, exec, s[20:21]
	v_or_b32_e32 v128, 16, v162
	v_ashrrev_i32_e32 v129, 31, v128
	v_lshlrev_b64 v[130:131], 10, v[128:129]
	v_lshl_add_u64 v[130:131], v[130:131], 0, v[160:161]
	v_lshlrev_b64 v[138:139], 1, v[130:131]
	v_lshl_add_u64 v[134:135], s[8:9], 0, v[138:139]
	v_mov_b32_e32 v130, v188
	v_mov_b32_e32 v131, v189
	v_mov_b32_e32 v132, v190
	v_mov_b32_e32 v133, v191
	s_nop 0
	v_mov_b32_e32 v134, v192
	v_mov_b32_e32 v135, v193
	v_mov_b32_e32 v136, v194
	v_mov_b32_e32 v137, v195
	v_add_f32_e32 v125, v125, v69
	v_add_f32_e32 v124, v124, v68
	v_mul_f32_e32 v125, 0xbfb8aa3b, v125
	v_add_f32_e32 v126, v126, v70
	v_add_f32_e32 v127, v127, v71
	v_add_f32_e32 v120, v120, v64
	v_add_f32_e32 v121, v121, v65
	v_add_f32_e32 v122, v122, v66
	v_mul_f32_e32 v124, 0xbfb8aa3b, v124
	v_exp_f32_e32 v125, v125
	v_add_f32_e32 v123, v123, v67
	v_mul_f32_e32 v126, 0xbfb8aa3b, v126
	v_mul_f32_e32 v127, 0xbfb8aa3b, v127
	v_mul_f32_e32 v120, 0xbfb8aa3b, v120
	v_mul_f32_e32 v121, 0xbfb8aa3b, v121
	v_mul_f32_e32 v122, 0xbfb8aa3b, v122
	v_exp_f32_e32 v124, v124
	v_add_f32_e32 v112, v112, v56
	v_add_f32_e32 v116, v116, v48
	v_mul_f32_e32 v123, 0xbfb8aa3b, v123
	v_exp_f32_e32 v126, v126
	v_exp_f32_e32 v127, v127
	v_exp_f32_e32 v120, v120
	v_exp_f32_e32 v121, v121
	v_exp_f32_e32 v122, v122
	v_mul_f32_e32 v112, 0xbfb8aa3b, v112
	v_mul_f32_e32 v116, 0xbfb8aa3b, v116
	v_exp_f32_e32 v123, v123
	v_exp_f32_e32 v112, v112
	v_add_f32_e32 v117, v117, v49
	v_exp_f32_e32 v140, v116
	v_add_f32_e32 v125, 1.0, v125
	v_mul_f32_e32 v117, 0xbfb8aa3b, v117
	v_add_f32_e32 v124, 1.0, v124
	v_rcp_f32_e32 v125, v125
	v_exp_f32_e32 v141, v117
	v_add_f32_e32 v126, 1.0, v126
	v_add_f32_e32 v127, 1.0, v127
	v_add_f32_e32 v120, 1.0, v120
	v_add_f32_e32 v121, 1.0, v121
	v_add_f32_e32 v122, 1.0, v122
	v_rcp_f32_e32 v124, v124
	v_add_f32_e32 v113, v113, v57
	v_add_f32_e32 v123, 1.0, v123
	v_rcp_f32_e32 v126, v126
	v_rcp_f32_e32 v127, v127
	v_rcp_f32_e32 v120, v120
	v_rcp_f32_e32 v121, v121
	v_rcp_f32_e32 v122, v122
	v_add_f32_e32 v112, 1.0, v112
	v_mul_f32_e32 v113, 0xbfb8aa3b, v113
	v_lshl_add_u64 v[116:117], s[48:49], 0, v[138:139]
	v_add_f32_e32 v138, 1.0, v140
	v_rcp_f32_e32 v123, v123
	v_add_f32_e32 v118, v118, v50
	v_rcp_f32_e32 v112, v112
	v_exp_f32_e32 v113, v113
	v_mul_f32_e32 v118, 0xbfb8aa3b, v118
	v_add_f32_e32 v119, v119, v51
	v_add_f32_e32 v139, 1.0, v141
	v_exp_f32_e32 v118, v118
	v_mul_f32_e32 v119, 0xbfb8aa3b, v119
	v_exp_f32_e32 v119, v119
	v_rcp_f32_e32 v138, v138
	v_rcp_f32_e32 v139, v139
	v_add_f32_e32 v118, 1.0, v118
	v_rcp_f32_e32 v118, v118
	v_add_f32_e32 v119, 1.0, v119
	v_rcp_f32_e32 v119, v119
	v_lshlrev_b32_e32 v140, 16, v130
	v_and_b32_e32 v130, 0xffff0000, v130
	v_mul_f32_e32 v125, v125, v130
	v_lshlrev_b32_e32 v141, 16, v131
	v_and_b32_e32 v131, 0xffff0000, v131
	v_lshlrev_b32_e32 v142, 16, v132
	v_and_b32_e32 v132, 0xffff0000, v132
	v_lshlrev_b32_e32 v143, 16, v133
	v_mul_f32_e32 v124, v124, v140
	v_mul_f32_e32 v140, v125, v125
	v_and_b32_e32 v133, 0xffff0000, v133
	v_lshlrev_b32_e32 v171, 16, v136
	v_mul_f32_e32 v126, v126, v141
	v_mul_f32_e32 v127, v127, v131
	v_mul_f32_e32 v130, v120, v142
	v_mul_f32_e32 v131, v121, v132
	v_mul_f32_e32 v132, v122, v143
	v_cvt_pk_bf16_f32 v122, v130, v131
	v_fmac_f32_e32 v140, v124, v124
	v_mul_f32_e32 v133, v123, v133
	v_cvt_pk_bf16_f32 v120, v124, v125
	v_cvt_pk_bf16_f32 v121, v126, v127
	v_cvt_pk_bf16_f32 v123, v132, v133
	global_store_dwordx4 v[116:117], v[120:123], off
	v_fmac_f32_e32 v140, v126, v126
	v_fmac_f32_e32 v140, v127, v127
	v_mul_f32_e32 v122, v112, v171
	v_add_f32_e32 v112, 1.0, v113
	v_add_f32_e32 v113, v114, v58
	v_mul_f32_e32 v113, 0xbfb8aa3b, v113
	v_add_f32_e32 v114, v115, v59
	v_fmac_f32_e32 v140, v130, v130
	v_rcp_f32_e32 v112, v112
	v_exp_f32_e32 v113, v113
	v_mul_f32_e32 v114, 0xbfb8aa3b, v114
	v_fmac_f32_e32 v140, v131, v131
	v_exp_f32_e32 v114, v114
	v_lshlrev_b32_e32 v163, 16, v134
	v_fmac_f32_e32 v140, v132, v132
	v_and_b32_e32 v134, 0xffff0000, v134
	v_and_b32_e32 v136, 0xffff0000, v136
	v_fmac_f32_e32 v140, v133, v133
	v_mul_f32_e32 v120, v138, v163
	v_lshlrev_b32_e32 v170, 16, v135
	v_fmac_f32_e32 v140, v120, v120
	v_mul_f32_e32 v121, v139, v134
	v_mul_f32_e32 v115, v112, v136
	v_add_f32_e32 v112, 1.0, v113
	v_and_b32_e32 v135, 0xffff0000, v135
	v_fmac_f32_e32 v140, v121, v121
	v_mul_f32_e32 v118, v118, v170
	v_rcp_f32_e32 v112, v112
	v_add_f32_e32 v113, 1.0, v114
	v_fmac_f32_e32 v140, v118, v118
	v_mul_f32_e32 v119, v119, v135
	v_rcp_f32_e32 v113, v113
	v_fmac_f32_e32 v140, v119, v119
	v_lshlrev_b32_e32 v172, 16, v137
	v_fmac_f32_e32 v140, v122, v122
	v_and_b32_e32 v137, 0xffff0000, v137
	v_fmac_f32_e32 v140, v115, v115
	v_mul_f32_e32 v123, v112, v172
	v_fmac_f32_e32 v140, v123, v123
	v_mul_f32_e32 v124, v113, v137
	v_fmac_f32_e32 v140, v124, v124
	v_cvt_pk_bf16_f32 v112, v120, v121
	v_cvt_pk_bf16_f32 v113, v118, v119
	v_cvt_pk_bf16_f32 v114, v122, v115
	v_cvt_pk_bf16_f32 v115, v123, v124
	global_store_dwordx4 v[116:117], v[112:115], off offset:256
	s_nop 1
	v_mov_b32_e32 v112, v140
	s_nop 1
	v_permlane16_swap_b32_e32 v140, v112
	v_add_f32_e32 v112, v140, v112
	v_mov_b32_e32 v113, v112
	s_nop 1
	v_permlane32_swap_b32_e32 v112, v113
	s_and_saveexec_b64 s[20:21], s[4:5]
	s_cbranch_execz .LBB0_1155
	v_lshl_add_u64 v[114:115], v[128:129], 2, s[0:1]
	v_add_f32_e32 v112, v112, v113
	global_atomic_add_f32 v[114:115], v112, off
; __device__ __forceinline__ void unpack8(const u32x4 w, float (&f)[8]) { f[0] = bflo(w.x); f[1] = bfhi(w.x); f[2] = bflo(w.y); f[3] = bfhi(w.y); f[4] = bflo(w.z); f[5] = bfhi(w.z); f[6] = bflo(w.w); f[7] = bfhi(w.w); }
; __device__ __forceinline__ u32x4 pack8(const float (&f)[8]) { u32x4 o; o.x = pk2(f[0], f[1]); o.y = pk2(f[2], f[3]); o.z = pk2(f[4], f[5]); o.w = pk2(f[6], f[7]); return o; }
; __device__ __forceinline__ float sigmoidf_(float x) { return __builtin_amdgcn_rcpf(1.0f + __expf(-x)); }
;     __device__ __forceinline__ void operator()(const f32x4 (&acc)[2][2][4][2], const Unit& u, int wr, int wc, int fr, int fq) const {
;     ...
;             for (int m = 0; m < 4; ++m) { const int row = row0 + ai * HALF + m * 16; const size_t off = (size_t)row * DM + col0; float s = 0.f;
; #pragma unroll
;                 for (int bj = 0; bj < 2; ++bj) { float e[8], o[8]; unpack8(*(const u32x4*)(E + off + bj * HALF), e);
; #pragma unroll
;                     for (int n = 0; n < 2; ++n) { const f32x4 v = acc[ai][bj][m][n] + bv[bj][n];
; #pragma unroll
;                         for (int j = 0; j < 4; ++j) { o[4 * n + j] = sigmoidf_(v[j]) * e[4 * n + j]; s += o[4 * n + j] * o[4 * n + j]; } }
;                     *(u32x4*)(C + off + bj * HALF) = pack8(o); }
;                 { auto r16 = __builtin_amdgcn_permlane16_swap(__float_as_uint(s), __float_as_uint(s), false, false); s = __uint_as_float(r16[0]) + __uint_as_float(r16[1]);
;                   auto r32 = __builtin_amdgcn_permlane32_swap(__float_as_uint(s), __float_as_uint(s), false, false); s = __uint_as_float(r32[0]) + __uint_as_float(r32[1]); }
;                 if (fq == 0) atomicAdd(ss + row, s); }
.LBB0_1155:
	s_or_b64 exec, exec, s[20:21]
	v_or_b32_e32 v112, 32, v162
	v_ashrrev_i32_e32 v113, 31, v112
	v_lshlrev_b64 v[114:115], 10, v[112:113]
	v_lshl_add_u64 v[114:115], v[114:115], 0, v[160:161]
	v_lshlrev_b64 v[122:123], 1, v[114:115]
	v_lshl_add_u64 v[118:119], s[8:9], 0, v[122:123]
	v_mov_b32_e32 v114, v196
	v_mov_b32_e32 v115, v197
	v_mov_b32_e32 v116, v198
	v_mov_b32_e32 v117, v199
	s_nop 0
	v_mov_b32_e32 v118, v200
	v_mov_b32_e32 v119, v201
	v_mov_b32_e32 v120, v202
	v_mov_b32_e32 v121, v203
	v_add_f32_e32 v109, v109, v69
	v_add_f32_e32 v108, v108, v68
	v_mul_f32_e32 v109, 0xbfb8aa3b, v109
	v_add_f32_e32 v110, v110, v70
	v_add_f32_e32 v111, v111, v71
	v_add_f32_e32 v104, v104, v64
	v_add_f32_e32 v105, v105, v65
	v_add_f32_e32 v106, v106, v66
	v_mul_f32_e32 v108, 0xbfb8aa3b, v108
	v_exp_f32_e32 v109, v109
	v_add_f32_e32 v107, v107, v67
	v_mul_f32_e32 v110, 0xbfb8aa3b, v110
	v_mul_f32_e32 v111, 0xbfb8aa3b, v111
	v_mul_f32_e32 v104, 0xbfb8aa3b, v104
	v_mul_f32_e32 v105, 0xbfb8aa3b, v105
	v_mul_f32_e32 v106, 0xbfb8aa3b, v106
	v_exp_f32_e32 v108, v108
	v_add_f32_e32 v96, v96, v56
	v_add_f32_e32 v100, v100, v48
	v_mul_f32_e32 v107, 0xbfb8aa3b, v107
	v_exp_f32_e32 v110, v110
	v_exp_f32_e32 v111, v111
	v_exp_f32_e32 v104, v104
	v_exp_f32_e32 v105, v105
	v_exp_f32_e32 v106, v106
	v_mul_f32_e32 v96, 0xbfb8aa3b, v96
	v_mul_f32_e32 v100, 0xbfb8aa3b, v100
	v_exp_f32_e32 v107, v107
	v_exp_f32_e32 v96, v96
	v_add_f32_e32 v101, v101, v49
	v_exp_f32_e32 v124, v100
	v_add_f32_e32 v109, 1.0, v109
	v_mul_f32_e32 v101, 0xbfb8aa3b, v101
	v_add_f32_e32 v108, 1.0, v108
	v_rcp_f32_e32 v109, v109
	v_exp_f32_e32 v125, v101
	v_add_f32_e32 v110, 1.0, v110
	v_add_f32_e32 v111, 1.0, v111
	v_add_f32_e32 v104, 1.0, v104
	v_add_f32_e32 v105, 1.0, v105
	v_add_f32_e32 v106, 1.0, v106
	v_rcp_f32_e32 v108, v108
	v_add_f32_e32 v97, v97, v57
	v_add_f32_e32 v107, 1.0, v107
	v_rcp_f32_e32 v110, v110
	v_rcp_f32_e32 v111, v111
	v_rcp_f32_e32 v104, v104
	v_rcp_f32_e32 v105, v105
	v_rcp_f32_e32 v106, v106
	v_add_f32_e32 v96, 1.0, v96
	v_mul_f32_e32 v97, 0xbfb8aa3b, v97
	v_lshl_add_u64 v[100:101], s[48:49], 0, v[122:123]
	v_add_f32_e32 v122, 1.0, v124
	v_rcp_f32_e32 v107, v107
	v_add_f32_e32 v102, v102, v50
	v_rcp_f32_e32 v96, v96
	v_exp_f32_e32 v97, v97
	v_mul_f32_e32 v102, 0xbfb8aa3b, v102
	v_add_f32_e32 v103, v103, v51
	v_add_f32_e32 v123, 1.0, v125
	v_exp_f32_e32 v102, v102
	v_mul_f32_e32 v103, 0xbfb8aa3b, v103
	v_exp_f32_e32 v103, v103
	v_rcp_f32_e32 v122, v122
	v_rcp_f32_e32 v123, v123
	v_add_f32_e32 v102, 1.0, v102
	v_rcp_f32_e32 v102, v102
	v_add_f32_e32 v103, 1.0, v103
	v_rcp_f32_e32 v103, v103
	v_lshlrev_b32_e32 v124, 16, v114
	v_and_b32_e32 v114, 0xffff0000, v114
	v_mul_f32_e32 v109, v109, v114
	v_lshlrev_b32_e32 v125, 16, v115
	v_and_b32_e32 v115, 0xffff0000, v115
	v_lshlrev_b32_e32 v126, 16, v116
	v_and_b32_e32 v116, 0xffff0000, v116
	v_lshlrev_b32_e32 v127, 16, v117
	v_mul_f32_e32 v108, v108, v124
	v_mul_f32_e32 v124, v109, v109
	v_and_b32_e32 v117, 0xffff0000, v117
	v_lshlrev_b32_e32 v130, 16, v120
	v_mul_f32_e32 v110, v110, v125
	v_mul_f32_e32 v111, v111, v115
	v_mul_f32_e32 v114, v104, v126
	v_mul_f32_e32 v115, v105, v116
	v_mul_f32_e32 v116, v106, v127
	v_cvt_pk_bf16_f32 v106, v114, v115
	v_fmac_f32_e32 v124, v108, v108
	v_mul_f32_e32 v117, v107, v117
	v_cvt_pk_bf16_f32 v104, v108, v109
	v_cvt_pk_bf16_f32 v105, v110, v111
	v_cvt_pk_bf16_f32 v107, v116, v117
	global_store_dwordx4 v[100:101], v[104:107], off
	v_fmac_f32_e32 v124, v110, v110
	v_fmac_f32_e32 v124, v111, v111
	v_mul_f32_e32 v106, v96, v130
	v_add_f32_e32 v96, 1.0, v97
	v_add_f32_e32 v97, v98, v58
	v_mul_f32_e32 v97, 0xbfb8aa3b, v97
	v_add_f32_e32 v98, v99, v59
	v_fmac_f32_e32 v124, v114, v114
	v_rcp_f32_e32 v96, v96
	v_exp_f32_e32 v97, v97
	v_mul_f32_e32 v98, 0xbfb8aa3b, v98
	v_fmac_f32_e32 v124, v115, v115
	v_exp_f32_e32 v98, v98
	v_lshlrev_b32_e32 v128, 16, v118
	v_fmac_f32_e32 v124, v116, v116
	v_and_b32_e32 v118, 0xffff0000, v118
	v_and_b32_e32 v120, 0xffff0000, v120
	v_fmac_f32_e32 v124, v117, v117
	v_mul_f32_e32 v104, v122, v128
	v_lshlrev_b32_e32 v129, 16, v119
	v_fmac_f32_e32 v124, v104, v104
	v_mul_f32_e32 v105, v123, v118
	v_mul_f32_e32 v99, v96, v120
	v_add_f32_e32 v96, 1.0, v97
	v_and_b32_e32 v119, 0xffff0000, v119
	v_fmac_f32_e32 v124, v105, v105
	v_mul_f32_e32 v102, v102, v129
	v_rcp_f32_e32 v96, v96
	v_add_f32_e32 v97, 1.0, v98
	v_fmac_f32_e32 v124, v102, v102
	v_mul_f32_e32 v103, v103, v119
	v_rcp_f32_e32 v97, v97
	v_fmac_f32_e32 v124, v103, v103
	v_lshlrev_b32_e32 v131, 16, v121
	v_fmac_f32_e32 v124, v106, v106
	v_and_b32_e32 v121, 0xffff0000, v121
	v_fmac_f32_e32 v124, v99, v99
	v_mul_f32_e32 v107, v96, v131
	v_fmac_f32_e32 v124, v107, v107
	v_mul_f32_e32 v108, v97, v121
	v_fmac_f32_e32 v124, v108, v108
	v_cvt_pk_bf16_f32 v96, v104, v105
	v_cvt_pk_bf16_f32 v97, v102, v103
	v_cvt_pk_bf16_f32 v98, v106, v99
	v_cvt_pk_bf16_f32 v99, v107, v108
	global_store_dwordx4 v[100:101], v[96:99], off offset:256
	s_nop 1
	v_mov_b32_e32 v96, v124
	s_nop 1
	v_permlane16_swap_b32_e32 v124, v96
	v_add_f32_e32 v96, v124, v96
	v_mov_b32_e32 v97, v96
	s_nop 1
	v_permlane32_swap_b32_e32 v96, v97
	s_and_saveexec_b64 s[20:21], s[4:5]
	s_cbranch_execz .LBB0_1157
	v_lshl_add_u64 v[98:99], v[112:113], 2, s[0:1]
	v_add_f32_e32 v96, v96, v97
	global_atomic_add_f32 v[98:99], v96, off
; __device__ __forceinline__ void unpack8(const u32x4 w, float (&f)[8]) { f[0] = bflo(w.x); f[1] = bfhi(w.x); f[2] = bflo(w.y); f[3] = bfhi(w.y); f[4] = bflo(w.z); f[5] = bfhi(w.z); f[6] = bflo(w.w); f[7] = bfhi(w.w); }
; __device__ __forceinline__ u32x4 pack8(const float (&f)[8]) { u32x4 o; o.x = pk2(f[0], f[1]); o.y = pk2(f[2], f[3]); o.z = pk2(f[4], f[5]); o.w = pk2(f[6], f[7]); return o; }
; __device__ __forceinline__ float sigmoidf_(float x) { return __builtin_amdgcn_rcpf(1.0f + __expf(-x)); }
;     __device__ __forceinline__ void operator()(const f32x4 (&acc)[2][2][4][2], const Unit& u, int wr, int wc, int fr, int fq) const {
;     ...
;             for (int m = 0; m < 4; ++m) { const int row = row0 + ai * HALF + m * 16; const size_t off = (size_t)row * DM + col0; float s = 0.f;
; #pragma unroll
;                 for (int bj = 0; bj < 2; ++bj) { float e[8], o[8]; unpack8(*(const u32x4*)(E + off + bj * HALF), e);
; #pragma unroll
;                     for (int n = 0; n < 2; ++n) { const f32x4 v = acc[ai][bj][m][n] + bv[bj][n];
; #pragma unroll
;                         for (int j = 0; j < 4; ++j) { o[4 * n + j] = sigmoidf_(v[j]) * e[4 * n + j]; s += o[4 * n + j] * o[4 * n + j]; } }
;                     *(u32x4*)(C + off + bj * HALF) = pack8(o); }
;                 { auto r16 = __builtin_amdgcn_permlane16_swap(__float_as_uint(s), __float_as_uint(s), false, false); s = __uint_as_float(r16[0]) + __uint_as_float(r16[1]);
;                   auto r32 = __builtin_amdgcn_permlane32_swap(__float_as_uint(s), __float_as_uint(s), false, false); s = __uint_as_float(r32[0]) + __uint_as_float(r32[1]); }
;                 if (fq == 0) atomicAdd(ss + row, s); }
.LBB0_1157:
	s_or_b64 exec, exec, s[20:21]
	v_or_b32_e32 v96, 48, v162
	v_ashrrev_i32_e32 v97, 31, v96
	v_lshlrev_b64 v[98:99], 10, v[96:97]
	v_lshl_add_u64 v[98:99], v[98:99], 0, v[160:161]
	v_lshlrev_b64 v[106:107], 1, v[98:99]
	v_lshl_add_u64 v[102:103], s[8:9], 0, v[106:107]
	v_mov_b32_e32 v98, v204
	v_mov_b32_e32 v99, v205
	v_mov_b32_e32 v100, v206
	v_mov_b32_e32 v101, v207
	s_nop 0
	v_mov_b32_e32 v102, v208
	v_mov_b32_e32 v103, v209
	v_mov_b32_e32 v104, v210
	v_mov_b32_e32 v105, v211
	v_add_f32_e32 v93, v93, v69
	v_add_f32_e32 v92, v92, v68
	v_mul_f32_e32 v93, 0xbfb8aa3b, v93
	v_add_f32_e32 v94, v94, v70
	v_add_f32_e32 v95, v95, v71
	v_add_f32_e32 v88, v88, v64
	v_add_f32_e32 v89, v89, v65
	v_add_f32_e32 v90, v90, v66
	v_mul_f32_e32 v92, 0xbfb8aa3b, v92
	v_exp_f32_e32 v93, v93
	v_add_f32_e32 v91, v91, v67
	v_mul_f32_e32 v94, 0xbfb8aa3b, v94
	v_mul_f32_e32 v95, 0xbfb8aa3b, v95
	v_mul_f32_e32 v88, 0xbfb8aa3b, v88
	v_mul_f32_e32 v89, 0xbfb8aa3b, v89
	v_mul_f32_e32 v90, 0xbfb8aa3b, v90
	v_exp_f32_e32 v92, v92
	v_add_f32_e32 v80, v80, v56
	v_add_f32_e32 v84, v84, v48
	v_mul_f32_e32 v91, 0xbfb8aa3b, v91
	v_exp_f32_e32 v94, v94
	v_exp_f32_e32 v95, v95
	v_exp_f32_e32 v88, v88
	v_exp_f32_e32 v89, v89
	v_exp_f32_e32 v90, v90
	v_mul_f32_e32 v80, 0xbfb8aa3b, v80
	v_mul_f32_e32 v84, 0xbfb8aa3b, v84
	v_exp_f32_e32 v91, v91
	v_exp_f32_e32 v80, v80
	v_add_f32_e32 v85, v85, v49
	v_exp_f32_e32 v108, v84
	v_add_f32_e32 v93, 1.0, v93
	v_mul_f32_e32 v85, 0xbfb8aa3b, v85
	v_add_f32_e32 v92, 1.0, v92
	v_rcp_f32_e32 v93, v93
	v_exp_f32_e32 v109, v85
	v_add_f32_e32 v94, 1.0, v94
	v_add_f32_e32 v95, 1.0, v95
	v_add_f32_e32 v88, 1.0, v88
	v_add_f32_e32 v89, 1.0, v89
	v_add_f32_e32 v90, 1.0, v90
	v_rcp_f32_e32 v92, v92
	v_add_f32_e32 v81, v81, v57
	v_add_f32_e32 v91, 1.0, v91
	v_rcp_f32_e32 v94, v94
	v_rcp_f32_e32 v95, v95
	v_rcp_f32_e32 v88, v88
	v_rcp_f32_e32 v89, v89
	v_rcp_f32_e32 v90, v90
	v_add_f32_e32 v80, 1.0, v80
	v_mul_f32_e32 v81, 0xbfb8aa3b, v81
	v_lshl_add_u64 v[84:85], s[48:49], 0, v[106:107]
	v_add_f32_e32 v106, 1.0, v108
	v_rcp_f32_e32 v91, v91
	v_add_f32_e32 v86, v86, v50
	v_rcp_f32_e32 v80, v80
	v_exp_f32_e32 v81, v81
	v_mul_f32_e32 v86, 0xbfb8aa3b, v86
	v_add_f32_e32 v87, v87, v51
	v_add_f32_e32 v107, 1.0, v109
	v_exp_f32_e32 v86, v86
	v_mul_f32_e32 v87, 0xbfb8aa3b, v87
	v_exp_f32_e32 v87, v87
	v_rcp_f32_e32 v106, v106
	v_rcp_f32_e32 v107, v107
	v_add_f32_e32 v86, 1.0, v86
	v_rcp_f32_e32 v86, v86
	v_add_f32_e32 v87, 1.0, v87
	v_rcp_f32_e32 v87, v87
	v_lshlrev_b32_e32 v108, 16, v98
	v_and_b32_e32 v98, 0xffff0000, v98
	v_mul_f32_e32 v93, v93, v98
	v_lshlrev_b32_e32 v109, 16, v99
	v_and_b32_e32 v99, 0xffff0000, v99
	v_lshlrev_b32_e32 v110, 16, v100
	v_and_b32_e32 v100, 0xffff0000, v100
	v_lshlrev_b32_e32 v111, 16, v101
	v_mul_f32_e32 v92, v92, v108
	v_mul_f32_e32 v108, v93, v93
	v_and_b32_e32 v101, 0xffff0000, v101
	v_lshlrev_b32_e32 v114, 16, v104
	v_mul_f32_e32 v94, v94, v109
	v_mul_f32_e32 v95, v95, v99
	v_mul_f32_e32 v98, v88, v110
	v_mul_f32_e32 v99, v89, v100
	v_mul_f32_e32 v100, v90, v111
	v_cvt_pk_bf16_f32 v90, v98, v99
	v_fmac_f32_e32 v108, v92, v92
	v_mul_f32_e32 v101, v91, v101
	v_cvt_pk_bf16_f32 v88, v92, v93
	v_cvt_pk_bf16_f32 v89, v94, v95
	v_cvt_pk_bf16_f32 v91, v100, v101
	global_store_dwordx4 v[84:85], v[88:91], off
	v_fmac_f32_e32 v108, v94, v94
	v_fmac_f32_e32 v108, v95, v95
	v_mul_f32_e32 v90, v80, v114
	v_add_f32_e32 v80, 1.0, v81
	v_add_f32_e32 v81, v82, v58
	v_mul_f32_e32 v81, 0xbfb8aa3b, v81
	v_add_f32_e32 v82, v83, v59
	v_fmac_f32_e32 v108, v98, v98
	v_rcp_f32_e32 v80, v80
	v_exp_f32_e32 v81, v81
	v_mul_f32_e32 v82, 0xbfb8aa3b, v82
	v_fmac_f32_e32 v108, v99, v99
	v_exp_f32_e32 v82, v82
	v_lshlrev_b32_e32 v112, 16, v102
	v_fmac_f32_e32 v108, v100, v100
	v_and_b32_e32 v102, 0xffff0000, v102
	v_and_b32_e32 v104, 0xffff0000, v104
	v_fmac_f32_e32 v108, v101, v101
	v_mul_f32_e32 v88, v106, v112
	v_lshlrev_b32_e32 v113, 16, v103
	v_fmac_f32_e32 v108, v88, v88
	v_mul_f32_e32 v89, v107, v102
	v_mul_f32_e32 v83, v80, v104
	v_add_f32_e32 v80, 1.0, v81
	v_and_b32_e32 v103, 0xffff0000, v103
	v_fmac_f32_e32 v108, v89, v89
	v_mul_f32_e32 v86, v86, v113
	v_rcp_f32_e32 v80, v80
	v_add_f32_e32 v81, 1.0, v82
	v_fmac_f32_e32 v108, v86, v86
	v_mul_f32_e32 v87, v87, v103
	v_rcp_f32_e32 v81, v81
	v_fmac_f32_e32 v108, v87, v87
	v_lshlrev_b32_e32 v115, 16, v105
	v_fmac_f32_e32 v108, v90, v90
	v_and_b32_e32 v105, 0xffff0000, v105
	v_fmac_f32_e32 v108, v83, v83
	v_mul_f32_e32 v91, v80, v115
	v_fmac_f32_e32 v108, v91, v91
	v_mul_f32_e32 v92, v81, v105
	v_fmac_f32_e32 v108, v92, v92
	v_cvt_pk_bf16_f32 v80, v88, v89
	v_cvt_pk_bf16_f32 v81, v86, v87
	v_cvt_pk_bf16_f32 v82, v90, v83
	v_cvt_pk_bf16_f32 v83, v91, v92
	global_store_dwordx4 v[84:85], v[80:83], off offset:256
	s_nop 1
	v_mov_b32_e32 v80, v108
	s_nop 1
	v_permlane16_swap_b32_e32 v108, v80
	v_add_f32_e32 v80, v108, v80
	v_mov_b32_e32 v81, v80
	s_nop 1
	v_permlane32_swap_b32_e32 v80, v81
	s_and_saveexec_b64 s[20:21], s[4:5]
	s_cbranch_execz .LBB0_1159
	v_lshl_add_u64 v[82:83], v[96:97], 2, s[0:1]
	v_add_f32_e32 v80, v80, v81
	global_atomic_add_f32 v[82:83], v80, off
; __device__ __forceinline__ void unpack8(const u32x4 w, float (&f)[8]) { f[0] = bflo(w.x); f[1] = bfhi(w.x); f[2] = bflo(w.y); f[3] = bfhi(w.y); f[4] = bflo(w.z); f[5] = bfhi(w.z); f[6] = bflo(w.w); f[7] = bfhi(w.w); }
; __device__ __forceinline__ u32x4 pack8(const float (&f)[8]) { u32x4 o; o.x = pk2(f[0], f[1]); o.y = pk2(f[2], f[3]); o.z = pk2(f[4], f[5]); o.w = pk2(f[6], f[7]); return o; }
; __device__ __forceinline__ float sigmoidf_(float x) { return __builtin_amdgcn_rcpf(1.0f + __expf(-x)); }
;     __device__ __forceinline__ void operator()(const f32x4 (&acc)[2][2][4][2], const Unit& u, int wr, int wc, int fr, int fq) const {
;     ...
;             for (int m = 0; m < 4; ++m) { const int row = row0 + ai * HALF + m * 16; const size_t off = (size_t)row * DM + col0; float s = 0.f;
; #pragma unroll
;                 for (int bj = 0; bj < 2; ++bj) { float e[8], o[8]; unpack8(*(const u32x4*)(E + off + bj * HALF), e);
; #pragma unroll
;                     for (int n = 0; n < 2; ++n) { const f32x4 v = acc[ai][bj][m][n] + bv[bj][n];
; #pragma unroll
;                         for (int j = 0; j < 4; ++j) { o[4 * n + j] = sigmoidf_(v[j]) * e[4 * n + j]; s += o[4 * n + j] * o[4 * n + j]; } }
;                     *(u32x4*)(C + off + bj * HALF) = pack8(o); }
;                 { auto r16 = __builtin_amdgcn_permlane16_swap(__float_as_uint(s), __float_as_uint(s), false, false); s = __uint_as_float(r16[0]) + __uint_as_float(r16[1]);
;                   auto r32 = __builtin_amdgcn_permlane32_swap(__float_as_uint(s), __float_as_uint(s), false, false); s = __uint_as_float(r32[0]) + __uint_as_float(r32[1]); }
;                 if (fq == 0) atomicAdd(ss + row, s); }
.LBB0_1159:
	s_or_b64 exec, exec, s[20:21]
	v_add_u32_e32 v80, 0x80, v162
	v_ashrrev_i32_e32 v81, 31, v80
	v_lshlrev_b64 v[82:83], 10, v[80:81]
	v_lshl_add_u64 v[82:83], v[82:83], 0, v[160:161]
	v_lshlrev_b64 v[90:91], 1, v[82:83]
	v_lshl_add_u64 v[86:87], s[8:9], 0, v[90:91]
	v_mov_b32_e32 v82, v212
	v_mov_b32_e32 v83, v213
	v_mov_b32_e32 v84, v214
	v_mov_b32_e32 v85, v215
	s_nop 0
	v_mov_b32_e32 v86, v216
	v_mov_b32_e32 v87, v217
	v_mov_b32_e32 v88, v218
	v_mov_b32_e32 v89, v219
	v_add_f32_e32 v77, v77, v69
	v_add_f32_e32 v76, v76, v68
	v_mul_f32_e32 v77, 0xbfb8aa3b, v77
	v_add_f32_e32 v78, v78, v70
	v_add_f32_e32 v79, v79, v71
	v_add_f32_e32 v72, v72, v64
	v_add_f32_e32 v73, v73, v65
	v_add_f32_e32 v74, v74, v66
	v_mul_f32_e32 v76, 0xbfb8aa3b, v76
	v_exp_f32_e32 v77, v77
	v_add_f32_e32 v75, v75, v67
	v_mul_f32_e32 v78, 0xbfb8aa3b, v78
	v_mul_f32_e32 v79, 0xbfb8aa3b, v79
	v_mul_f32_e32 v72, 0xbfb8aa3b, v72
	v_mul_f32_e32 v73, 0xbfb8aa3b, v73
	v_mul_f32_e32 v74, 0xbfb8aa3b, v74
	v_exp_f32_e32 v76, v76
	v_add_f32_e32 v52, v52, v56
	v_add_f32_e32 v60, v60, v48
	v_mul_f32_e32 v75, 0xbfb8aa3b, v75
	v_exp_f32_e32 v78, v78
	v_exp_f32_e32 v79, v79
	v_exp_f32_e32 v72, v72
	v_exp_f32_e32 v73, v73
	v_exp_f32_e32 v74, v74
	v_mul_f32_e32 v52, 0xbfb8aa3b, v52
	v_mul_f32_e32 v60, 0xbfb8aa3b, v60
	v_exp_f32_e32 v75, v75
	v_exp_f32_e32 v52, v52
	v_add_f32_e32 v61, v61, v49
	v_exp_f32_e32 v92, v60
	v_add_f32_e32 v77, 1.0, v77
	v_mul_f32_e32 v61, 0xbfb8aa3b, v61
	v_add_f32_e32 v76, 1.0, v76
	v_rcp_f32_e32 v77, v77
	v_exp_f32_e32 v93, v61
	v_add_f32_e32 v78, 1.0, v78
	v_add_f32_e32 v79, 1.0, v79
	v_add_f32_e32 v72, 1.0, v72
	v_add_f32_e32 v73, 1.0, v73
	v_add_f32_e32 v74, 1.0, v74
	v_rcp_f32_e32 v76, v76
	v_add_f32_e32 v53, v53, v57
	v_add_f32_e32 v75, 1.0, v75
	v_rcp_f32_e32 v78, v78
	v_rcp_f32_e32 v79, v79
	v_rcp_f32_e32 v72, v72
	v_rcp_f32_e32 v73, v73
	v_rcp_f32_e32 v74, v74
	v_add_f32_e32 v52, 1.0, v52
	v_mul_f32_e32 v53, 0xbfb8aa3b, v53
	v_lshl_add_u64 v[60:61], s[48:49], 0, v[90:91]
	v_add_f32_e32 v90, 1.0, v92
	v_rcp_f32_e32 v75, v75
	v_add_f32_e32 v62, v62, v50
	v_rcp_f32_e32 v52, v52
	v_exp_f32_e32 v53, v53
	v_mul_f32_e32 v62, 0xbfb8aa3b, v62
	v_add_f32_e32 v63, v63, v51
	v_add_f32_e32 v91, 1.0, v93
	v_exp_f32_e32 v62, v62
	v_mul_f32_e32 v63, 0xbfb8aa3b, v63
	v_exp_f32_e32 v63, v63
	v_rcp_f32_e32 v90, v90
	v_rcp_f32_e32 v91, v91
	v_add_f32_e32 v62, 1.0, v62
	v_rcp_f32_e32 v62, v62
	v_add_f32_e32 v63, 1.0, v63
	v_rcp_f32_e32 v63, v63
	v_lshlrev_b32_e32 v92, 16, v82
	v_and_b32_e32 v82, 0xffff0000, v82
	v_mul_f32_e32 v77, v77, v82
	v_lshlrev_b32_e32 v93, 16, v83
	v_and_b32_e32 v83, 0xffff0000, v83
	v_lshlrev_b32_e32 v94, 16, v84
	v_and_b32_e32 v84, 0xffff0000, v84
	v_lshlrev_b32_e32 v95, 16, v85
	v_mul_f32_e32 v76, v76, v92
	v_mul_f32_e32 v92, v77, v77
	v_and_b32_e32 v85, 0xffff0000, v85
	v_lshlrev_b32_e32 v98, 16, v88
	v_mul_f32_e32 v78, v78, v93
	v_mul_f32_e32 v79, v79, v83
	v_mul_f32_e32 v82, v72, v94
	v_mul_f32_e32 v83, v73, v84
	v_mul_f32_e32 v84, v74, v95
	v_cvt_pk_bf16_f32 v74, v82, v83
	v_fmac_f32_e32 v92, v76, v76
	v_mul_f32_e32 v85, v75, v85
	v_cvt_pk_bf16_f32 v72, v76, v77
	v_cvt_pk_bf16_f32 v73, v78, v79
	v_cvt_pk_bf16_f32 v75, v84, v85
	global_store_dwordx4 v[60:61], v[72:75], off
	v_fmac_f32_e32 v92, v78, v78
	v_fmac_f32_e32 v92, v79, v79
	v_mul_f32_e32 v74, v52, v98
	v_add_f32_e32 v52, 1.0, v53
	v_add_f32_e32 v53, v54, v58
	v_mul_f32_e32 v53, 0xbfb8aa3b, v53
	v_add_f32_e32 v54, v55, v59
	v_fmac_f32_e32 v92, v82, v82
	v_rcp_f32_e32 v52, v52
	v_exp_f32_e32 v53, v53
	v_mul_f32_e32 v54, 0xbfb8aa3b, v54
	v_fmac_f32_e32 v92, v83, v83
	v_exp_f32_e32 v54, v54
	v_lshlrev_b32_e32 v96, 16, v86
	v_fmac_f32_e32 v92, v84, v84
	v_and_b32_e32 v86, 0xffff0000, v86
	v_and_b32_e32 v88, 0xffff0000, v88
	v_fmac_f32_e32 v92, v85, v85
	v_mul_f32_e32 v72, v90, v96
	v_lshlrev_b32_e32 v97, 16, v87
	v_fmac_f32_e32 v92, v72, v72
	v_mul_f32_e32 v73, v91, v86
	v_mul_f32_e32 v55, v52, v88
	v_add_f32_e32 v52, 1.0, v53
	v_and_b32_e32 v87, 0xffff0000, v87
	v_fmac_f32_e32 v92, v73, v73
	v_mul_f32_e32 v62, v62, v97
	v_rcp_f32_e32 v52, v52
	v_add_f32_e32 v53, 1.0, v54
	v_fmac_f32_e32 v92, v62, v62
	v_mul_f32_e32 v63, v63, v87
	v_rcp_f32_e32 v53, v53
	v_fmac_f32_e32 v92, v63, v63
	v_lshlrev_b32_e32 v99, 16, v89
	v_fmac_f32_e32 v92, v74, v74
	v_and_b32_e32 v89, 0xffff0000, v89
	v_fmac_f32_e32 v92, v55, v55
	v_mul_f32_e32 v75, v52, v99
	v_fmac_f32_e32 v92, v75, v75
	v_mul_f32_e32 v76, v53, v89
	v_fmac_f32_e32 v92, v76, v76
	v_cvt_pk_bf16_f32 v52, v72, v73
	v_cvt_pk_bf16_f32 v53, v62, v63
	v_cvt_pk_bf16_f32 v54, v74, v55
	v_cvt_pk_bf16_f32 v55, v75, v76
	global_store_dwordx4 v[60:61], v[52:55], off offset:256
	s_nop 1
	v_mov_b32_e32 v52, v92
	s_nop 1
	v_permlane16_swap_b32_e32 v92, v52
	v_add_f32_e32 v52, v92, v52
	v_mov_b32_e32 v53, v52
	s_nop 1
	v_permlane32_swap_b32_e32 v52, v53
	s_and_saveexec_b64 s[20:21], s[4:5]
	s_cbranch_execz .LBB0_1161
	v_lshl_add_u64 v[54:55], v[80:81], 2, s[0:1]
	v_add_f32_e32 v52, v52, v53
	global_atomic_add_f32 v[54:55], v52, off
; __device__ __forceinline__ void unpack8(const u32x4 w, float (&f)[8]) { f[0] = bflo(w.x); f[1] = bfhi(w.x); f[2] = bflo(w.y); f[3] = bfhi(w.y); f[4] = bflo(w.z); f[5] = bfhi(w.z); f[6] = bflo(w.w); f[7] = bfhi(w.w); }
; __device__ __forceinline__ u32x4 pack8(const float (&f)[8]) { u32x4 o; o.x = pk2(f[0], f[1]); o.y = pk2(f[2], f[3]); o.z = pk2(f[4], f[5]); o.w = pk2(f[6], f[7]); return o; }
; __device__ __forceinline__ float sigmoidf_(float x) { return __builtin_amdgcn_rcpf(1.0f + __expf(-x)); }
;     __device__ __forceinline__ void operator()(const f32x4 (&acc)[2][2][4][2], const Unit& u, int wr, int wc, int fr, int fq) const {
;     ...
;             for (int m = 0; m < 4; ++m) { const int row = row0 + ai * HALF + m * 16; const size_t off = (size_t)row * DM + col0; float s = 0.f;
; #pragma unroll
;                 for (int bj = 0; bj < 2; ++bj) { float e[8], o[8]; unpack8(*(const u32x4*)(E + off + bj * HALF), e);
; #pragma unroll
;                     for (int n = 0; n < 2; ++n) { const f32x4 v = acc[ai][bj][m][n] + bv[bj][n];
; #pragma unroll
;                         for (int j = 0; j < 4; ++j) { o[4 * n + j] = sigmoidf_(v[j]) * e[4 * n + j]; s += o[4 * n + j] * o[4 * n + j]; } }
;                     *(u32x4*)(C + off + bj * HALF) = pack8(o); }
;                 { auto r16 = __builtin_amdgcn_permlane16_swap(__float_as_uint(s), __float_as_uint(s), false, false); s = __uint_as_float(r16[0]) + __uint_as_float(r16[1]);
;                   auto r32 = __builtin_amdgcn_permlane32_swap(__float_as_uint(s), __float_as_uint(s), false, false); s = __uint_as_float(r32[0]) + __uint_as_float(r32[1]); }
;                 if (fq == 0) atomicAdd(ss + row, s); }
.LBB0_1161:
	s_or_b64 exec, exec, s[20:21]
	v_add_u32_e32 v52, 0x90, v162
	v_ashrrev_i32_e32 v53, 31, v52
	v_lshlrev_b64 v[54:55], 10, v[52:53]
	v_lshl_add_u64 v[54:55], v[54:55], 0, v[160:161]
	v_lshlrev_b64 v[54:55], 1, v[54:55]
	v_lshl_add_u64 v[72:73], s[8:9], 0, v[54:55]
	v_mov_b32_e32 v60, v220
	v_mov_b32_e32 v61, v221
	v_mov_b32_e32 v62, v222
	v_mov_b32_e32 v63, v223
	s_nop 0
	v_mov_b32_e32 v72, v224
	v_mov_b32_e32 v73, v225
	v_mov_b32_e32 v74, v226
	v_mov_b32_e32 v75, v227
	v_add_f32_e32 v45, v45, v69
	v_add_f32_e32 v44, v44, v68
	v_mul_f32_e32 v45, 0xbfb8aa3b, v45
	v_add_f32_e32 v46, v46, v70
	v_add_f32_e32 v47, v47, v71
	v_add_f32_e32 v40, v40, v64
	v_add_f32_e32 v41, v41, v65
	v_add_f32_e32 v42, v42, v66
	v_mul_f32_e32 v44, 0xbfb8aa3b, v44
	v_exp_f32_e32 v45, v45
	v_add_f32_e32 v43, v43, v67
	v_mul_f32_e32 v46, 0xbfb8aa3b, v46
	v_mul_f32_e32 v47, 0xbfb8aa3b, v47
	v_mul_f32_e32 v40, 0xbfb8aa3b, v40
	v_mul_f32_e32 v41, 0xbfb8aa3b, v41
	v_mul_f32_e32 v42, 0xbfb8aa3b, v42
	v_exp_f32_e32 v44, v44
	v_add_f32_e32 v32, v32, v56
	v_add_f32_e32 v36, v36, v48
	v_mul_f32_e32 v43, 0xbfb8aa3b, v43
	v_exp_f32_e32 v46, v46
	v_exp_f32_e32 v47, v47
	v_exp_f32_e32 v40, v40
	v_exp_f32_e32 v41, v41
	v_exp_f32_e32 v42, v42
	v_mul_f32_e32 v32, 0xbfb8aa3b, v32
	v_mul_f32_e32 v36, 0xbfb8aa3b, v36
	v_exp_f32_e32 v43, v43
	v_exp_f32_e32 v32, v32
	v_add_f32_e32 v37, v37, v49
	v_exp_f32_e32 v76, v36
	v_add_f32_e32 v45, 1.0, v45
	v_mul_f32_e32 v37, 0xbfb8aa3b, v37
	v_add_f32_e32 v44, 1.0, v44
	v_rcp_f32_e32 v45, v45
	v_exp_f32_e32 v77, v37
	v_add_f32_e32 v46, 1.0, v46
	v_add_f32_e32 v47, 1.0, v47
	v_add_f32_e32 v40, 1.0, v40
	v_add_f32_e32 v41, 1.0, v41
	v_add_f32_e32 v42, 1.0, v42
	v_rcp_f32_e32 v44, v44
	v_add_f32_e32 v33, v33, v57
	v_add_f32_e32 v43, 1.0, v43
	v_rcp_f32_e32 v46, v46
	v_rcp_f32_e32 v47, v47
	v_rcp_f32_e32 v40, v40
	v_rcp_f32_e32 v41, v41
	v_rcp_f32_e32 v42, v42
	v_add_f32_e32 v32, 1.0, v32
	v_mul_f32_e32 v33, 0xbfb8aa3b, v33
	v_lshl_add_u64 v[36:37], s[48:49], 0, v[54:55]
	v_add_f32_e32 v54, 1.0, v76
	v_rcp_f32_e32 v43, v43
	v_add_f32_e32 v38, v38, v50
	v_rcp_f32_e32 v32, v32
	v_exp_f32_e32 v33, v33
	v_mul_f32_e32 v38, 0xbfb8aa3b, v38
	v_add_f32_e32 v39, v39, v51
	v_add_f32_e32 v55, 1.0, v77
	v_exp_f32_e32 v38, v38
	v_mul_f32_e32 v39, 0xbfb8aa3b, v39
	v_exp_f32_e32 v39, v39
	v_rcp_f32_e32 v54, v54
	v_rcp_f32_e32 v55, v55
	v_add_f32_e32 v38, 1.0, v38
	v_rcp_f32_e32 v38, v38
	v_add_f32_e32 v39, 1.0, v39
	v_rcp_f32_e32 v39, v39
	v_lshlrev_b32_e32 v76, 16, v60
	v_and_b32_e32 v60, 0xffff0000, v60
	v_mul_f32_e32 v45, v45, v60
	v_lshlrev_b32_e32 v77, 16, v61
	v_and_b32_e32 v61, 0xffff0000, v61
	v_lshlrev_b32_e32 v78, 16, v62
	v_and_b32_e32 v62, 0xffff0000, v62
	v_lshlrev_b32_e32 v79, 16, v63
	v_mul_f32_e32 v44, v44, v76
	v_mul_f32_e32 v76, v45, v45
	v_and_b32_e32 v63, 0xffff0000, v63
	v_lshlrev_b32_e32 v82, 16, v74
	v_mul_f32_e32 v46, v46, v77
	v_mul_f32_e32 v47, v47, v61
	v_mul_f32_e32 v60, v40, v78
	v_mul_f32_e32 v61, v41, v62
	v_mul_f32_e32 v62, v42, v79
	v_cvt_pk_bf16_f32 v42, v60, v61
	v_fmac_f32_e32 v76, v44, v44
	v_mul_f32_e32 v63, v43, v63
	v_cvt_pk_bf16_f32 v40, v44, v45
	v_cvt_pk_bf16_f32 v41, v46, v47
	v_cvt_pk_bf16_f32 v43, v62, v63
	global_store_dwordx4 v[36:37], v[40:43], off
	v_fmac_f32_e32 v76, v46, v46
	v_fmac_f32_e32 v76, v47, v47
	v_mul_f32_e32 v42, v32, v82
	v_add_f32_e32 v32, 1.0, v33
	v_add_f32_e32 v33, v34, v58
	v_mul_f32_e32 v33, 0xbfb8aa3b, v33
	v_add_f32_e32 v34, v35, v59
	v_fmac_f32_e32 v76, v60, v60
	v_rcp_f32_e32 v32, v32
	v_exp_f32_e32 v33, v33
	v_mul_f32_e32 v34, 0xbfb8aa3b, v34
	v_fmac_f32_e32 v76, v61, v61
	v_exp_f32_e32 v34, v34
	v_lshlrev_b32_e32 v80, 16, v72
	v_fmac_f32_e32 v76, v62, v62
	v_and_b32_e32 v72, 0xffff0000, v72
	v_and_b32_e32 v74, 0xffff0000, v74
	v_fmac_f32_e32 v76, v63, v63
	v_mul_f32_e32 v40, v54, v80
	v_lshlrev_b32_e32 v81, 16, v73
	v_fmac_f32_e32 v76, v40, v40
	v_mul_f32_e32 v41, v55, v72
	v_mul_f32_e32 v35, v32, v74
	v_add_f32_e32 v32, 1.0, v33
	v_and_b32_e32 v73, 0xffff0000, v73
	v_fmac_f32_e32 v76, v41, v41
	v_mul_f32_e32 v38, v38, v81
	v_rcp_f32_e32 v32, v32
	v_add_f32_e32 v33, 1.0, v34
	v_fmac_f32_e32 v76, v38, v38
	v_mul_f32_e32 v39, v39, v73
	v_rcp_f32_e32 v33, v33
	v_fmac_f32_e32 v76, v39, v39
	v_lshlrev_b32_e32 v83, 16, v75
	v_fmac_f32_e32 v76, v42, v42
	v_and_b32_e32 v75, 0xffff0000, v75
	v_fmac_f32_e32 v76, v35, v35
	v_mul_f32_e32 v43, v32, v83
	v_fmac_f32_e32 v76, v43, v43
	v_mul_f32_e32 v44, v33, v75
	v_fmac_f32_e32 v76, v44, v44
	v_cvt_pk_bf16_f32 v32, v40, v41
	v_cvt_pk_bf16_f32 v33, v38, v39
	v_cvt_pk_bf16_f32 v34, v42, v35
	v_cvt_pk_bf16_f32 v35, v43, v44
	global_store_dwordx4 v[36:37], v[32:35], off offset:256
	s_nop 1
	v_mov_b32_e32 v32, v76
	s_nop 1
	v_permlane16_swap_b32_e32 v76, v32
	v_add_f32_e32 v32, v76, v32
	v_mov_b32_e32 v33, v32
	s_nop 1
	v_permlane32_swap_b32_e32 v32, v33
	s_and_saveexec_b64 s[20:21], s[4:5]
	s_cbranch_execz .LBB0_1163
	v_lshl_add_u64 v[34:35], v[52:53], 2, s[0:1]
	v_add_f32_e32 v32, v32, v33
	global_atomic_add_f32 v[34:35], v32, off
; __device__ __forceinline__ void unpack8(const u32x4 w, float (&f)[8]) { f[0] = bflo(w.x); f[1] = bfhi(w.x); f[2] = bflo(w.y); f[3] = bfhi(w.y); f[4] = bflo(w.z); f[5] = bfhi(w.z); f[6] = bflo(w.w); f[7] = bfhi(w.w); }
; __device__ __forceinline__ u32x4 pack8(const float (&f)[8]) { u32x4 o; o.x = pk2(f[0], f[1]); o.y = pk2(f[2], f[3]); o.z = pk2(f[4], f[5]); o.w = pk2(f[6], f[7]); return o; }
; __device__ __forceinline__ float sigmoidf_(float x) { return __builtin_amdgcn_rcpf(1.0f + __expf(-x)); }
;     __device__ __forceinline__ void operator()(const f32x4 (&acc)[2][2][4][2], const Unit& u, int wr, int wc, int fr, int fq) const {
;     ...
;             for (int m = 0; m < 4; ++m) { const int row = row0 + ai * HALF + m * 16; const size_t off = (size_t)row * DM + col0; float s = 0.f;
; #pragma unroll
;                 for (int bj = 0; bj < 2; ++bj) { float e[8], o[8]; unpack8(*(const u32x4*)(E + off + bj * HALF), e);
; #pragma unroll
;                     for (int n = 0; n < 2; ++n) { const f32x4 v = acc[ai][bj][m][n] + bv[bj][n];
; #pragma unroll
;                         for (int j = 0; j < 4; ++j) { o[4 * n + j] = sigmoidf_(v[j]) * e[4 * n + j]; s += o[4 * n + j] * o[4 * n + j]; } }
;                     *(u32x4*)(C + off + bj * HALF) = pack8(o); }
;                 { auto r16 = __builtin_amdgcn_permlane16_swap(__float_as_uint(s), __float_as_uint(s), false, false); s = __uint_as_float(r16[0]) + __uint_as_float(r16[1]);
;                   auto r32 = __builtin_amdgcn_permlane32_swap(__float_as_uint(s), __float_as_uint(s), false, false); s = __uint_as_float(r32[0]) + __uint_as_float(r32[1]); }
;                 if (fq == 0) atomicAdd(ss + row, s); }
.LBB0_1163:
	s_or_b64 exec, exec, s[20:21]
	v_add_u32_e32 v32, 0xa0, v162
	v_ashrrev_i32_e32 v33, 31, v32
	v_lshlrev_b64 v[34:35], 10, v[32:33]
	v_lshl_add_u64 v[34:35], v[34:35], 0, v[160:161]
	v_lshlrev_b64 v[42:43], 1, v[34:35]
	v_lshl_add_u64 v[38:39], s[8:9], 0, v[42:43]
	v_mov_b32_e32 v34, v228
	v_mov_b32_e32 v35, v229
	v_mov_b32_e32 v36, v230
	v_mov_b32_e32 v37, v231
	s_nop 0
	v_mov_b32_e32 v38, v232
	v_mov_b32_e32 v39, v233
	v_mov_b32_e32 v40, v234
	v_mov_b32_e32 v41, v235
	v_add_f32_e32 v29, v29, v69
	v_add_f32_e32 v28, v28, v68
	v_mul_f32_e32 v29, 0xbfb8aa3b, v29
	v_add_f32_e32 v30, v30, v70
	v_add_f32_e32 v31, v31, v71
	v_add_f32_e32 v24, v24, v64
	v_add_f32_e32 v25, v25, v65
	v_add_f32_e32 v26, v26, v66
	v_mul_f32_e32 v28, 0xbfb8aa3b, v28
	v_exp_f32_e32 v29, v29
	v_add_f32_e32 v27, v27, v67
	v_mul_f32_e32 v30, 0xbfb8aa3b, v30
	v_mul_f32_e32 v31, 0xbfb8aa3b, v31
	v_mul_f32_e32 v24, 0xbfb8aa3b, v24
	v_mul_f32_e32 v25, 0xbfb8aa3b, v25
	v_mul_f32_e32 v26, 0xbfb8aa3b, v26
	v_exp_f32_e32 v28, v28
	v_add_f32_e32 v16, v16, v56
	v_add_f32_e32 v20, v20, v48
	v_mul_f32_e32 v27, 0xbfb8aa3b, v27
	v_exp_f32_e32 v30, v30
	v_exp_f32_e32 v31, v31
	v_exp_f32_e32 v24, v24
	v_exp_f32_e32 v25, v25
	v_exp_f32_e32 v26, v26
	v_mul_f32_e32 v16, 0xbfb8aa3b, v16
	v_mul_f32_e32 v20, 0xbfb8aa3b, v20
	v_exp_f32_e32 v27, v27
	v_exp_f32_e32 v16, v16
	v_add_f32_e32 v21, v21, v49
	v_exp_f32_e32 v44, v20
	v_add_f32_e32 v29, 1.0, v29
	v_mul_f32_e32 v21, 0xbfb8aa3b, v21
	v_add_f32_e32 v28, 1.0, v28
	v_rcp_f32_e32 v29, v29
	v_exp_f32_e32 v45, v21
	v_add_f32_e32 v30, 1.0, v30
	v_add_f32_e32 v31, 1.0, v31
	v_add_f32_e32 v24, 1.0, v24
	v_add_f32_e32 v25, 1.0, v25
	v_add_f32_e32 v26, 1.0, v26
	v_rcp_f32_e32 v28, v28
	v_add_f32_e32 v17, v17, v57
	v_add_f32_e32 v27, 1.0, v27
	v_rcp_f32_e32 v30, v30
	v_rcp_f32_e32 v31, v31
	v_rcp_f32_e32 v24, v24
	v_rcp_f32_e32 v25, v25
	v_rcp_f32_e32 v26, v26
	v_add_f32_e32 v16, 1.0, v16
	v_mul_f32_e32 v17, 0xbfb8aa3b, v17
	v_lshl_add_u64 v[20:21], s[48:49], 0, v[42:43]
	v_add_f32_e32 v42, 1.0, v44
	v_rcp_f32_e32 v27, v27
	v_add_f32_e32 v22, v22, v50
	v_rcp_f32_e32 v16, v16
	v_exp_f32_e32 v17, v17
	v_mul_f32_e32 v22, 0xbfb8aa3b, v22
	v_add_f32_e32 v23, v23, v51
	v_add_f32_e32 v43, 1.0, v45
	v_exp_f32_e32 v22, v22
	v_mul_f32_e32 v23, 0xbfb8aa3b, v23
	v_exp_f32_e32 v23, v23
	v_rcp_f32_e32 v42, v42
	v_rcp_f32_e32 v43, v43
	v_add_f32_e32 v22, 1.0, v22
	v_rcp_f32_e32 v22, v22
	v_add_f32_e32 v23, 1.0, v23
	v_rcp_f32_e32 v23, v23
	v_lshlrev_b32_e32 v44, 16, v34
	v_and_b32_e32 v34, 0xffff0000, v34
	v_mul_f32_e32 v29, v29, v34
	v_lshlrev_b32_e32 v45, 16, v35
	v_and_b32_e32 v35, 0xffff0000, v35
	v_lshlrev_b32_e32 v46, 16, v36
	v_and_b32_e32 v36, 0xffff0000, v36
	v_lshlrev_b32_e32 v47, 16, v37
	v_mul_f32_e32 v28, v28, v44
	v_mul_f32_e32 v44, v29, v29
	v_and_b32_e32 v37, 0xffff0000, v37
	v_lshlrev_b32_e32 v54, 16, v40
	v_mul_f32_e32 v30, v30, v45
	v_mul_f32_e32 v31, v31, v35
	v_mul_f32_e32 v34, v24, v46
	v_mul_f32_e32 v35, v25, v36
	v_mul_f32_e32 v36, v26, v47
	v_cvt_pk_bf16_f32 v26, v34, v35
	v_fmac_f32_e32 v44, v28, v28
	v_mul_f32_e32 v37, v27, v37
	v_cvt_pk_bf16_f32 v24, v28, v29
	v_cvt_pk_bf16_f32 v25, v30, v31
	v_cvt_pk_bf16_f32 v27, v36, v37
	global_store_dwordx4 v[20:21], v[24:27], off
	v_fmac_f32_e32 v44, v30, v30
	v_fmac_f32_e32 v44, v31, v31
	v_mul_f32_e32 v26, v16, v54
	v_add_f32_e32 v16, 1.0, v17
	v_add_f32_e32 v17, v18, v58
	v_mul_f32_e32 v17, 0xbfb8aa3b, v17
	v_add_f32_e32 v18, v19, v59
	v_fmac_f32_e32 v44, v34, v34
	v_rcp_f32_e32 v16, v16
	v_exp_f32_e32 v17, v17
	v_mul_f32_e32 v18, 0xbfb8aa3b, v18
	v_fmac_f32_e32 v44, v35, v35
	v_exp_f32_e32 v18, v18
	v_lshlrev_b32_e32 v52, 16, v38
	v_fmac_f32_e32 v44, v36, v36
	v_and_b32_e32 v38, 0xffff0000, v38
	v_and_b32_e32 v40, 0xffff0000, v40
	v_fmac_f32_e32 v44, v37, v37
	v_mul_f32_e32 v24, v42, v52
	v_lshlrev_b32_e32 v53, 16, v39
	v_fmac_f32_e32 v44, v24, v24
	v_mul_f32_e32 v25, v43, v38
	v_mul_f32_e32 v19, v16, v40
	v_add_f32_e32 v16, 1.0, v17
	v_and_b32_e32 v39, 0xffff0000, v39
	v_fmac_f32_e32 v44, v25, v25
	v_mul_f32_e32 v22, v22, v53
	v_rcp_f32_e32 v16, v16
	v_add_f32_e32 v17, 1.0, v18
	v_fmac_f32_e32 v44, v22, v22
	v_mul_f32_e32 v23, v23, v39
	v_rcp_f32_e32 v17, v17
	v_fmac_f32_e32 v44, v23, v23
	v_lshlrev_b32_e32 v55, 16, v41
	v_fmac_f32_e32 v44, v26, v26
	v_and_b32_e32 v41, 0xffff0000, v41
	v_fmac_f32_e32 v44, v19, v19
	v_mul_f32_e32 v27, v16, v55
	v_fmac_f32_e32 v44, v27, v27
	v_mul_f32_e32 v28, v17, v41
	v_fmac_f32_e32 v44, v28, v28
	v_cvt_pk_bf16_f32 v16, v24, v25
	v_cvt_pk_bf16_f32 v17, v22, v23
	v_cvt_pk_bf16_f32 v18, v26, v19
	v_cvt_pk_bf16_f32 v19, v27, v28
	global_store_dwordx4 v[20:21], v[16:19], off offset:256
	s_nop 1
	v_mov_b32_e32 v16, v44
	s_nop 1
	v_permlane16_swap_b32_e32 v44, v16
	v_add_f32_e32 v16, v44, v16
	v_mov_b32_e32 v17, v16
	s_nop 1
	v_permlane32_swap_b32_e32 v16, v17
	s_and_saveexec_b64 s[20:21], s[4:5]
	s_cbranch_execz .LBB0_1165
	v_lshl_add_u64 v[18:19], v[32:33], 2, s[0:1]
	v_add_f32_e32 v16, v16, v17
	global_atomic_add_f32 v[18:19], v16, off
; __device__ __forceinline__ void unpack8(const u32x4 w, float (&f)[8]) { f[0] = bflo(w.x); f[1] = bfhi(w.x); f[2] = bflo(w.y); f[3] = bfhi(w.y); f[4] = bflo(w.z); f[5] = bfhi(w.z); f[6] = bflo(w.w); f[7] = bfhi(w.w); }
; __device__ __forceinline__ u32x4 pack8(const float (&f)[8]) { u32x4 o; o.x = pk2(f[0], f[1]); o.y = pk2(f[2], f[3]); o.z = pk2(f[4], f[5]); o.w = pk2(f[6], f[7]); return o; }
; __device__ __forceinline__ float sigmoidf_(float x) { return __builtin_amdgcn_rcpf(1.0f + __expf(-x)); }
;     __device__ __forceinline__ void operator()(const f32x4 (&acc)[2][2][4][2], const Unit& u, int wr, int wc, int fr, int fq) const {
;     ...
;             for (int m = 0; m < 4; ++m) { const int row = row0 + ai * HALF + m * 16; const size_t off = (size_t)row * DM + col0; float s = 0.f;
; #pragma unroll
;                 for (int bj = 0; bj < 2; ++bj) { float e[8], o[8]; unpack8(*(const u32x4*)(E + off + bj * HALF), e);
; #pragma unroll
;                     for (int n = 0; n < 2; ++n) { const f32x4 v = acc[ai][bj][m][n] + bv[bj][n];
; #pragma unroll
;                         for (int j = 0; j < 4; ++j) { o[4 * n + j] = sigmoidf_(v[j]) * e[4 * n + j]; s += o[4 * n + j] * o[4 * n + j]; } }
;                     *(u32x4*)(C + off + bj * HALF) = pack8(o); }
;                 { auto r16 = __builtin_amdgcn_permlane16_swap(__float_as_uint(s), __float_as_uint(s), false, false); s = __uint_as_float(r16[0]) + __uint_as_float(r16[1]);
;                   auto r32 = __builtin_amdgcn_permlane32_swap(__float_as_uint(s), __float_as_uint(s), false, false); s = __uint_as_float(r32[0]) + __uint_as_float(r32[1]); }
;                 if (fq == 0) atomicAdd(ss + row, s); }
.LBB0_1165:
	s_or_b64 exec, exec, s[20:21]
	v_add_u32_e32 v16, 0xb0, v162
	v_ashrrev_i32_e32 v17, 31, v16
	v_lshlrev_b64 v[18:19], 10, v[16:17]
	v_lshl_add_u64 v[18:19], v[18:19], 0, v[160:161]
	v_lshlrev_b64 v[26:27], 1, v[18:19]
	v_lshl_add_u64 v[22:23], s[8:9], 0, v[26:27]
	v_mov_b32_e32 v18, v236
	v_mov_b32_e32 v19, v237
	v_mov_b32_e32 v20, v238
	v_mov_b32_e32 v21, v239
	s_nop 0
	v_mov_b32_e32 v22, v240
	v_mov_b32_e32 v23, v241
	v_mov_b32_e32 v24, v242
	v_mov_b32_e32 v25, v243
	v_add_f32_e32 v13, v13, v69
	v_add_f32_e32 v12, v12, v68
	v_mul_f32_e32 v13, 0xbfb8aa3b, v13
	v_add_f32_e32 v14, v14, v70
	v_add_f32_e32 v15, v15, v71
	v_add_f32_e32 v8, v8, v64
	v_add_f32_e32 v9, v9, v65
	v_add_f32_e32 v10, v10, v66
	v_mul_f32_e32 v12, 0xbfb8aa3b, v12
	v_exp_f32_e32 v13, v13
	v_add_f32_e32 v11, v11, v67
	v_mul_f32_e32 v14, 0xbfb8aa3b, v14
	v_mul_f32_e32 v15, 0xbfb8aa3b, v15
	v_mul_f32_e32 v8, 0xbfb8aa3b, v8
	v_mul_f32_e32 v9, 0xbfb8aa3b, v9
	v_mul_f32_e32 v10, 0xbfb8aa3b, v10
	v_exp_f32_e32 v12, v12
	v_add_f32_e32 v0, v0, v56
	v_add_f32_e32 v4, v4, v48
	v_mul_f32_e32 v11, 0xbfb8aa3b, v11
	v_exp_f32_e32 v14, v14
	v_exp_f32_e32 v15, v15
	v_exp_f32_e32 v8, v8
	v_exp_f32_e32 v9, v9
	v_exp_f32_e32 v10, v10
	v_mul_f32_e32 v0, 0xbfb8aa3b, v0
	v_mul_f32_e32 v4, 0xbfb8aa3b, v4
	v_exp_f32_e32 v11, v11
	v_exp_f32_e32 v0, v0
	v_add_f32_e32 v5, v5, v49
	v_exp_f32_e32 v28, v4
	v_add_f32_e32 v13, 1.0, v13
	v_mul_f32_e32 v5, 0xbfb8aa3b, v5
	v_add_f32_e32 v12, 1.0, v12
	v_rcp_f32_e32 v13, v13
	v_exp_f32_e32 v29, v5
	v_add_f32_e32 v14, 1.0, v14
	v_add_f32_e32 v15, 1.0, v15
	v_add_f32_e32 v8, 1.0, v8
	v_add_f32_e32 v9, 1.0, v9
	v_add_f32_e32 v10, 1.0, v10
	v_rcp_f32_e32 v12, v12
	v_add_f32_e32 v1, v1, v57
	v_add_f32_e32 v11, 1.0, v11
	v_rcp_f32_e32 v14, v14
	v_rcp_f32_e32 v15, v15
	v_rcp_f32_e32 v8, v8
	v_rcp_f32_e32 v9, v9
	v_rcp_f32_e32 v10, v10
	v_add_f32_e32 v0, 1.0, v0
	v_mul_f32_e32 v1, 0xbfb8aa3b, v1
	v_lshl_add_u64 v[4:5], s[48:49], 0, v[26:27]
	v_add_f32_e32 v26, 1.0, v28
	v_rcp_f32_e32 v11, v11
	v_add_f32_e32 v6, v6, v50
	v_rcp_f32_e32 v0, v0
	v_exp_f32_e32 v1, v1
	v_mul_f32_e32 v6, 0xbfb8aa3b, v6
	v_add_f32_e32 v7, v7, v51
	v_add_f32_e32 v27, 1.0, v29
	v_exp_f32_e32 v6, v6
	v_mul_f32_e32 v7, 0xbfb8aa3b, v7
	v_exp_f32_e32 v7, v7
	v_rcp_f32_e32 v26, v26
	v_rcp_f32_e32 v27, v27
	v_add_f32_e32 v6, 1.0, v6
	v_rcp_f32_e32 v6, v6
	v_add_f32_e32 v7, 1.0, v7
	v_rcp_f32_e32 v7, v7
	v_lshlrev_b32_e32 v28, 16, v18
	v_and_b32_e32 v18, 0xffff0000, v18
	v_mul_f32_e32 v13, v13, v18
	v_lshlrev_b32_e32 v29, 16, v19
	v_and_b32_e32 v19, 0xffff0000, v19
	v_lshlrev_b32_e32 v30, 16, v20
	v_and_b32_e32 v20, 0xffff0000, v20
	v_lshlrev_b32_e32 v31, 16, v21
	v_mul_f32_e32 v12, v12, v28
	v_mul_f32_e32 v28, v13, v13
	v_and_b32_e32 v21, 0xffff0000, v21
	v_lshlrev_b32_e32 v34, 16, v24
	v_mul_f32_e32 v14, v14, v29
	v_mul_f32_e32 v15, v15, v19
	v_mul_f32_e32 v18, v8, v30
	v_mul_f32_e32 v19, v9, v20
	v_mul_f32_e32 v20, v10, v31
	v_cvt_pk_bf16_f32 v10, v18, v19
	v_fmac_f32_e32 v28, v12, v12
	v_mul_f32_e32 v21, v11, v21
	v_cvt_pk_bf16_f32 v8, v12, v13
	v_cvt_pk_bf16_f32 v9, v14, v15
	v_cvt_pk_bf16_f32 v11, v20, v21
	global_store_dwordx4 v[4:5], v[8:11], off
	v_fmac_f32_e32 v28, v14, v14
	v_fmac_f32_e32 v28, v15, v15
	v_mul_f32_e32 v10, v0, v34
	v_add_f32_e32 v0, 1.0, v1
	v_add_f32_e32 v1, v2, v58
	v_mul_f32_e32 v1, 0xbfb8aa3b, v1
	v_add_f32_e32 v2, v3, v59
	v_fmac_f32_e32 v28, v18, v18
	v_rcp_f32_e32 v0, v0
	v_exp_f32_e32 v1, v1
	v_mul_f32_e32 v2, 0xbfb8aa3b, v2
	v_fmac_f32_e32 v28, v19, v19
	v_exp_f32_e32 v2, v2
	v_lshlrev_b32_e32 v32, 16, v22
	v_fmac_f32_e32 v28, v20, v20
	v_and_b32_e32 v22, 0xffff0000, v22
	v_and_b32_e32 v24, 0xffff0000, v24
	v_fmac_f32_e32 v28, v21, v21
	v_mul_f32_e32 v8, v26, v32
	v_lshlrev_b32_e32 v33, 16, v23
	v_fmac_f32_e32 v28, v8, v8
	v_mul_f32_e32 v9, v27, v22
	v_mul_f32_e32 v3, v0, v24
	v_add_f32_e32 v0, 1.0, v1
	v_and_b32_e32 v23, 0xffff0000, v23
	v_fmac_f32_e32 v28, v9, v9
	v_mul_f32_e32 v6, v6, v33
	v_rcp_f32_e32 v0, v0
	v_add_f32_e32 v1, 1.0, v2
	v_fmac_f32_e32 v28, v6, v6
	v_mul_f32_e32 v7, v7, v23
	v_rcp_f32_e32 v1, v1
	v_fmac_f32_e32 v28, v7, v7
	v_lshlrev_b32_e32 v35, 16, v25
	v_fmac_f32_e32 v28, v10, v10
	v_and_b32_e32 v25, 0xffff0000, v25
	v_fmac_f32_e32 v28, v3, v3
	v_mul_f32_e32 v11, v0, v35
	v_fmac_f32_e32 v28, v11, v11
	v_mul_f32_e32 v12, v1, v25
	v_fmac_f32_e32 v28, v12, v12
	v_cvt_pk_bf16_f32 v0, v8, v9
	v_cvt_pk_bf16_f32 v1, v6, v7
	v_cvt_pk_bf16_f32 v2, v10, v3
	v_cvt_pk_bf16_f32 v3, v11, v12
	global_store_dwordx4 v[4:5], v[0:3], off offset:256
	s_nop 1
	v_mov_b32_e32 v0, v28
	s_nop 1
	v_permlane16_swap_b32_e32 v28, v0
	v_add_f32_e32 v0, v28, v0
	v_mov_b32_e32 v1, v0
	s_nop 1
	v_permlane32_swap_b32_e32 v0, v1
	s_and_saveexec_b64 s[20:21], s[4:5]
	s_cbranch_execz .LBB0_1142
	v_lshl_add_u64 v[2:3], v[16:17], 2, s[0:1]
	v_add_f32_e32 v0, v0, v1
	global_atomic_add_f32 v[2:3], v0, off
	s_branch .LBB0_1142
